# rwkv_fin second-half items: S_mid.z loop unrolled, the 16 S_mid slices fetched up front before the barrier and consumed with counted waits
# speedup vs baseline: 1.0019x; 1.0019x over previous
; __device__ __forceinline__ float bf2f(unsigned short b) { return __uint_as_float(((unsigned)b) << 16); }
; __device__ __forceinline__ float sigmoidf_(float x) { return __builtin_amdgcn_rcpf(1.0f + __expf(-x)); }
; __device__ __forceinline__ void rwkv_fin_item(const Params& p, int l, int item, char* ldsraw) {
;     ...
;   for (int i = 0; i < 4; i++) {
;     int idx = tid + 256 * i; int t = idx >> 6, c = idx & 63;
;     int col = C_RW + 832 + c; int tok = tok0 + t;
;     float cur = bf2f(P[(size_t)tok * PIN + col]);
;     float prv = (s0 + t > 0) ? bf2f(P[(size_t)(tok - 1) * PIN + col]) : 0.f;
;     float v = cur + (prv - cur) * mu[832 + c];
;     lds[t * 64 + c] = sigmoidf_(v);
;   }
;   __syncthreads();
;   {
;     float gacc[16];
; #pragma unroll
;     for (int t = 0; t < 16; t++) gacc[t] = 0.f;
;     const float* g2 = p.g2 + (size_t)l * 64 * 256 + tid;
;     float g2c[64];
; #pragma unroll
;     for (int i = 0; i < 64; i++) g2c[i] = g2[i * 256];
; #pragma unroll
;     for (int i4 = 0; i4 < 16; i4++) {
; #pragma unroll
;       for (int t = 0; t < 16; t++) {
;         const f32x4 x = *(const f32x4*)(lds + t * 64 + i4 * 4);
;         gacc[t] += x[0] * g2c[i4 * 4] + x[1] * g2c[i4 * 4 + 1] + x[2] * g2c[i4 * 4 + 2] + x[3] * g2c[i4 * 4 + 3];
;       }
;     }
.LBB0_148:
	s_or_b64 exec, exec, s[28:29]
	s_waitcnt vmcnt(0)
	v_lshlrev_b32_e32 v4, 16, v7
	v_sub_f32_e32 v5, v6, v4
	v_fmac_f32_e32 v4, v1, v5
	v_mul_f32_e32 v1, 0xbfb8aa3b, v4
	v_exp_f32_e32 v1, v1
	s_add_u32 s27, s46, s27
	s_addc_u32 s38, s47, 0
	s_add_u32 s28, s46, s3
	v_add_f32_e32 v1, 1.0, v1
	v_rcp_f32_e32 v1, v1
	s_addc_u32 s29, s47, 0
	s_add_u32 s37, s27, 0xc0a8000
	s_addc_u32 s38, s38, 0
	ds_write_b32 v56, v1 offset:3072
	v_ashrrev_i32_e32 v1, 31, v0
	v_lshl_add_u64 v[4:5], v[0:1], 2, s[34:35]
	s_waitcnt lgkmcnt(0)
	s_barrier
	global_load_dword v79, v[4:5], off
	global_load_dword v95, v[4:5], off offset:1024
	global_load_dword v93, v[4:5], off offset:2048
	global_load_dword v94, v[4:5], off offset:3072
	s_add_u32 s27, s46, s2
	s_movk_i32 s2, 0x1000
	v_add_co_u32_e32 v6, vcc, s2, v4
	s_movk_i32 s2, 0x2000
	s_nop 0
	v_addc_co_u32_e32 v7, vcc, 0, v5, vcc
	v_add_co_u32_e32 v8, vcc, s2, v4
	s_movk_i32 s2, 0x3000
	s_nop 0
	v_addc_co_u32_e32 v9, vcc, 0, v5, vcc
	global_load_dword v76, v[8:9], off offset:-4096
	global_load_dword v78, v[6:7], off offset:1024
	global_load_dword v77, v[6:7], off offset:2048
	global_load_dword v75, v[6:7], off offset:3072
	global_load_dword v71, v[8:9], off
	global_load_dword v74, v[8:9], off offset:1024
	global_load_dword v72, v[8:9], off offset:2048
	global_load_dword v73, v[8:9], off offset:3072
	v_add_co_u32_e32 v6, vcc, s2, v4
	s_movk_i32 s2, 0x5000
	s_nop 0
	v_addc_co_u32_e32 v7, vcc, 0, v5, vcc
	v_add_co_u32_e32 v8, vcc, s22, v4
	v_readlane_b32 s4, v252, 19
	s_nop 0
	v_addc_co_u32_e32 v9, vcc, 0, v5, vcc
	global_load_dword v67, v[8:9], off offset:-4096
	global_load_dword v70, v[6:7], off offset:1024
	global_load_dword v68, v[6:7], off offset:2048
	global_load_dword v69, v[6:7], off offset:3072
	global_load_dword v63, v[8:9], off
	global_load_dword v66, v[8:9], off offset:1024
	global_load_dword v64, v[8:9], off offset:2048
	global_load_dword v65, v[8:9], off offset:3072
	v_add_co_u32_e32 v6, vcc, s2, v4
	s_movk_i32 s2, 0x6000
	s_nop 0
	v_addc_co_u32_e32 v7, vcc, 0, v5, vcc
	v_add_co_u32_e32 v8, vcc, s2, v4
	s_movk_i32 s2, 0x7000
	s_nop 0
	v_addc_co_u32_e32 v9, vcc, 0, v5, vcc
	global_load_dword v59, v[8:9], off offset:-4096
	global_load_dword v62, v[6:7], off offset:1024
	global_load_dword v60, v[6:7], off offset:2048
	global_load_dword v61, v[6:7], off offset:3072
	global_load_dword v53, v[8:9], off
	global_load_dword v58, v[8:9], off offset:1024
	global_load_dword v54, v[8:9], off offset:2048
	global_load_dword v55, v[8:9], off offset:3072
	v_add_co_u32_e32 v6, vcc, s2, v4
	s_mov_b32 s2, 0x8000
	s_nop 0
	v_addc_co_u32_e32 v7, vcc, 0, v5, vcc
	v_add_co_u32_e32 v8, vcc, s2, v4
	s_mov_b32 s2, 0x9000
	s_nop 0
	v_addc_co_u32_e32 v9, vcc, 0, v5, vcc
	global_load_dword v49, v[8:9], off offset:-4096
	global_load_dword v52, v[6:7], off offset:1024
	global_load_dword v50, v[6:7], off offset:2048
	global_load_dword v51, v[6:7], off offset:3072
	global_load_dword v41, v[8:9], off
	global_load_dword v48, v[8:9], off offset:1024
	global_load_dword v42, v[8:9], off offset:2048
	global_load_dword v43, v[8:9], off offset:3072
	v_add_co_u32_e32 v6, vcc, s2, v4
	s_mov_b32 s2, 0xa000
	s_nop 0
	v_addc_co_u32_e32 v7, vcc, 0, v5, vcc
	v_add_co_u32_e32 v8, vcc, s2, v4
	s_mov_b32 s2, 0xb000
	s_nop 0
	v_addc_co_u32_e32 v9, vcc, 0, v5, vcc
	global_load_dword v37, v[8:9], off offset:-4096
	global_load_dword v40, v[6:7], off offset:1024
	global_load_dword v38, v[6:7], off offset:2048
	global_load_dword v39, v[6:7], off offset:3072
	global_load_dword v33, v[8:9], off
	global_load_dword v36, v[8:9], off offset:1024
	global_load_dword v34, v[8:9], off offset:2048
	global_load_dword v35, v[8:9], off offset:3072
	v_add_co_u32_e32 v6, vcc, s2, v4
	s_mov_b32 s2, 0xc000
	s_nop 0
	v_addc_co_u32_e32 v7, vcc, 0, v5, vcc
	v_add_co_u32_e32 v8, vcc, s2, v4
	s_mov_b32 s2, 0xd000
	s_nop 0
	v_addc_co_u32_e32 v9, vcc, 0, v5, vcc
	global_load_dword v29, v[8:9], off offset:-4096
	global_load_dword v32, v[6:7], off offset:1024
	global_load_dword v30, v[6:7], off offset:2048
	global_load_dword v31, v[6:7], off offset:3072
	global_load_dword v25, v[8:9], off
	global_load_dword v28, v[8:9], off offset:1024
	global_load_dword v26, v[8:9], off offset:2048
	global_load_dword v27, v[8:9], off offset:3072
	v_add_co_u32_e32 v6, vcc, s2, v4
	s_mov_b32 s2, 0xe000
	s_nop 0
	v_addc_co_u32_e32 v7, vcc, 0, v5, vcc
	v_add_co_u32_e32 v8, vcc, s2, v4
	s_mov_b32 s2, 0xf000
	s_nop 0
	v_addc_co_u32_e32 v9, vcc, 0, v5, vcc
	v_add_co_u32_e32 v4, vcc, s2, v4
	global_load_dword v21, v[8:9], off offset:-4096
	global_load_dword v24, v[6:7], off offset:1024
	global_load_dword v22, v[6:7], off offset:2048
	global_load_dword v23, v[6:7], off offset:3072
	global_load_dword v17, v[8:9], off
	global_load_dword v20, v[8:9], off offset:1024
	global_load_dword v18, v[8:9], off offset:2048
	global_load_dword v19, v[8:9], off offset:3072
	v_addc_co_u32_e32 v5, vcc, 0, v5, vcc
	global_load_dword v44, v[4:5], off
	global_load_dword v46, v[4:5], off offset:1024
	global_load_dword v45, v[4:5], off offset:2048
	ds_read_b128 v[80:83], v3
	global_load_dword v47, v[4:5], off offset:3072
	ds_read_b128 v[12:15], v3 offset:16
	ds_read_b128 v[8:11], v3 offset:32
	ds_read_b128 v[4:7], v3 offset:48
	ds_read_b128 v[84:87], v3 offset:256
	ds_read_b128 v[98:101], v3 offset:2304
	s_waitcnt vmcnt(62) lgkmcnt(5)
	v_mul_f32_e32 v81, v95, v81
	v_fmac_f32_e32 v81, v79, v80
	s_waitcnt vmcnt(61)
	v_fmac_f32_e32 v81, v93, v82
	s_waitcnt vmcnt(60)
	v_fmac_f32_e32 v81, v94, v83
	v_add_f32_e32 v97, 0, v81
	ds_read_b128 v[80:83], v3 offset:512
	s_waitcnt lgkmcnt(2)
; __device__ __forceinline__ void rwkv_fin_item(const Params& p, int l, int item, char* ldsraw) {
;     ...
; #pragma unroll
;     for (int i4 = 0; i4 < 16; i4++) {
; #pragma unroll
;       for (int t = 0; t < 16; t++) {
;         const f32x4 x = *(const f32x4*)(lds + t * 64 + i4 * 4);
;         gacc[t] += x[0] * g2c[i4 * 4] + x[1] * g2c[i4 * 4 + 1] + x[2] * g2c[i4 * 4 + 2] + x[3] * g2c[i4 * 4 + 3];
;       }
;     }
	v_mul_f32_e32 v85, v95, v85
	v_fmac_f32_e32 v85, v79, v84
	v_fmac_f32_e32 v85, v93, v86
	v_fmac_f32_e32 v85, v94, v87
	s_waitcnt lgkmcnt(0)
	v_mul_f32_e32 v81, v95, v81
	v_fmac_f32_e32 v81, v79, v80
	v_fmac_f32_e32 v81, v93, v82
	v_fmac_f32_e32 v81, v94, v83
	v_add_f32_e32 v96, 0, v85
	ds_read_b128 v[84:87], v3 offset:768
	v_add_f32_e32 v92, 0, v81
	ds_read_b128 v[80:83], v3 offset:1024
	s_waitcnt vmcnt(58)
	v_mul_f32_e32 v13, v78, v13
	v_fmac_f32_e32 v13, v76, v12
	s_waitcnt lgkmcnt(1)
	v_mul_f32_e32 v85, v95, v85
	v_fmac_f32_e32 v85, v79, v84
	s_waitcnt lgkmcnt(0)
	v_mul_f32_e32 v81, v95, v81
	v_fmac_f32_e32 v81, v79, v80
	v_fmac_f32_e32 v85, v93, v86
	v_fmac_f32_e32 v81, v93, v82
	v_fmac_f32_e32 v85, v94, v87
	v_fmac_f32_e32 v81, v94, v83
	v_add_f32_e32 v91, 0, v85
	ds_read_b128 v[84:87], v3 offset:1280
	v_add_f32_e32 v88, 0, v81
	ds_read_b128 v[80:83], v3 offset:1536
	ds_read_b128 v[102:105], v3 offset:3072
	s_waitcnt vmcnt(57)
	v_fmac_f32_e32 v13, v77, v14
	s_waitcnt lgkmcnt(2)
	v_mul_f32_e32 v85, v95, v85
	v_fmac_f32_e32 v85, v79, v84
	s_waitcnt lgkmcnt(1)
	v_mul_f32_e32 v81, v95, v81
	v_fmac_f32_e32 v81, v79, v80
	v_fmac_f32_e32 v85, v93, v86
	v_fmac_f32_e32 v81, v93, v82
	v_fmac_f32_e32 v85, v94, v87
	v_fmac_f32_e32 v81, v94, v83
	v_add_f32_e32 v90, 0, v85
	ds_read_b128 v[84:87], v3 offset:1792
	v_add_f32_e32 v89, 0, v81
	ds_read_b128 v[80:83], v3 offset:2048
	s_waitcnt vmcnt(56)
	v_fmac_f32_e32 v13, v75, v15
	v_add_f32_e32 v12, v97, v13
	s_waitcnt lgkmcnt(1)
	v_mul_f32_e32 v85, v95, v85
	v_fmac_f32_e32 v85, v79, v84
	s_waitcnt lgkmcnt(0)
	v_mul_f32_e32 v81, v95, v81
	v_fmac_f32_e32 v81, v79, v80
	v_fmac_f32_e32 v81, v93, v82
	v_fmac_f32_e32 v81, v94, v83
	v_fmac_f32_e32 v85, v93, v86
	v_add_f32_e32 v86, 0, v81
	ds_read_b128 v[80:83], v3 offset:2560
	v_mul_f32_e32 v84, v95, v99
	v_fmac_f32_e32 v84, v79, v98
	v_fmac_f32_e32 v84, v93, v100
	v_fmac_f32_e32 v84, v94, v101
	ds_read_b128 v[98:101], v3 offset:2816
	s_waitcnt lgkmcnt(1)
	v_mul_f32_e32 v81, v95, v81
	v_fmac_f32_e32 v81, v79, v80
	v_fmac_f32_e32 v81, v93, v82
	v_fmac_f32_e32 v81, v94, v83
	s_waitcnt lgkmcnt(0)
	v_mul_f32_e32 v80, v95, v99
	v_fmac_f32_e32 v80, v79, v98
	v_fmac_f32_e32 v80, v93, v100
	v_fmac_f32_e32 v80, v94, v101
	ds_read_b128 v[98:101], v3 offset:3328
	v_add_f32_e32 v83, 0, v80
	v_mul_f32_e32 v80, v95, v103
	v_fmac_f32_e32 v80, v79, v102
	v_fmac_f32_e32 v80, v93, v104
	v_fmac_f32_e32 v80, v94, v105
	v_add_f32_e32 v82, 0, v80
	ds_read_b128 v[102:105], v3 offset:3584
	s_waitcnt lgkmcnt(1)
	v_mul_f32_e32 v80, v95, v99
	v_fmac_f32_e32 v80, v79, v98
	v_fmac_f32_e32 v80, v93, v100
	v_fmac_f32_e32 v80, v94, v101
	ds_read_b128 v[98:101], v3 offset:3840
	v_fmac_f32_e32 v85, v94, v87
	v_add_f32_e32 v87, 0, v85
	v_add_f32_e32 v85, 0, v84
	v_add_f32_e32 v84, 0, v81
	v_add_f32_e32 v81, 0, v80
	s_waitcnt lgkmcnt(1)
	v_mul_f32_e32 v80, v95, v103
	s_waitcnt lgkmcnt(0)
	v_mul_f32_e32 v95, v95, v99
	v_fmac_f32_e32 v95, v79, v98
	v_fmac_f32_e32 v95, v93, v100
	v_fmac_f32_e32 v95, v94, v101
	ds_read_b128 v[98:101], v3 offset:272
	v_fmac_f32_e32 v80, v79, v102
	v_fmac_f32_e32 v80, v93, v104
	v_fmac_f32_e32 v80, v94, v105
	ds_read_b128 v[102:105], v3 offset:528
	s_waitcnt lgkmcnt(1)
	v_mul_f32_e32 v13, v78, v99
	v_fmac_f32_e32 v13, v76, v98
	v_fmac_f32_e32 v13, v77, v100
	v_fmac_f32_e32 v13, v75, v101
	v_add_f32_e32 v79, 0, v95
	v_add_f32_e32 v13, v96, v13
	ds_read_b128 v[94:97], v3 offset:784
	ds_read_b128 v[98:101], v3 offset:1040
	s_waitcnt lgkmcnt(2)
	v_mul_f32_e32 v14, v78, v103
	v_fmac_f32_e32 v14, v76, v102
	v_fmac_f32_e32 v14, v77, v104
	s_waitcnt lgkmcnt(1)
	v_mul_f32_e32 v15, v78, v95
	v_fmac_f32_e32 v15, v76, v94
	v_fmac_f32_e32 v14, v75, v105
	v_fmac_f32_e32 v15, v77, v96
	v_add_f32_e32 v14, v92, v14
	v_fmac_f32_e32 v15, v75, v97
	ds_read_b128 v[92:95], v3 offset:1296
	v_add_f32_e32 v15, v91, v15
	s_waitcnt lgkmcnt(1)
	v_mul_f32_e32 v91, v78, v99
	v_fmac_f32_e32 v91, v76, v98
	v_fmac_f32_e32 v91, v77, v100
	v_fmac_f32_e32 v91, v75, v101
	ds_read_b128 v[96:99], v3 offset:1552
	v_add_f32_e32 v88, v88, v91
	s_waitcnt lgkmcnt(1)
	v_mul_f32_e32 v91, v78, v93
	v_fmac_f32_e32 v91, v76, v92
	v_fmac_f32_e32 v91, v77, v94
	v_fmac_f32_e32 v91, v75, v95
	ds_read_b128 v[92:95], v3 offset:1808
	v_add_f32_e32 v90, v90, v91
	s_waitcnt lgkmcnt(1)
	v_mul_f32_e32 v91, v78, v97
	v_fmac_f32_e32 v91, v76, v96
	v_fmac_f32_e32 v91, v77, v98
	v_fmac_f32_e32 v91, v75, v99
	ds_read_b128 v[96:99], v3 offset:2064
	v_add_f32_e32 v89, v89, v91
	s_waitcnt lgkmcnt(1)
	v_mul_f32_e32 v91, v78, v93
	v_fmac_f32_e32 v91, v76, v92
	v_fmac_f32_e32 v91, v77, v94
	v_fmac_f32_e32 v91, v75, v95
	ds_read_b128 v[92:95], v3 offset:2320
	v_add_f32_e32 v87, v87, v91
	s_waitcnt lgkmcnt(1)
	v_mul_f32_e32 v91, v78, v97
	v_fmac_f32_e32 v91, v76, v96
	v_fmac_f32_e32 v91, v77, v98
	v_fmac_f32_e32 v91, v75, v99
	ds_read_b128 v[96:99], v3 offset:2576
	v_add_f32_e32 v86, v86, v91
	s_waitcnt lgkmcnt(1)
	v_mul_f32_e32 v91, v78, v93
	v_fmac_f32_e32 v91, v76, v92
	v_fmac_f32_e32 v91, v77, v94
	v_fmac_f32_e32 v91, v75, v95
	ds_read_b128 v[92:95], v3 offset:2832
	v_add_f32_e32 v85, v85, v91
	s_waitcnt lgkmcnt(1)
	v_mul_f32_e32 v91, v78, v97
	v_fmac_f32_e32 v91, v76, v96
	v_fmac_f32_e32 v91, v77, v98
	v_fmac_f32_e32 v91, v75, v99
	ds_read_b128 v[96:99], v3 offset:3088
	v_add_f32_e32 v91, v84, v91
	s_waitcnt lgkmcnt(1)
	v_mul_f32_e32 v84, v78, v93
	v_fmac_f32_e32 v84, v76, v92
	v_fmac_f32_e32 v84, v77, v94
	v_fmac_f32_e32 v84, v75, v95
	ds_read_b128 v[92:95], v3 offset:3344
	v_add_f32_e32 v100, v83, v84
	s_waitcnt lgkmcnt(1)
; __device__ __forceinline__ void rwkv_fin_item(const Params& p, int l, int item, char* ldsraw) {
;     ...
; #pragma unroll
;     for (int i4 = 0; i4 < 16; i4++) {
; #pragma unroll
;       for (int t = 0; t < 16; t++) {
;         const f32x4 x = *(const f32x4*)(lds + t * 64 + i4 * 4);
;         gacc[t] += x[0] * g2c[i4 * 4] + x[1] * g2c[i4 * 4 + 1] + x[2] * g2c[i4 * 4 + 2] + x[3] * g2c[i4 * 4 + 3];
;       }
;     }
	v_mul_f32_e32 v83, v78, v97
	v_fmac_f32_e32 v83, v76, v96
	v_fmac_f32_e32 v83, v77, v98
	v_fmac_f32_e32 v83, v75, v99
	v_add_f32_e32 v101, v82, v83
	ds_read_b128 v[96:99], v3 offset:3600
	s_waitcnt lgkmcnt(1)
	v_mul_f32_e32 v82, v78, v93
	v_fmac_f32_e32 v82, v76, v92
	v_fmac_f32_e32 v82, v77, v94
	v_fmac_f32_e32 v82, v75, v95
	ds_read_b128 v[92:95], v3 offset:3856
	v_add_f32_e32 v102, v81, v82
	s_waitcnt lgkmcnt(1)
	v_mul_f32_e32 v81, v78, v97
	v_fmac_f32_e32 v81, v76, v96
	v_fmac_f32_e32 v81, v77, v98
	s_waitcnt lgkmcnt(0)
	v_mul_f32_e32 v78, v78, v93
	v_fmac_f32_e32 v78, v76, v92
	v_fmac_f32_e32 v78, v77, v94
	v_fmac_f32_e32 v78, v75, v95
	v_add_f32_e32 v92, v79, v78
	s_waitcnt vmcnt(54)
	v_mul_f32_e32 v9, v74, v9
	ds_read_b128 v[76:79], v3 offset:288
	v_fmac_f32_e32 v9, v71, v8
	s_waitcnt vmcnt(53)
	v_fmac_f32_e32 v9, v72, v10
	s_waitcnt vmcnt(52)
	v_fmac_f32_e32 v9, v73, v11
	v_add_f32_e32 v93, v12, v9
	ds_read_b128 v[8:11], v3 offset:544
	s_waitcnt lgkmcnt(1)
	v_mul_f32_e32 v12, v74, v77
	v_fmac_f32_e32 v12, v71, v76
	v_fmac_f32_e32 v12, v72, v78
	v_fmac_f32_e32 v12, v73, v79
	ds_read_b128 v[76:79], v3 offset:800
	s_waitcnt lgkmcnt(1)
	v_mul_f32_e32 v9, v74, v9
	v_fmac_f32_e32 v9, v71, v8
	v_fmac_f32_e32 v9, v72, v10
	v_fmac_f32_e32 v9, v73, v11
	v_add_f32_e32 v83, v13, v12
	v_add_f32_e32 v82, v14, v9
	ds_read_b128 v[8:11], v3 offset:1056
	s_waitcnt lgkmcnt(1)
	v_mul_f32_e32 v12, v74, v77
	v_fmac_f32_e32 v12, v71, v76
	v_fmac_f32_e32 v12, v72, v78
	v_add_f32_e32 v80, 0, v80
	v_fmac_f32_e32 v81, v75, v99
	v_fmac_f32_e32 v12, v73, v79
	v_add_f32_e32 v96, v80, v81
	v_add_f32_e32 v81, v15, v12
	ds_read_b128 v[12:15], v3 offset:1312
	s_waitcnt lgkmcnt(1)
	v_mul_f32_e32 v9, v74, v9
	v_fmac_f32_e32 v9, v71, v8
	v_fmac_f32_e32 v9, v72, v10
	v_fmac_f32_e32 v9, v73, v11
	v_add_f32_e32 v80, v88, v9
	ds_read_b128 v[8:11], v3 offset:1568
	s_waitcnt lgkmcnt(1)
	v_mul_f32_e32 v13, v74, v13
	v_fmac_f32_e32 v13, v71, v12
	v_fmac_f32_e32 v13, v72, v14
	v_fmac_f32_e32 v13, v73, v15
	v_add_f32_e32 v79, v90, v13
	ds_read_b128 v[12:15], v3 offset:1824
	s_waitcnt lgkmcnt(1)
	v_mul_f32_e32 v9, v74, v9
	v_fmac_f32_e32 v9, v71, v8
	v_fmac_f32_e32 v9, v72, v10
	v_fmac_f32_e32 v9, v73, v11
	v_add_f32_e32 v78, v89, v9
	ds_read_b128 v[8:11], v3 offset:2080
	s_waitcnt lgkmcnt(1)
	v_mul_f32_e32 v13, v74, v13
	v_fmac_f32_e32 v13, v71, v12
	v_fmac_f32_e32 v13, v72, v14
	v_fmac_f32_e32 v13, v73, v15
	v_add_f32_e32 v77, v87, v13
	ds_read_b128 v[12:15], v3 offset:2336
	s_waitcnt lgkmcnt(1)
	v_mul_f32_e32 v9, v74, v9
	v_fmac_f32_e32 v9, v71, v8
	v_fmac_f32_e32 v9, v72, v10
	v_fmac_f32_e32 v9, v73, v11
	v_add_f32_e32 v76, v86, v9
	ds_read_b128 v[8:11], v3 offset:2592
	s_waitcnt lgkmcnt(1)
	v_mul_f32_e32 v13, v74, v13
	v_fmac_f32_e32 v13, v71, v12
	v_fmac_f32_e32 v13, v72, v14
	v_fmac_f32_e32 v13, v73, v15
	v_add_f32_e32 v75, v85, v13
	ds_read_b128 v[84:87], v3 offset:2848
	s_waitcnt lgkmcnt(1)
	v_mul_f32_e32 v9, v74, v9
	v_fmac_f32_e32 v9, v71, v8
	v_fmac_f32_e32 v9, v72, v10
	v_fmac_f32_e32 v9, v73, v11
	v_add_f32_e32 v14, v91, v9
	ds_read_b128 v[8:11], v3 offset:3104
	s_waitcnt lgkmcnt(1)
	v_mul_f32_e32 v12, v74, v85
	v_fmac_f32_e32 v12, v71, v84
	v_fmac_f32_e32 v12, v72, v86
	v_fmac_f32_e32 v12, v73, v87
	ds_read_b128 v[84:87], v3 offset:3360
	ds_read_b128 v[88:91], v3 offset:3616
	s_waitcnt lgkmcnt(2)
	v_mul_f32_e32 v9, v74, v9
	v_fmac_f32_e32 v9, v71, v8
	v_fmac_f32_e32 v9, v72, v10
	s_waitcnt lgkmcnt(1)
	v_mul_f32_e32 v8, v74, v85
	v_fmac_f32_e32 v8, v71, v84
	v_fmac_f32_e32 v8, v72, v86
	v_fmac_f32_e32 v8, v73, v87
	ds_read_b128 v[84:87], v3 offset:3872
	v_add_f32_e32 v10, v102, v8
	s_waitcnt lgkmcnt(1)
	v_mul_f32_e32 v8, v74, v89
	v_fmac_f32_e32 v8, v71, v88
	v_fmac_f32_e32 v8, v72, v90
	v_fmac_f32_e32 v9, v73, v11
	v_fmac_f32_e32 v8, v73, v91
	s_waitcnt vmcnt(50)
	v_mul_f32_e32 v5, v70, v5
	v_add_f32_e32 v11, v101, v9
	v_add_f32_e32 v9, v96, v8
	s_waitcnt lgkmcnt(0)
	v_mul_f32_e32 v8, v74, v85
	v_fmac_f32_e32 v5, v67, v4
	v_fmac_f32_e32 v8, v71, v84
	s_waitcnt vmcnt(49)
	v_fmac_f32_e32 v5, v68, v6
	v_fmac_f32_e32 v8, v72, v86
	s_waitcnt vmcnt(48)
	v_fmac_f32_e32 v5, v69, v7
	v_fmac_f32_e32 v8, v73, v87
	ds_read_b128 v[84:87], v3 offset:304
	v_add_f32_e32 v13, v93, v5
	ds_read_b128 v[4:7], v3 offset:560
	v_add_f32_e32 v8, v92, v8
	v_add_f32_e32 v12, v100, v12
	s_waitcnt lgkmcnt(1)
	v_mul_f32_e32 v15, v70, v85
	v_fmac_f32_e32 v15, v67, v84
	s_waitcnt lgkmcnt(0)
	v_mul_f32_e32 v5, v70, v5
	v_fmac_f32_e32 v5, v67, v4
	v_fmac_f32_e32 v5, v68, v6
	v_fmac_f32_e32 v15, v68, v86
	v_fmac_f32_e32 v5, v69, v7
	v_fmac_f32_e32 v15, v69, v87
	ds_read_b128 v[84:87], v3 offset:816
	v_add_f32_e32 v71, v82, v5
	ds_read_b128 v[4:7], v3 offset:1072
	v_add_f32_e32 v15, v83, v15
	s_addc_u32 s39, s47, 0
	s_waitcnt lgkmcnt(1)
	v_mul_f32_e32 v72, v70, v85
	v_fmac_f32_e32 v72, v67, v84
	s_waitcnt lgkmcnt(0)
	v_mul_f32_e32 v5, v70, v5
	v_fmac_f32_e32 v5, v67, v4
	v_fmac_f32_e32 v5, v68, v6
	v_fmac_f32_e32 v5, v69, v7
	ds_read_b128 v[82:85], v3 offset:1328
	v_add_f32_e32 v73, v80, v5
	ds_read_b128 v[4:7], v3 offset:1584
	v_fmac_f32_e32 v72, v68, v86
	v_fmac_f32_e32 v72, v69, v87
	s_waitcnt lgkmcnt(1)
	v_mul_f32_e32 v74, v70, v83
	v_add_f32_e32 v72, v81, v72
	s_waitcnt lgkmcnt(0)
	v_mul_f32_e32 v5, v70, v5
	v_fmac_f32_e32 v74, v67, v82
	ds_read_b128 v[80:83], v3 offset:1840
	v_fmac_f32_e32 v5, v67, v4
	v_fmac_f32_e32 v5, v68, v6
	v_fmac_f32_e32 v5, v69, v7
	v_fmac_f32_e32 v74, v68, v84
	v_add_f32_e32 v78, v78, v5
	ds_read_b128 v[4:7], v3 offset:2096
	v_fmac_f32_e32 v74, v69, v85
	v_add_f32_e32 v74, v79, v74
	s_waitcnt lgkmcnt(1)
; __device__ __forceinline__ void rwkv_fin_item(const Params& p, int l, int item, char* ldsraw) {
;     ...
; #pragma unroll
;     for (int i4 = 0; i4 < 16; i4++) {
; #pragma unroll
;       for (int t = 0; t < 16; t++) {
;         const f32x4 x = *(const f32x4*)(lds + t * 64 + i4 * 4);
;         gacc[t] += x[0] * g2c[i4 * 4] + x[1] * g2c[i4 * 4 + 1] + x[2] * g2c[i4 * 4 + 2] + x[3] * g2c[i4 * 4 + 3];
;       }
;     }
	v_mul_f32_e32 v79, v70, v81
	v_fmac_f32_e32 v79, v67, v80
	v_fmac_f32_e32 v79, v68, v82
	v_fmac_f32_e32 v79, v69, v83
	s_waitcnt lgkmcnt(0)
	v_mul_f32_e32 v5, v70, v5
	ds_read_b128 v[80:83], v3 offset:2352
	v_fmac_f32_e32 v5, v67, v4
	v_fmac_f32_e32 v5, v68, v6
	v_fmac_f32_e32 v5, v69, v7
	v_add_f32_e32 v76, v76, v5
	ds_read_b128 v[4:7], v3 offset:2608
	v_add_f32_e32 v77, v77, v79
	s_waitcnt lgkmcnt(1)
	v_mul_f32_e32 v79, v70, v81
	v_fmac_f32_e32 v79, v67, v80
	v_fmac_f32_e32 v79, v68, v82
	v_fmac_f32_e32 v79, v69, v83
	ds_read_b128 v[82:85], v3 offset:2864
	s_waitcnt lgkmcnt(1)
	v_mul_f32_e32 v5, v70, v5
	v_fmac_f32_e32 v5, v67, v4
	v_fmac_f32_e32 v5, v68, v6
	v_fmac_f32_e32 v5, v69, v7
	v_add_f32_e32 v81, v14, v5
	ds_read_b128 v[4:7], v3 offset:3120
	s_waitcnt lgkmcnt(1)
	v_mul_f32_e32 v14, v70, v83
	v_fmac_f32_e32 v14, v67, v82
	v_fmac_f32_e32 v14, v68, v84
	v_fmac_f32_e32 v14, v69, v85
	ds_read_b128 v[82:85], v3 offset:3376
	ds_read_b128 v[86:89], v3 offset:3632
	s_waitcnt lgkmcnt(2)
	v_mul_f32_e32 v5, v70, v5
	v_fmac_f32_e32 v5, v67, v4
	v_fmac_f32_e32 v5, v68, v6
	s_waitcnt lgkmcnt(1)
	v_mul_f32_e32 v4, v70, v83
	v_fmac_f32_e32 v4, v67, v82
	v_fmac_f32_e32 v4, v68, v84
	v_fmac_f32_e32 v5, v69, v7
	v_fmac_f32_e32 v4, v69, v85
	v_add_f32_e32 v90, v11, v5
	v_add_f32_e32 v91, v10, v4
	ds_read_b128 v[4:7], v3 offset:3888
	s_waitcnt lgkmcnt(1)
	v_mul_f32_e32 v10, v70, v87
	ds_read_b128 v[82:85], v3 offset:64
	v_fmac_f32_e32 v10, v67, v86
	v_fmac_f32_e32 v10, v68, v88
	s_waitcnt lgkmcnt(1)
	v_mul_f32_e32 v5, v70, v5
	v_fmac_f32_e32 v5, v67, v4
	v_fmac_f32_e32 v5, v68, v6
	v_fmac_f32_e32 v5, v69, v7
	v_add_f32_e32 v87, v8, v5
	ds_read_b128 v[4:7], v3 offset:320
	s_waitcnt vmcnt(46) lgkmcnt(1)
	v_mul_f32_e32 v8, v66, v83
	v_fmac_f32_e32 v8, v63, v82
	s_waitcnt vmcnt(45)
	v_fmac_f32_e32 v8, v64, v84
	v_fmac_f32_e32 v10, v69, v89
	s_waitcnt lgkmcnt(0)
	v_mul_f32_e32 v5, v66, v5
	v_fmac_f32_e32 v5, v63, v4
	v_fmac_f32_e32 v5, v64, v6
	s_waitcnt vmcnt(44)
	v_fmac_f32_e32 v8, v65, v85
	v_fmac_f32_e32 v5, v65, v7
	v_add_f32_e32 v80, v75, v79
	v_add_f32_e32 v12, v12, v14
	v_add_f32_e32 v86, v9, v10
	v_add_f32_e32 v14, v13, v8
	ds_read_b128 v[8:11], v3 offset:576
	v_add_f32_e32 v79, v15, v5
	ds_read_b128 v[4:7], v3 offset:832
	v_readlane_b32 s8, v252, 23
	v_readlane_b32 s9, v252, 24
	s_waitcnt lgkmcnt(1)
	v_mul_f32_e32 v9, v66, v9
	v_fmac_f32_e32 v9, v63, v8
	s_waitcnt lgkmcnt(0)
	v_mul_f32_e32 v5, v66, v5
	v_fmac_f32_e32 v5, v63, v4
	v_fmac_f32_e32 v9, v64, v10
	v_fmac_f32_e32 v5, v64, v6
	v_fmac_f32_e32 v9, v65, v11
	v_fmac_f32_e32 v5, v65, v7
	v_add_f32_e32 v75, v71, v9
	ds_read_b128 v[8:11], v3 offset:1088
	v_add_f32_e32 v72, v72, v5
	ds_read_b128 v[4:7], v3 offset:1344
	s_ashr_i32 s2, s31, 6
	s_and_b32 s2, s2, -4
	s_waitcnt lgkmcnt(1)
	v_mul_f32_e32 v9, v66, v9
	v_fmac_f32_e32 v9, v63, v8
	s_waitcnt lgkmcnt(0)
	v_mul_f32_e32 v5, v66, v5
	v_fmac_f32_e32 v5, v63, v4
	v_fmac_f32_e32 v9, v64, v10
	v_fmac_f32_e32 v5, v64, v6
	v_fmac_f32_e32 v9, v65, v11
	v_fmac_f32_e32 v5, v65, v7
	v_add_f32_e32 v71, v73, v9
	ds_read_b128 v[8:11], v3 offset:1600
	v_add_f32_e32 v70, v74, v5
	ds_read_b128 v[4:7], v3 offset:1856
	v_readlane_b32 s10, v252, 25
	v_readlane_b32 s11, v252, 26
	s_waitcnt lgkmcnt(1)
	v_mul_f32_e32 v9, v66, v9
	v_fmac_f32_e32 v9, v63, v8
	s_waitcnt lgkmcnt(0)
	v_mul_f32_e32 v5, v66, v5
	v_fmac_f32_e32 v5, v63, v4
	v_fmac_f32_e32 v9, v64, v10
	v_fmac_f32_e32 v5, v64, v6
	v_fmac_f32_e32 v9, v65, v11
	v_fmac_f32_e32 v5, v65, v7
	v_add_f32_e32 v69, v78, v9
	ds_read_b128 v[8:11], v3 offset:2112
	v_add_f32_e32 v68, v77, v5
	ds_read_b128 v[4:7], v3 offset:2368
	v_lshlrev_b64 v[114:115], 1, v[0:1]
	s_movk_i32 s4, 0x280
	s_waitcnt lgkmcnt(1)
	v_mul_f32_e32 v9, v66, v9
	v_fmac_f32_e32 v9, v63, v8
	s_waitcnt lgkmcnt(0)
	v_mul_f32_e32 v5, v66, v5
	v_fmac_f32_e32 v5, v63, v4
	v_fmac_f32_e32 v9, v64, v10
	v_fmac_f32_e32 v5, v64, v6
	v_fmac_f32_e32 v9, v65, v11
	v_fmac_f32_e32 v5, v65, v7
	v_add_f32_e32 v67, v76, v9
	ds_read_b128 v[8:11], v3 offset:2624
	v_add_f32_e32 v15, v80, v5
	ds_read_b128 v[4:7], v3 offset:2880
	v_readlane_b32 s5, v252, 20
	v_readlane_b32 s6, v252, 21
	s_waitcnt lgkmcnt(1)
	v_mul_f32_e32 v9, v66, v9
	v_fmac_f32_e32 v9, v63, v8
	s_waitcnt lgkmcnt(0)
	v_mul_f32_e32 v5, v66, v5
	v_fmac_f32_e32 v5, v63, v4
	v_fmac_f32_e32 v9, v64, v10
	v_fmac_f32_e32 v5, v64, v6
	v_fmac_f32_e32 v9, v65, v11
	v_fmac_f32_e32 v5, v65, v7
	v_add_f32_e32 v13, v81, v9
	ds_read_b128 v[80:83], v3 offset:3136
	v_add_f32_e32 v11, v12, v5
	ds_read_b128 v[4:7], v3 offset:3392
	v_readlane_b32 s7, v252, 22
	v_readlane_b32 s12, v252, 27
	s_waitcnt lgkmcnt(1)
	v_mul_f32_e32 v8, v66, v81
	v_fmac_f32_e32 v8, v63, v80
	s_waitcnt lgkmcnt(0)
	v_mul_f32_e32 v5, v66, v5
	v_fmac_f32_e32 v5, v63, v4
	v_fmac_f32_e32 v5, v64, v6
	v_fmac_f32_e32 v8, v64, v82
	v_fmac_f32_e32 v5, v65, v7
	v_fmac_f32_e32 v8, v65, v83
	ds_read_b128 v[80:83], v3 offset:3648
	v_add_f32_e32 v9, v91, v5
	ds_read_b128 v[4:7], v3 offset:3904
	v_add_f32_e32 v10, v90, v8
	v_readlane_b32 s13, v252, 28
	s_waitcnt lgkmcnt(1)
	v_mul_f32_e32 v8, v66, v81
	v_fmac_f32_e32 v8, v63, v80
	s_waitcnt lgkmcnt(0)
	v_mul_f32_e32 v5, v66, v5
	v_fmac_f32_e32 v5, v63, v4
	v_fmac_f32_e32 v5, v64, v6
	v_fmac_f32_e32 v8, v64, v82
	v_fmac_f32_e32 v5, v65, v7
	v_fmac_f32_e32 v8, v65, v83
	ds_read_b128 v[80:83], v3 offset:80
	v_add_f32_e32 v12, v87, v5
	ds_read_b128 v[4:7], v3 offset:336
	v_add_f32_e32 v8, v86, v8
	v_readlane_b32 s14, v252, 29
	s_waitcnt vmcnt(42) lgkmcnt(1)
	v_mul_f32_e32 v63, v62, v81
	v_fmac_f32_e32 v63, v59, v80
	s_waitcnt lgkmcnt(0)
	v_mul_f32_e32 v5, v62, v5
	v_fmac_f32_e32 v5, v59, v4
	s_waitcnt vmcnt(41)
; __device__ __forceinline__ void rwkv_fin_item(const Params& p, int l, int item, char* ldsraw) {
;     ...
; #pragma unroll
;     for (int i4 = 0; i4 < 16; i4++) {
; #pragma unroll
;       for (int t = 0; t < 16; t++) {
;         const f32x4 x = *(const f32x4*)(lds + t * 64 + i4 * 4);
;         gacc[t] += x[0] * g2c[i4 * 4] + x[1] * g2c[i4 * 4 + 1] + x[2] * g2c[i4 * 4 + 2] + x[3] * g2c[i4 * 4 + 3];
;       }
;     }
	v_fmac_f32_e32 v63, v60, v82
	v_fmac_f32_e32 v5, v60, v6
	s_waitcnt vmcnt(40)
	v_fmac_f32_e32 v63, v61, v83
	v_fmac_f32_e32 v5, v61, v7
	v_add_f32_e32 v14, v14, v63
	ds_read_b128 v[80:83], v3 offset:592
	v_add_f32_e32 v63, v79, v5
	ds_read_b128 v[4:7], v3 offset:848
	v_readlane_b32 s15, v252, 30
	v_readlane_b32 s16, v252, 31
	s_waitcnt lgkmcnt(1)
	v_mul_f32_e32 v64, v62, v81
	v_fmac_f32_e32 v64, v59, v80
	s_waitcnt lgkmcnt(0)
	v_mul_f32_e32 v5, v62, v5
	v_fmac_f32_e32 v5, v59, v4
	v_fmac_f32_e32 v64, v60, v82
	v_fmac_f32_e32 v5, v60, v6
	v_fmac_f32_e32 v64, v61, v83
	v_fmac_f32_e32 v5, v61, v7
	v_add_f32_e32 v64, v75, v64
	ds_read_b128 v[74:77], v3 offset:1104
	v_add_f32_e32 v65, v72, v5
	ds_read_b128 v[4:7], v3 offset:1360
	v_readlane_b32 s17, v252, 32
	v_readlane_b32 s18, v252, 33
	s_waitcnt lgkmcnt(1)
	v_mul_f32_e32 v66, v62, v75
	v_fmac_f32_e32 v66, v59, v74
	s_waitcnt lgkmcnt(0)
	v_mul_f32_e32 v5, v62, v5
	v_fmac_f32_e32 v5, v59, v4
	v_fmac_f32_e32 v5, v60, v6
	v_fmac_f32_e32 v5, v61, v7
	ds_read_b128 v[72:75], v3 offset:1616
	v_add_f32_e32 v70, v70, v5
	ds_read_b128 v[4:7], v3 offset:1872
	v_fmac_f32_e32 v66, v60, v76
	v_fmac_f32_e32 v66, v61, v77
	v_add_f32_e32 v66, v71, v66
	s_waitcnt lgkmcnt(1)
	v_mul_f32_e32 v71, v62, v73
	s_waitcnt lgkmcnt(0)
	v_mul_f32_e32 v5, v62, v5
	v_fmac_f32_e32 v5, v59, v4
	v_fmac_f32_e32 v71, v59, v72
	v_fmac_f32_e32 v5, v60, v6
	v_fmac_f32_e32 v71, v60, v74
	v_fmac_f32_e32 v5, v61, v7
	v_fmac_f32_e32 v71, v61, v75
	ds_read_b128 v[72:75], v3 offset:2128
	v_add_f32_e32 v68, v68, v5
	ds_read_b128 v[4:7], v3 offset:2384
	v_add_f32_e32 v69, v69, v71
	v_readlane_b32 s19, v252, 34
	s_waitcnt lgkmcnt(1)
	v_mul_f32_e32 v71, v62, v73
	v_fmac_f32_e32 v71, v59, v72
	s_waitcnt lgkmcnt(0)
	v_mul_f32_e32 v5, v62, v5
	v_fmac_f32_e32 v5, v59, v4
	v_fmac_f32_e32 v5, v60, v6
	v_fmac_f32_e32 v71, v60, v74
	v_fmac_f32_e32 v5, v61, v7
	v_fmac_f32_e32 v71, v61, v75
	ds_read_b128 v[72:75], v3 offset:2640
	v_add_f32_e32 v15, v15, v5
	ds_read_b128 v[4:7], v3 offset:2896
	v_add_f32_e32 v71, v67, v71
	s_waitcnt lgkmcnt(1)
	v_mul_f32_e32 v67, v62, v73
	v_fmac_f32_e32 v67, v59, v72
	s_waitcnt lgkmcnt(0)
	v_mul_f32_e32 v5, v62, v5
	v_fmac_f32_e32 v5, v59, v4
	v_fmac_f32_e32 v5, v60, v6
	v_fmac_f32_e32 v67, v60, v74
	v_fmac_f32_e32 v5, v61, v7
	v_fmac_f32_e32 v67, v61, v75
	ds_read_b128 v[72:75], v3 offset:3152
	v_add_f32_e32 v76, v11, v5
	ds_read_b128 v[4:7], v3 offset:3408
	v_add_f32_e32 v13, v13, v67
	s_waitcnt lgkmcnt(1)
	v_mul_f32_e32 v11, v62, v73
	v_fmac_f32_e32 v11, v59, v72
	s_waitcnt lgkmcnt(0)
	v_mul_f32_e32 v5, v62, v5
	v_fmac_f32_e32 v5, v59, v4
	v_fmac_f32_e32 v5, v60, v6
	v_fmac_f32_e32 v11, v60, v74
	v_fmac_f32_e32 v5, v61, v7
	v_fmac_f32_e32 v11, v61, v75
	ds_read_b128 v[72:75], v3 offset:3664
	v_add_f32_e32 v78, v9, v5
	ds_read_b128 v[4:7], v3 offset:3920
	v_add_f32_e32 v77, v10, v11
	s_waitcnt lgkmcnt(1)
	v_mul_f32_e32 v9, v62, v73
	v_fmac_f32_e32 v9, v59, v72
	s_waitcnt lgkmcnt(0)
	v_mul_f32_e32 v5, v62, v5
	v_fmac_f32_e32 v5, v59, v4
	v_fmac_f32_e32 v9, v60, v74
	v_fmac_f32_e32 v5, v60, v6
	v_fmac_f32_e32 v9, v61, v75
	v_fmac_f32_e32 v5, v61, v7
	v_add_f32_e32 v73, v8, v9
	ds_read_b128 v[8:11], v3 offset:96
	v_add_f32_e32 v12, v12, v5
	ds_read_b128 v[4:7], v3 offset:352
	s_waitcnt vmcnt(38) lgkmcnt(1)
	v_mul_f32_e32 v9, v58, v9
	v_fmac_f32_e32 v9, v53, v8
	s_waitcnt lgkmcnt(0)
	v_mul_f32_e32 v5, v58, v5
	v_fmac_f32_e32 v5, v53, v4
	s_waitcnt vmcnt(37)
	v_fmac_f32_e32 v9, v54, v10
	v_fmac_f32_e32 v5, v54, v6
	s_waitcnt vmcnt(36)
	v_fmac_f32_e32 v9, v55, v11
	v_fmac_f32_e32 v5, v55, v7
	v_add_f32_e32 v14, v14, v9
	ds_read_b128 v[8:11], v3 offset:608
	v_add_f32_e32 v72, v63, v5
	ds_read_b128 v[4:7], v3 offset:864
	s_waitcnt lgkmcnt(1)
	v_mul_f32_e32 v9, v58, v9
	v_fmac_f32_e32 v9, v53, v8
	s_waitcnt lgkmcnt(0)
	v_mul_f32_e32 v5, v58, v5
	v_fmac_f32_e32 v5, v53, v4
	v_fmac_f32_e32 v9, v54, v10
	v_fmac_f32_e32 v5, v54, v6
	v_fmac_f32_e32 v9, v55, v11
	v_fmac_f32_e32 v5, v55, v7
	v_add_f32_e32 v67, v64, v9
	ds_read_b128 v[8:11], v3 offset:1120
	v_add_f32_e32 v64, v65, v5
	ds_read_b128 v[4:7], v3 offset:1376
	s_waitcnt lgkmcnt(1)
	v_mul_f32_e32 v9, v58, v9
	v_fmac_f32_e32 v9, v53, v8
	s_waitcnt lgkmcnt(0)
	v_mul_f32_e32 v5, v58, v5
	v_fmac_f32_e32 v5, v53, v4
	v_fmac_f32_e32 v9, v54, v10
	v_fmac_f32_e32 v5, v54, v6
	v_fmac_f32_e32 v9, v55, v11
	v_fmac_f32_e32 v5, v55, v7
	v_add_f32_e32 v63, v66, v9
	ds_read_b128 v[8:11], v3 offset:1632
	v_add_f32_e32 v62, v70, v5
	ds_read_b128 v[4:7], v3 offset:1888
	s_waitcnt lgkmcnt(1)
	v_mul_f32_e32 v9, v58, v9
	v_fmac_f32_e32 v9, v53, v8
	s_waitcnt lgkmcnt(0)
	v_mul_f32_e32 v5, v58, v5
	v_fmac_f32_e32 v5, v53, v4
	v_fmac_f32_e32 v9, v54, v10
	v_fmac_f32_e32 v5, v54, v6
	v_fmac_f32_e32 v9, v55, v11
	v_fmac_f32_e32 v5, v55, v7
	v_add_f32_e32 v61, v69, v9
	ds_read_b128 v[8:11], v3 offset:2144
	v_add_f32_e32 v60, v68, v5
	ds_read_b128 v[4:7], v3 offset:2400
	s_waitcnt lgkmcnt(1)
	v_mul_f32_e32 v9, v58, v9
	v_fmac_f32_e32 v9, v53, v8
	s_waitcnt lgkmcnt(0)
	v_mul_f32_e32 v5, v58, v5
	v_fmac_f32_e32 v5, v53, v4
	v_fmac_f32_e32 v9, v54, v10
	v_fmac_f32_e32 v5, v54, v6
	v_fmac_f32_e32 v9, v55, v11
	v_fmac_f32_e32 v5, v55, v7
	v_add_f32_e32 v59, v71, v9
	ds_read_b128 v[8:11], v3 offset:2656
	v_add_f32_e32 v15, v15, v5
	ds_read_b128 v[4:7], v3 offset:2912
	ds_read_b128 v[68:71], v3 offset:3168
	s_waitcnt lgkmcnt(2)
	v_mul_f32_e32 v9, v58, v9
	v_fmac_f32_e32 v9, v53, v8
	s_waitcnt lgkmcnt(1)
	v_mul_f32_e32 v5, v58, v5
	v_fmac_f32_e32 v5, v53, v4
	v_fmac_f32_e32 v5, v54, v6
	v_fmac_f32_e32 v9, v54, v10
	v_fmac_f32_e32 v5, v55, v7
	v_fmac_f32_e32 v9, v55, v11
	v_add_f32_e32 v11, v76, v5
	ds_read_b128 v[4:7], v3 offset:3424
	s_waitcnt lgkmcnt(1)
; __device__ __forceinline__ void rwkv_fin_item(const Params& p, int l, int item, char* ldsraw) {
;     ...
; #pragma unroll
;     for (int i4 = 0; i4 < 16; i4++) {
; #pragma unroll
;       for (int t = 0; t < 16; t++) {
;         const f32x4 x = *(const f32x4*)(lds + t * 64 + i4 * 4);
;         gacc[t] += x[0] * g2c[i4 * 4] + x[1] * g2c[i4 * 4 + 1] + x[2] * g2c[i4 * 4 + 2] + x[3] * g2c[i4 * 4 + 3];
;       }
;     }
	v_mul_f32_e32 v8, v58, v69
	v_fmac_f32_e32 v8, v53, v68
	v_fmac_f32_e32 v8, v54, v70
	v_add_f32_e32 v13, v13, v9
	s_waitcnt lgkmcnt(0)
	v_mul_f32_e32 v5, v58, v5
	v_fmac_f32_e32 v5, v53, v4
	v_fmac_f32_e32 v5, v54, v6
	v_fmac_f32_e32 v5, v55, v7
	v_fmac_f32_e32 v8, v55, v71
	ds_read_b128 v[68:71], v3 offset:3680
	v_add_f32_e32 v9, v78, v5
	ds_read_b128 v[4:7], v3 offset:3936
	v_add_f32_e32 v10, v77, v8
	s_waitcnt lgkmcnt(1)
	v_mul_f32_e32 v8, v58, v69
	v_fmac_f32_e32 v8, v53, v68
	s_waitcnt lgkmcnt(0)
	v_mul_f32_e32 v5, v58, v5
	v_fmac_f32_e32 v5, v53, v4
	v_fmac_f32_e32 v5, v54, v6
	v_fmac_f32_e32 v8, v54, v70
	v_fmac_f32_e32 v5, v55, v7
	v_fmac_f32_e32 v8, v55, v71
	ds_read_b128 v[68:71], v3 offset:112
	v_add_f32_e32 v12, v12, v5
	ds_read_b128 v[4:7], v3 offset:368
	v_add_f32_e32 v8, v73, v8
	s_waitcnt vmcnt(34) lgkmcnt(1)
	v_mul_f32_e32 v53, v52, v69
	v_fmac_f32_e32 v53, v49, v68
	s_waitcnt lgkmcnt(0)
	v_mul_f32_e32 v5, v52, v5
	v_fmac_f32_e32 v5, v49, v4
	s_waitcnt vmcnt(33)
	v_fmac_f32_e32 v53, v50, v70
	v_fmac_f32_e32 v5, v50, v6
	s_waitcnt vmcnt(32)
	v_fmac_f32_e32 v53, v51, v71
	v_fmac_f32_e32 v5, v51, v7
	v_add_f32_e32 v14, v14, v53
	ds_read_b128 v[68:71], v3 offset:624
	v_add_f32_e32 v53, v72, v5
	ds_read_b128 v[4:7], v3 offset:880
	s_waitcnt lgkmcnt(1)
	v_mul_f32_e32 v54, v52, v69
	v_fmac_f32_e32 v54, v49, v68
	s_waitcnt lgkmcnt(0)
	v_mul_f32_e32 v5, v52, v5
	v_fmac_f32_e32 v5, v49, v4
	v_fmac_f32_e32 v54, v50, v70
	v_fmac_f32_e32 v5, v50, v6
	v_fmac_f32_e32 v54, v51, v71
	v_fmac_f32_e32 v5, v51, v7
	v_add_f32_e32 v54, v67, v54
	ds_read_b128 v[66:69], v3 offset:1136
	v_add_f32_e32 v55, v64, v5
	ds_read_b128 v[4:7], v3 offset:1392
	s_waitcnt lgkmcnt(1)
	v_mul_f32_e32 v58, v52, v67
	v_fmac_f32_e32 v58, v49, v66
	s_waitcnt lgkmcnt(0)
	v_mul_f32_e32 v5, v52, v5
	v_fmac_f32_e32 v5, v49, v4
	v_fmac_f32_e32 v5, v50, v6
	v_fmac_f32_e32 v5, v51, v7
	ds_read_b128 v[64:67], v3 offset:1648
	v_add_f32_e32 v62, v62, v5
	ds_read_b128 v[4:7], v3 offset:1904
	v_fmac_f32_e32 v58, v50, v68
	v_fmac_f32_e32 v58, v51, v69
	v_add_f32_e32 v58, v63, v58
	s_waitcnt lgkmcnt(1)
	v_mul_f32_e32 v63, v52, v65
	s_waitcnt lgkmcnt(0)
	v_mul_f32_e32 v5, v52, v5
	v_fmac_f32_e32 v5, v49, v4
	v_fmac_f32_e32 v63, v49, v64
	v_fmac_f32_e32 v5, v50, v6
	v_fmac_f32_e32 v63, v50, v66
	v_fmac_f32_e32 v5, v51, v7
	v_fmac_f32_e32 v63, v51, v67
	ds_read_b128 v[64:67], v3 offset:2160
	v_add_f32_e32 v60, v60, v5
	ds_read_b128 v[4:7], v3 offset:2416
	v_add_f32_e32 v61, v61, v63
	s_waitcnt lgkmcnt(1)
	v_mul_f32_e32 v63, v52, v65
	v_fmac_f32_e32 v63, v49, v64
	s_waitcnt lgkmcnt(0)
	v_mul_f32_e32 v5, v52, v5
	v_fmac_f32_e32 v5, v49, v4
	v_fmac_f32_e32 v5, v50, v6
	v_fmac_f32_e32 v63, v50, v66
	v_fmac_f32_e32 v5, v51, v7
	v_fmac_f32_e32 v63, v51, v67
	ds_read_b128 v[64:67], v3 offset:2672
	v_add_f32_e32 v15, v15, v5
	ds_read_b128 v[4:7], v3 offset:2928
	v_add_f32_e32 v63, v59, v63
	s_waitcnt lgkmcnt(1)
	v_mul_f32_e32 v59, v52, v65
	v_fmac_f32_e32 v59, v49, v64
	s_waitcnt lgkmcnt(0)
	v_mul_f32_e32 v5, v52, v5
	v_fmac_f32_e32 v5, v49, v4
	v_fmac_f32_e32 v5, v50, v6
	v_fmac_f32_e32 v59, v50, v66
	v_fmac_f32_e32 v5, v51, v7
	v_fmac_f32_e32 v59, v51, v67
	ds_read_b128 v[64:67], v3 offset:3184
	v_add_f32_e32 v68, v11, v5
	ds_read_b128 v[4:7], v3 offset:3440
	v_add_f32_e32 v13, v13, v59
	s_waitcnt lgkmcnt(1)
	v_mul_f32_e32 v11, v52, v65
	v_fmac_f32_e32 v11, v49, v64
	s_waitcnt lgkmcnt(0)
	v_mul_f32_e32 v5, v52, v5
	v_fmac_f32_e32 v5, v49, v4
	v_fmac_f32_e32 v5, v50, v6
	v_fmac_f32_e32 v11, v50, v66
	v_fmac_f32_e32 v5, v51, v7
	v_fmac_f32_e32 v11, v51, v67
	ds_read_b128 v[64:67], v3 offset:3696
	v_add_f32_e32 v70, v9, v5
	ds_read_b128 v[4:7], v3 offset:3952
	v_add_f32_e32 v69, v10, v11
	s_waitcnt lgkmcnt(1)
	v_mul_f32_e32 v9, v52, v65
	v_fmac_f32_e32 v9, v49, v64
	s_waitcnt lgkmcnt(0)
	v_mul_f32_e32 v5, v52, v5
	v_fmac_f32_e32 v5, v49, v4
	v_fmac_f32_e32 v9, v50, v66
	v_fmac_f32_e32 v5, v50, v6
	v_fmac_f32_e32 v9, v51, v67
	v_fmac_f32_e32 v5, v51, v7
	v_add_f32_e32 v65, v8, v9
	ds_read_b128 v[8:11], v3 offset:128
	v_add_f32_e32 v12, v12, v5
	ds_read_b128 v[4:7], v3 offset:384
	s_waitcnt vmcnt(30) lgkmcnt(1)
	v_mul_f32_e32 v9, v48, v9
	v_fmac_f32_e32 v9, v41, v8
	s_waitcnt lgkmcnt(0)
	v_mul_f32_e32 v5, v48, v5
	v_fmac_f32_e32 v5, v41, v4
	s_waitcnt vmcnt(29)
	v_fmac_f32_e32 v9, v42, v10
	v_fmac_f32_e32 v5, v42, v6
	s_waitcnt vmcnt(28)
	v_fmac_f32_e32 v9, v43, v11
	v_fmac_f32_e32 v5, v43, v7
	v_add_f32_e32 v14, v14, v9
	ds_read_b128 v[8:11], v3 offset:640
	v_add_f32_e32 v64, v53, v5
	ds_read_b128 v[4:7], v3 offset:896
	s_waitcnt lgkmcnt(1)
	v_mul_f32_e32 v9, v48, v9
	v_fmac_f32_e32 v9, v41, v8
	s_waitcnt lgkmcnt(0)
	v_mul_f32_e32 v5, v48, v5
	v_fmac_f32_e32 v5, v41, v4
	v_fmac_f32_e32 v9, v42, v10
	v_fmac_f32_e32 v5, v42, v6
	v_fmac_f32_e32 v9, v43, v11
	v_fmac_f32_e32 v5, v43, v7
	v_add_f32_e32 v59, v54, v9
	ds_read_b128 v[8:11], v3 offset:1152
	v_add_f32_e32 v54, v55, v5
	ds_read_b128 v[4:7], v3 offset:1408
	s_waitcnt lgkmcnt(1)
	v_mul_f32_e32 v9, v48, v9
	v_fmac_f32_e32 v9, v41, v8
	s_waitcnt lgkmcnt(0)
	v_mul_f32_e32 v5, v48, v5
	v_fmac_f32_e32 v5, v41, v4
	v_fmac_f32_e32 v9, v42, v10
	v_fmac_f32_e32 v5, v42, v6
	v_fmac_f32_e32 v9, v43, v11
	v_fmac_f32_e32 v5, v43, v7
	v_add_f32_e32 v53, v58, v9
	ds_read_b128 v[8:11], v3 offset:1664
	v_add_f32_e32 v52, v62, v5
	ds_read_b128 v[4:7], v3 offset:1920
	s_waitcnt lgkmcnt(1)
	v_mul_f32_e32 v9, v48, v9
	v_fmac_f32_e32 v9, v41, v8
	s_waitcnt lgkmcnt(0)
	v_mul_f32_e32 v5, v48, v5
	v_fmac_f32_e32 v5, v41, v4
	v_fmac_f32_e32 v9, v42, v10
	v_fmac_f32_e32 v5, v42, v6
	v_fmac_f32_e32 v9, v43, v11
	v_fmac_f32_e32 v5, v43, v7
	v_add_f32_e32 v51, v61, v9
	ds_read_b128 v[8:11], v3 offset:2176
	v_add_f32_e32 v50, v60, v5
	ds_read_b128 v[4:7], v3 offset:2432
	s_waitcnt lgkmcnt(1)
; __device__ __forceinline__ void rwkv_fin_item(const Params& p, int l, int item, char* ldsraw) {
;     ...
; #pragma unroll
;     for (int i4 = 0; i4 < 16; i4++) {
; #pragma unroll
;       for (int t = 0; t < 16; t++) {
;         const f32x4 x = *(const f32x4*)(lds + t * 64 + i4 * 4);
;         gacc[t] += x[0] * g2c[i4 * 4] + x[1] * g2c[i4 * 4 + 1] + x[2] * g2c[i4 * 4 + 2] + x[3] * g2c[i4 * 4 + 3];
;       }
;     }
	v_mul_f32_e32 v9, v48, v9
	v_fmac_f32_e32 v9, v41, v8
	s_waitcnt lgkmcnt(0)
	v_mul_f32_e32 v5, v48, v5
	v_fmac_f32_e32 v5, v41, v4
	v_fmac_f32_e32 v9, v42, v10
	v_fmac_f32_e32 v5, v42, v6
	v_fmac_f32_e32 v9, v43, v11
	v_fmac_f32_e32 v5, v43, v7
	v_add_f32_e32 v49, v63, v9
	ds_read_b128 v[8:11], v3 offset:2688
	v_add_f32_e32 v15, v15, v5
	ds_read_b128 v[4:7], v3 offset:2944
	ds_read_b128 v[60:63], v3 offset:3200
	s_waitcnt lgkmcnt(2)
	v_mul_f32_e32 v9, v48, v9
	v_fmac_f32_e32 v9, v41, v8
	s_waitcnt lgkmcnt(1)
	v_mul_f32_e32 v5, v48, v5
	v_fmac_f32_e32 v5, v41, v4
	v_fmac_f32_e32 v5, v42, v6
	v_fmac_f32_e32 v9, v42, v10
	v_fmac_f32_e32 v5, v43, v7
	v_fmac_f32_e32 v9, v43, v11
	v_add_f32_e32 v11, v68, v5
	ds_read_b128 v[4:7], v3 offset:3456
	s_waitcnt lgkmcnt(1)
	v_mul_f32_e32 v8, v48, v61
	v_fmac_f32_e32 v8, v41, v60
	v_fmac_f32_e32 v8, v42, v62
	v_add_f32_e32 v13, v13, v9
	s_waitcnt lgkmcnt(0)
	v_mul_f32_e32 v5, v48, v5
	v_fmac_f32_e32 v5, v41, v4
	v_fmac_f32_e32 v5, v42, v6
	v_fmac_f32_e32 v5, v43, v7
	v_fmac_f32_e32 v8, v43, v63
	ds_read_b128 v[60:63], v3 offset:3712
	v_add_f32_e32 v9, v70, v5
	ds_read_b128 v[4:7], v3 offset:3968
	v_add_f32_e32 v10, v69, v8
	s_waitcnt lgkmcnt(1)
	v_mul_f32_e32 v8, v48, v61
	v_fmac_f32_e32 v8, v41, v60
	s_waitcnt lgkmcnt(0)
	v_mul_f32_e32 v5, v48, v5
	v_fmac_f32_e32 v5, v41, v4
	v_fmac_f32_e32 v5, v42, v6
	v_fmac_f32_e32 v8, v42, v62
	v_fmac_f32_e32 v5, v43, v7
	v_fmac_f32_e32 v8, v43, v63
	ds_read_b128 v[60:63], v3 offset:144
	v_add_f32_e32 v12, v12, v5
	ds_read_b128 v[4:7], v3 offset:400
	v_add_f32_e32 v8, v65, v8
	s_waitcnt vmcnt(26) lgkmcnt(1)
	v_mul_f32_e32 v41, v40, v61
	v_fmac_f32_e32 v41, v37, v60
	s_waitcnt lgkmcnt(0)
	v_mul_f32_e32 v5, v40, v5
	v_fmac_f32_e32 v5, v37, v4
	s_waitcnt vmcnt(25)
	v_fmac_f32_e32 v41, v38, v62
	v_fmac_f32_e32 v5, v38, v6
	s_waitcnt vmcnt(24)
	v_fmac_f32_e32 v41, v39, v63
	v_fmac_f32_e32 v5, v39, v7
	v_add_f32_e32 v14, v14, v41
	ds_read_b128 v[60:63], v3 offset:656
	v_add_f32_e32 v41, v64, v5
	ds_read_b128 v[4:7], v3 offset:912
	s_waitcnt lgkmcnt(1)
	v_mul_f32_e32 v42, v40, v61
	v_fmac_f32_e32 v42, v37, v60
	s_waitcnt lgkmcnt(0)
	v_mul_f32_e32 v5, v40, v5
	v_fmac_f32_e32 v5, v37, v4
	v_fmac_f32_e32 v42, v38, v62
	v_fmac_f32_e32 v5, v38, v6
	v_fmac_f32_e32 v42, v39, v63
	v_fmac_f32_e32 v5, v39, v7
	v_add_f32_e32 v42, v59, v42
	ds_read_b128 v[58:61], v3 offset:1168
	v_add_f32_e32 v43, v54, v5
	ds_read_b128 v[4:7], v3 offset:1424
	s_waitcnt lgkmcnt(1)
	v_mul_f32_e32 v48, v40, v59
	v_fmac_f32_e32 v48, v37, v58
	s_waitcnt lgkmcnt(0)
	v_mul_f32_e32 v5, v40, v5
	v_fmac_f32_e32 v5, v37, v4
	v_fmac_f32_e32 v5, v38, v6
	v_fmac_f32_e32 v48, v38, v60
	v_fmac_f32_e32 v5, v39, v7
	v_fmac_f32_e32 v48, v39, v61
	ds_read_b128 v[58:61], v3 offset:1680
	v_add_f32_e32 v52, v52, v5
	ds_read_b128 v[4:7], v3 offset:1936
	v_add_f32_e32 v48, v53, v48
	s_waitcnt lgkmcnt(1)
	v_mul_f32_e32 v53, v40, v59
	v_fmac_f32_e32 v53, v37, v58
	s_waitcnt lgkmcnt(0)
	v_mul_f32_e32 v5, v40, v5
	v_fmac_f32_e32 v5, v37, v4
	v_fmac_f32_e32 v5, v38, v6
	v_fmac_f32_e32 v53, v38, v60
	v_fmac_f32_e32 v5, v39, v7
	v_fmac_f32_e32 v53, v39, v61
	ds_read_b128 v[58:61], v3 offset:2192
	v_add_f32_e32 v50, v50, v5
	ds_read_b128 v[4:7], v3 offset:2448
	v_add_f32_e32 v51, v51, v53
	s_waitcnt lgkmcnt(1)
	v_mul_f32_e32 v53, v40, v59
	v_fmac_f32_e32 v53, v37, v58
	s_waitcnt lgkmcnt(0)
	v_mul_f32_e32 v5, v40, v5
	v_fmac_f32_e32 v5, v37, v4
	v_fmac_f32_e32 v5, v38, v6
	v_fmac_f32_e32 v53, v38, v60
	v_fmac_f32_e32 v5, v39, v7
	v_fmac_f32_e32 v53, v39, v61
	ds_read_b128 v[58:61], v3 offset:2704
	v_add_f32_e32 v15, v15, v5
	ds_read_b128 v[4:7], v3 offset:2960
	v_add_f32_e32 v53, v49, v53
	s_waitcnt lgkmcnt(1)
	v_mul_f32_e32 v49, v40, v59
	v_fmac_f32_e32 v49, v37, v58
	s_waitcnt lgkmcnt(0)
	v_mul_f32_e32 v5, v40, v5
	v_fmac_f32_e32 v5, v37, v4
	v_fmac_f32_e32 v5, v38, v6
	v_fmac_f32_e32 v49, v38, v60
	v_fmac_f32_e32 v5, v39, v7
	v_fmac_f32_e32 v49, v39, v61
	ds_read_b128 v[58:61], v3 offset:3216
	v_add_f32_e32 v55, v11, v5
	ds_read_b128 v[4:7], v3 offset:3472
	v_add_f32_e32 v13, v13, v49
	s_waitcnt lgkmcnt(1)
	v_mul_f32_e32 v11, v40, v59
	v_fmac_f32_e32 v11, v37, v58
	s_waitcnt lgkmcnt(0)
	v_mul_f32_e32 v5, v40, v5
	v_fmac_f32_e32 v5, v37, v4
	v_fmac_f32_e32 v5, v38, v6
	v_fmac_f32_e32 v11, v38, v60
	v_fmac_f32_e32 v5, v39, v7
	v_fmac_f32_e32 v11, v39, v61
	ds_read_b128 v[58:61], v3 offset:3728
	v_add_f32_e32 v63, v9, v5
	ds_read_b128 v[4:7], v3 offset:3984
	v_add_f32_e32 v62, v10, v11
	s_waitcnt lgkmcnt(1)
	v_mul_f32_e32 v9, v40, v59
	v_fmac_f32_e32 v9, v37, v58
	s_waitcnt lgkmcnt(0)
	v_mul_f32_e32 v5, v40, v5
	v_fmac_f32_e32 v5, v37, v4
	v_fmac_f32_e32 v9, v38, v60
	v_fmac_f32_e32 v5, v38, v6
	v_fmac_f32_e32 v9, v39, v61
	v_fmac_f32_e32 v5, v39, v7
	v_add_f32_e32 v58, v8, v9
	ds_read_b128 v[8:11], v3 offset:160
	v_add_f32_e32 v12, v12, v5
	ds_read_b128 v[4:7], v3 offset:416
	s_waitcnt vmcnt(22) lgkmcnt(1)
	v_mul_f32_e32 v9, v36, v9
	v_fmac_f32_e32 v9, v33, v8
	s_waitcnt lgkmcnt(0)
	v_mul_f32_e32 v5, v36, v5
	v_fmac_f32_e32 v5, v33, v4
	s_waitcnt vmcnt(21)
	v_fmac_f32_e32 v9, v34, v10
	v_fmac_f32_e32 v5, v34, v6
	s_waitcnt vmcnt(20)
	v_fmac_f32_e32 v9, v35, v11
	v_fmac_f32_e32 v5, v35, v7
	v_add_f32_e32 v14, v14, v9
	ds_read_b128 v[8:11], v3 offset:672
	v_add_f32_e32 v54, v41, v5
	ds_read_b128 v[4:7], v3 offset:928
	s_waitcnt lgkmcnt(1)
	v_mul_f32_e32 v9, v36, v9
	v_fmac_f32_e32 v9, v33, v8
	s_waitcnt lgkmcnt(0)
	v_mul_f32_e32 v5, v36, v5
	v_fmac_f32_e32 v5, v33, v4
	v_fmac_f32_e32 v9, v34, v10
	v_fmac_f32_e32 v5, v34, v6
	v_fmac_f32_e32 v9, v35, v11
	v_fmac_f32_e32 v5, v35, v7
	v_add_f32_e32 v49, v42, v9
	ds_read_b128 v[8:11], v3 offset:1184
	v_add_f32_e32 v42, v43, v5
	ds_read_b128 v[4:7], v3 offset:1440
	s_waitcnt lgkmcnt(1)
; __device__ __forceinline__ void rwkv_fin_item(const Params& p, int l, int item, char* ldsraw) {
;     ...
; #pragma unroll
;     for (int i4 = 0; i4 < 16; i4++) {
; #pragma unroll
;       for (int t = 0; t < 16; t++) {
;         const f32x4 x = *(const f32x4*)(lds + t * 64 + i4 * 4);
;         gacc[t] += x[0] * g2c[i4 * 4] + x[1] * g2c[i4 * 4 + 1] + x[2] * g2c[i4 * 4 + 2] + x[3] * g2c[i4 * 4 + 3];
;       }
;     }
	v_mul_f32_e32 v9, v36, v9
	v_fmac_f32_e32 v9, v33, v8
	s_waitcnt lgkmcnt(0)
	v_mul_f32_e32 v5, v36, v5
	v_fmac_f32_e32 v5, v33, v4
	v_fmac_f32_e32 v9, v34, v10
	v_fmac_f32_e32 v5, v34, v6
	v_fmac_f32_e32 v9, v35, v11
	v_fmac_f32_e32 v5, v35, v7
	v_add_f32_e32 v41, v48, v9
	ds_read_b128 v[8:11], v3 offset:1696
	v_add_f32_e32 v40, v52, v5
	ds_read_b128 v[4:7], v3 offset:1952
	s_waitcnt lgkmcnt(1)
	v_mul_f32_e32 v9, v36, v9
	v_fmac_f32_e32 v9, v33, v8
	s_waitcnt lgkmcnt(0)
	v_mul_f32_e32 v5, v36, v5
	v_fmac_f32_e32 v5, v33, v4
	v_fmac_f32_e32 v9, v34, v10
	v_fmac_f32_e32 v5, v34, v6
	v_fmac_f32_e32 v9, v35, v11
	v_fmac_f32_e32 v5, v35, v7
	v_add_f32_e32 v39, v51, v9
	ds_read_b128 v[8:11], v3 offset:2208
	v_add_f32_e32 v38, v50, v5
	ds_read_b128 v[4:7], v3 offset:2464
	s_waitcnt lgkmcnt(1)
	v_mul_f32_e32 v9, v36, v9
	v_fmac_f32_e32 v9, v33, v8
	s_waitcnt lgkmcnt(0)
	v_mul_f32_e32 v5, v36, v5
	v_fmac_f32_e32 v5, v33, v4
	v_fmac_f32_e32 v9, v34, v10
	v_fmac_f32_e32 v5, v34, v6
	v_fmac_f32_e32 v9, v35, v11
	v_fmac_f32_e32 v5, v35, v7
	v_add_f32_e32 v37, v53, v9
	ds_read_b128 v[8:11], v3 offset:2720
	v_add_f32_e32 v15, v15, v5
	ds_read_b128 v[4:7], v3 offset:2976
	ds_read_b128 v[50:53], v3 offset:3232
	s_waitcnt lgkmcnt(2)
	v_mul_f32_e32 v9, v36, v9
	v_fmac_f32_e32 v9, v33, v8
	s_waitcnt lgkmcnt(1)
	v_mul_f32_e32 v5, v36, v5
	v_fmac_f32_e32 v5, v33, v4
	v_fmac_f32_e32 v5, v34, v6
	v_fmac_f32_e32 v9, v34, v10
	v_fmac_f32_e32 v5, v35, v7
	v_fmac_f32_e32 v9, v35, v11
	v_add_f32_e32 v11, v55, v5
	ds_read_b128 v[4:7], v3 offset:3488
	s_waitcnt lgkmcnt(1)
	v_mul_f32_e32 v8, v36, v51
	v_fmac_f32_e32 v8, v33, v50
	v_fmac_f32_e32 v8, v34, v52
	v_add_f32_e32 v13, v13, v9
	s_waitcnt lgkmcnt(0)
	v_mul_f32_e32 v5, v36, v5
	v_fmac_f32_e32 v5, v33, v4
	v_fmac_f32_e32 v5, v34, v6
	v_fmac_f32_e32 v5, v35, v7
	v_fmac_f32_e32 v8, v35, v53
	ds_read_b128 v[50:53], v3 offset:3744
	v_add_f32_e32 v9, v63, v5
	ds_read_b128 v[4:7], v3 offset:4000
	v_add_f32_e32 v10, v62, v8
	s_waitcnt lgkmcnt(1)
	v_mul_f32_e32 v8, v36, v51
	v_fmac_f32_e32 v8, v33, v50
	s_waitcnt lgkmcnt(0)
	v_mul_f32_e32 v5, v36, v5
	v_fmac_f32_e32 v5, v33, v4
	v_fmac_f32_e32 v5, v34, v6
	v_fmac_f32_e32 v8, v34, v52
	v_fmac_f32_e32 v5, v35, v7
	v_fmac_f32_e32 v8, v35, v53
	ds_read_b128 v[50:53], v3 offset:176
	v_add_f32_e32 v12, v12, v5
	ds_read_b128 v[4:7], v3 offset:432
	v_add_f32_e32 v8, v58, v8
	s_waitcnt vmcnt(18) lgkmcnt(1)
	v_mul_f32_e32 v33, v32, v51
	v_fmac_f32_e32 v33, v29, v50
	s_waitcnt lgkmcnt(0)
	v_mul_f32_e32 v5, v32, v5
	v_fmac_f32_e32 v5, v29, v4
	s_waitcnt vmcnt(17)
	v_fmac_f32_e32 v33, v30, v52
	v_fmac_f32_e32 v5, v30, v6
	s_waitcnt vmcnt(16)
	v_fmac_f32_e32 v33, v31, v53
	v_fmac_f32_e32 v5, v31, v7
	v_add_f32_e32 v14, v14, v33
	ds_read_b128 v[50:53], v3 offset:688
	v_add_f32_e32 v33, v54, v5
	ds_read_b128 v[4:7], v3 offset:944
	s_waitcnt lgkmcnt(1)
	v_mul_f32_e32 v34, v32, v51
	v_fmac_f32_e32 v34, v29, v50
	s_waitcnt lgkmcnt(0)
	v_mul_f32_e32 v5, v32, v5
	v_fmac_f32_e32 v5, v29, v4
	v_fmac_f32_e32 v34, v30, v52
	v_fmac_f32_e32 v5, v30, v6
	v_fmac_f32_e32 v34, v31, v53
	v_fmac_f32_e32 v5, v31, v7
	v_add_f32_e32 v34, v49, v34
	ds_read_b128 v[48:51], v3 offset:1200
	v_add_f32_e32 v35, v42, v5
	ds_read_b128 v[4:7], v3 offset:1456
	s_waitcnt lgkmcnt(1)
	v_mul_f32_e32 v36, v32, v49
	v_fmac_f32_e32 v36, v29, v48
	s_waitcnt lgkmcnt(0)
	v_mul_f32_e32 v5, v32, v5
	v_fmac_f32_e32 v5, v29, v4
	v_fmac_f32_e32 v5, v30, v6
	v_fmac_f32_e32 v36, v30, v50
	v_fmac_f32_e32 v5, v31, v7
	v_fmac_f32_e32 v36, v31, v51
	ds_read_b128 v[48:51], v3 offset:1712
	v_add_f32_e32 v40, v40, v5
	ds_read_b128 v[4:7], v3 offset:1968
	v_add_f32_e32 v36, v41, v36
	s_waitcnt lgkmcnt(1)
	v_mul_f32_e32 v41, v32, v49
	v_fmac_f32_e32 v41, v29, v48
	s_waitcnt lgkmcnt(0)
	v_mul_f32_e32 v5, v32, v5
	v_fmac_f32_e32 v5, v29, v4
	v_fmac_f32_e32 v5, v30, v6
	v_fmac_f32_e32 v41, v30, v50
	v_fmac_f32_e32 v5, v31, v7
	v_fmac_f32_e32 v41, v31, v51
	ds_read_b128 v[48:51], v3 offset:2224
	v_add_f32_e32 v38, v38, v5
	ds_read_b128 v[4:7], v3 offset:2480
	v_add_f32_e32 v39, v39, v41
	s_waitcnt lgkmcnt(1)
	v_mul_f32_e32 v41, v32, v49
	v_fmac_f32_e32 v41, v29, v48
	s_waitcnt lgkmcnt(0)
	v_mul_f32_e32 v5, v32, v5
	v_fmac_f32_e32 v5, v29, v4
	v_fmac_f32_e32 v5, v30, v6
	v_fmac_f32_e32 v41, v30, v50
	v_fmac_f32_e32 v5, v31, v7
	v_fmac_f32_e32 v41, v31, v51
	ds_read_b128 v[48:51], v3 offset:2736
	v_add_f32_e32 v15, v15, v5
	ds_read_b128 v[4:7], v3 offset:2992
	v_add_f32_e32 v41, v37, v41
	s_waitcnt lgkmcnt(1)
	v_mul_f32_e32 v37, v32, v49
	v_fmac_f32_e32 v37, v29, v48
	s_waitcnt lgkmcnt(0)
	v_mul_f32_e32 v5, v32, v5
	v_fmac_f32_e32 v5, v29, v4
	v_fmac_f32_e32 v5, v30, v6
	v_fmac_f32_e32 v37, v30, v50
	v_fmac_f32_e32 v5, v31, v7
	v_fmac_f32_e32 v37, v31, v51
	ds_read_b128 v[48:51], v3 offset:3248
	v_add_f32_e32 v43, v11, v5
	ds_read_b128 v[4:7], v3 offset:3504
	v_add_f32_e32 v13, v13, v37
	s_waitcnt lgkmcnt(1)
	v_mul_f32_e32 v11, v32, v49
	v_fmac_f32_e32 v11, v29, v48
	s_waitcnt lgkmcnt(0)
	v_mul_f32_e32 v5, v32, v5
	v_fmac_f32_e32 v5, v29, v4
	v_fmac_f32_e32 v5, v30, v6
	v_fmac_f32_e32 v11, v30, v50
	v_fmac_f32_e32 v5, v31, v7
	v_fmac_f32_e32 v11, v31, v51
	ds_read_b128 v[48:51], v3 offset:3760
	v_add_f32_e32 v53, v9, v5
	ds_read_b128 v[4:7], v3 offset:4016
	v_add_f32_e32 v52, v10, v11
	s_waitcnt lgkmcnt(1)
	v_mul_f32_e32 v9, v32, v49
	v_fmac_f32_e32 v9, v29, v48
	s_waitcnt lgkmcnt(0)
	v_mul_f32_e32 v5, v32, v5
	v_fmac_f32_e32 v5, v29, v4
	v_fmac_f32_e32 v9, v30, v50
	v_fmac_f32_e32 v5, v30, v6
	v_fmac_f32_e32 v9, v31, v51
	v_fmac_f32_e32 v5, v31, v7
	v_add_f32_e32 v48, v8, v9
	ds_read_b128 v[8:11], v3 offset:192
	v_add_f32_e32 v12, v12, v5
	ds_read_b128 v[4:7], v3 offset:448
	s_waitcnt vmcnt(14) lgkmcnt(1)
; __device__ __forceinline__ void rwkv_fin_item(const Params& p, int l, int item, char* ldsraw) {
;     ...
; #pragma unroll
;     for (int i4 = 0; i4 < 16; i4++) {
; #pragma unroll
;       for (int t = 0; t < 16; t++) {
;         const f32x4 x = *(const f32x4*)(lds + t * 64 + i4 * 4);
;         gacc[t] += x[0] * g2c[i4 * 4] + x[1] * g2c[i4 * 4 + 1] + x[2] * g2c[i4 * 4 + 2] + x[3] * g2c[i4 * 4 + 3];
;       }
;     }
;     ...
;   const float lw = p.ln_w[l * 256 + tid], lb = p.ln_b[l * 256 + tid];
	v_mul_f32_e32 v9, v28, v9
	v_fmac_f32_e32 v9, v25, v8
	s_waitcnt lgkmcnt(0)
	v_mul_f32_e32 v5, v28, v5
	v_fmac_f32_e32 v5, v25, v4
	s_waitcnt vmcnt(13)
	v_fmac_f32_e32 v9, v26, v10
	v_fmac_f32_e32 v5, v26, v6
	s_waitcnt vmcnt(12)
	v_fmac_f32_e32 v9, v27, v11
	v_fmac_f32_e32 v5, v27, v7
	v_add_f32_e32 v14, v14, v9
	ds_read_b128 v[8:11], v3 offset:704
	v_add_f32_e32 v42, v33, v5
	ds_read_b128 v[4:7], v3 offset:960
	s_waitcnt lgkmcnt(1)
	v_mul_f32_e32 v9, v28, v9
	v_fmac_f32_e32 v9, v25, v8
	s_waitcnt lgkmcnt(0)
	v_mul_f32_e32 v5, v28, v5
	v_fmac_f32_e32 v5, v25, v4
	v_fmac_f32_e32 v9, v26, v10
	v_fmac_f32_e32 v5, v26, v6
	v_fmac_f32_e32 v9, v27, v11
	v_fmac_f32_e32 v5, v27, v7
	v_add_f32_e32 v37, v34, v9
	ds_read_b128 v[8:11], v3 offset:1216
	v_add_f32_e32 v34, v35, v5
	ds_read_b128 v[4:7], v3 offset:1472
	s_waitcnt lgkmcnt(1)
	v_mul_f32_e32 v9, v28, v9
	v_fmac_f32_e32 v9, v25, v8
	s_waitcnt lgkmcnt(0)
	v_mul_f32_e32 v5, v28, v5
	v_fmac_f32_e32 v5, v25, v4
	v_fmac_f32_e32 v9, v26, v10
	v_fmac_f32_e32 v5, v26, v6
	v_fmac_f32_e32 v9, v27, v11
	v_fmac_f32_e32 v5, v27, v7
	v_add_f32_e32 v33, v36, v9
	ds_read_b128 v[8:11], v3 offset:1728
	v_add_f32_e32 v32, v40, v5
	ds_read_b128 v[4:7], v3 offset:1984
	s_waitcnt lgkmcnt(1)
	v_mul_f32_e32 v9, v28, v9
	v_fmac_f32_e32 v9, v25, v8
	s_waitcnt lgkmcnt(0)
	v_mul_f32_e32 v5, v28, v5
	v_fmac_f32_e32 v5, v25, v4
	v_fmac_f32_e32 v9, v26, v10
	v_fmac_f32_e32 v5, v26, v6
	v_fmac_f32_e32 v9, v27, v11
	v_fmac_f32_e32 v5, v27, v7
	v_add_f32_e32 v31, v39, v9
	ds_read_b128 v[8:11], v3 offset:2240
	v_add_f32_e32 v30, v38, v5
	ds_read_b128 v[4:7], v3 offset:2496
	s_waitcnt lgkmcnt(1)
	v_mul_f32_e32 v9, v28, v9
	v_fmac_f32_e32 v9, v25, v8
	s_waitcnt lgkmcnt(0)
	v_mul_f32_e32 v5, v28, v5
	v_fmac_f32_e32 v5, v25, v4
	v_fmac_f32_e32 v9, v26, v10
	v_fmac_f32_e32 v5, v26, v6
	v_fmac_f32_e32 v9, v27, v11
	v_fmac_f32_e32 v5, v27, v7
	v_add_f32_e32 v29, v41, v9
	ds_read_b128 v[8:11], v3 offset:2752
	v_add_f32_e32 v15, v15, v5
	ds_read_b128 v[4:7], v3 offset:3008
	ds_read_b128 v[38:41], v3 offset:3264
	s_waitcnt lgkmcnt(2)
	v_mul_f32_e32 v9, v28, v9
	v_fmac_f32_e32 v9, v25, v8
	s_waitcnt lgkmcnt(1)
	v_mul_f32_e32 v5, v28, v5
	v_fmac_f32_e32 v5, v25, v4
	v_fmac_f32_e32 v5, v26, v6
	v_fmac_f32_e32 v9, v26, v10
	v_fmac_f32_e32 v5, v27, v7
	v_fmac_f32_e32 v9, v27, v11
	v_add_f32_e32 v11, v43, v5
	ds_read_b128 v[4:7], v3 offset:3520
	s_waitcnt lgkmcnt(1)
	v_mul_f32_e32 v8, v28, v39
	v_fmac_f32_e32 v8, v25, v38
	v_fmac_f32_e32 v8, v26, v40
	v_add_f32_e32 v13, v13, v9
	s_waitcnt lgkmcnt(0)
	v_mul_f32_e32 v5, v28, v5
	v_fmac_f32_e32 v5, v25, v4
	v_fmac_f32_e32 v5, v26, v6
	v_fmac_f32_e32 v5, v27, v7
	v_fmac_f32_e32 v8, v27, v41
	ds_read_b128 v[38:41], v3 offset:3776
	v_add_f32_e32 v9, v53, v5
	ds_read_b128 v[4:7], v3 offset:4032
	v_add_f32_e32 v10, v52, v8
	s_waitcnt lgkmcnt(1)
	v_mul_f32_e32 v8, v28, v39
	v_fmac_f32_e32 v8, v25, v38
	s_waitcnt lgkmcnt(0)
	v_mul_f32_e32 v5, v28, v5
	v_fmac_f32_e32 v5, v25, v4
	v_fmac_f32_e32 v5, v26, v6
	v_fmac_f32_e32 v8, v26, v40
	v_fmac_f32_e32 v5, v27, v7
	v_fmac_f32_e32 v8, v27, v41
	ds_read_b128 v[38:41], v3 offset:208
	v_add_f32_e32 v12, v12, v5
	ds_read_b128 v[4:7], v3 offset:464
	v_add_f32_e32 v8, v48, v8
	v_add_u32_e32 v48, s2, v16
	s_waitcnt vmcnt(10) lgkmcnt(1)
	v_mul_f32_e32 v25, v24, v39
	v_fmac_f32_e32 v25, v21, v38
	s_waitcnt lgkmcnt(0)
	v_mul_f32_e32 v5, v24, v5
	v_fmac_f32_e32 v5, v21, v4
	s_waitcnt vmcnt(9)
	v_fmac_f32_e32 v25, v22, v40
	v_fmac_f32_e32 v5, v22, v6
	s_waitcnt vmcnt(8)
	v_fmac_f32_e32 v25, v23, v41
	v_fmac_f32_e32 v5, v23, v7
	v_add_f32_e32 v14, v14, v25
	ds_read_b128 v[38:41], v3 offset:720
	v_add_f32_e32 v25, v42, v5
	ds_read_b128 v[4:7], v3 offset:976
	s_mov_b64 s[2:3], 0x97a8200
	v_ashrrev_i32_e32 v49, 31, v48
	s_waitcnt lgkmcnt(1)
	v_mul_f32_e32 v26, v24, v39
	v_fmac_f32_e32 v26, v21, v38
	s_waitcnt lgkmcnt(0)
	v_mul_f32_e32 v5, v24, v5
	v_fmac_f32_e32 v5, v21, v4
	v_fmac_f32_e32 v26, v22, v40
	v_fmac_f32_e32 v5, v22, v6
	v_fmac_f32_e32 v26, v23, v41
	v_fmac_f32_e32 v5, v23, v7
	v_add_f32_e32 v26, v37, v26
	ds_read_b128 v[36:39], v3 offset:1232
	v_add_f32_e32 v27, v34, v5
	ds_read_b128 v[4:7], v3 offset:1488
	s_waitcnt lgkmcnt(1)
	v_mul_f32_e32 v28, v24, v37
	v_fmac_f32_e32 v28, v21, v36
	s_waitcnt lgkmcnt(0)
	v_mul_f32_e32 v5, v24, v5
	v_fmac_f32_e32 v5, v21, v4
	v_fmac_f32_e32 v5, v22, v6
	v_fmac_f32_e32 v5, v23, v7
	ds_read_b128 v[34:37], v3 offset:1744
	v_add_f32_e32 v32, v32, v5
	ds_read_b128 v[4:7], v3 offset:2000
	v_fmac_f32_e32 v28, v22, v38
	v_fmac_f32_e32 v28, v23, v39
	v_add_f32_e32 v28, v33, v28
	s_waitcnt lgkmcnt(1)
	v_mul_f32_e32 v33, v24, v35
	s_waitcnt lgkmcnt(0)
	v_mul_f32_e32 v5, v24, v5
	v_fmac_f32_e32 v5, v21, v4
	v_fmac_f32_e32 v33, v21, v34
	v_fmac_f32_e32 v5, v22, v6
	v_fmac_f32_e32 v33, v22, v36
	v_fmac_f32_e32 v5, v23, v7
	v_fmac_f32_e32 v33, v23, v37
	ds_read_b128 v[34:37], v3 offset:2256
	v_add_f32_e32 v30, v30, v5
	ds_read_b128 v[4:7], v3 offset:2512
	v_add_f32_e32 v31, v31, v33
	s_waitcnt lgkmcnt(1)
	v_mul_f32_e32 v33, v24, v35
	v_fmac_f32_e32 v33, v21, v34
	s_waitcnt lgkmcnt(0)
	v_mul_f32_e32 v5, v24, v5
	v_fmac_f32_e32 v5, v21, v4
	v_fmac_f32_e32 v33, v22, v36
	v_fmac_f32_e32 v5, v22, v6
	v_fmac_f32_e32 v33, v23, v37
	v_fmac_f32_e32 v5, v23, v7
	v_add_f32_e32 v29, v29, v33
	ds_read_b128 v[34:37], v3 offset:2768
	v_add_f32_e32 v33, v15, v5
	ds_read_b128 v[4:7], v3 offset:3024
	s_waitcnt lgkmcnt(1)
	v_mul_f32_e32 v15, v24, v35
	v_fmac_f32_e32 v15, v21, v34
	s_waitcnt lgkmcnt(0)
; __device__ __forceinline__ void rwkv_fin_item(const Params& p, int l, int item, char* ldsraw) {
;     ...
; #pragma unroll
;     for (int i4 = 0; i4 < 16; i4++) {
; #pragma unroll
;       for (int t = 0; t < 16; t++) {
;         const f32x4 x = *(const f32x4*)(lds + t * 64 + i4 * 4);
;         gacc[t] += x[0] * g2c[i4 * 4] + x[1] * g2c[i4 * 4 + 1] + x[2] * g2c[i4 * 4 + 2] + x[3] * g2c[i4 * 4 + 3];
;       }
;     }
	v_mul_f32_e32 v5, v24, v5
	v_fmac_f32_e32 v5, v21, v4
	v_fmac_f32_e32 v5, v22, v6
	v_fmac_f32_e32 v15, v22, v36
	v_fmac_f32_e32 v5, v23, v7
	v_fmac_f32_e32 v15, v23, v37
	ds_read_b128 v[34:37], v3 offset:3280
	v_add_f32_e32 v39, v11, v5
	ds_read_b128 v[4:7], v3 offset:3536
	v_add_f32_e32 v38, v13, v15
	s_waitcnt lgkmcnt(1)
	v_mul_f32_e32 v11, v24, v35
	v_fmac_f32_e32 v11, v21, v34
	s_waitcnt lgkmcnt(0)
	v_mul_f32_e32 v5, v24, v5
	v_fmac_f32_e32 v5, v21, v4
	v_fmac_f32_e32 v5, v22, v6
	v_fmac_f32_e32 v11, v22, v36
	v_fmac_f32_e32 v5, v23, v7
	v_fmac_f32_e32 v11, v23, v37
	ds_read_b128 v[34:37], v3 offset:3792
	v_add_f32_e32 v41, v9, v5
	ds_read_b128 v[4:7], v3 offset:4048
	v_add_f32_e32 v40, v10, v11
	s_waitcnt lgkmcnt(1)
	v_mul_f32_e32 v9, v24, v35
	v_fmac_f32_e32 v9, v21, v34
	s_waitcnt lgkmcnt(0)
	v_mul_f32_e32 v5, v24, v5
	v_fmac_f32_e32 v5, v21, v4
	v_fmac_f32_e32 v9, v22, v36
	v_fmac_f32_e32 v5, v22, v6
	v_fmac_f32_e32 v9, v23, v37
	v_fmac_f32_e32 v5, v23, v7
	v_add_f32_e32 v34, v8, v9
	ds_read_b128 v[8:11], v3 offset:224
	v_add_f32_e32 v23, v12, v5
	ds_read_b128 v[4:7], v3 offset:480
	s_waitcnt vmcnt(6) lgkmcnt(1)
	v_mul_f32_e32 v9, v20, v9
	v_fmac_f32_e32 v9, v17, v8
	s_waitcnt lgkmcnt(0)
	v_mul_f32_e32 v5, v20, v5
	v_fmac_f32_e32 v5, v17, v4
	s_waitcnt vmcnt(5)
	v_fmac_f32_e32 v9, v18, v10
	v_fmac_f32_e32 v5, v18, v6
	s_waitcnt vmcnt(4)
	v_fmac_f32_e32 v9, v19, v11
	v_fmac_f32_e32 v5, v19, v7
	v_add_f32_e32 v22, v14, v9
	ds_read_b128 v[8:11], v3 offset:736
	v_add_f32_e32 v21, v25, v5
	ds_read_b128 v[4:7], v3 offset:992
	s_waitcnt lgkmcnt(1)
	v_mul_f32_e32 v9, v20, v9
	v_fmac_f32_e32 v9, v17, v8
	s_waitcnt lgkmcnt(0)
	v_mul_f32_e32 v5, v20, v5
	v_fmac_f32_e32 v5, v17, v4
	v_fmac_f32_e32 v9, v18, v10
	v_fmac_f32_e32 v5, v18, v6
	v_fmac_f32_e32 v9, v19, v11
	v_fmac_f32_e32 v5, v19, v7
	v_add_f32_e32 v15, v26, v9
	ds_read_b128 v[8:11], v3 offset:1248
	v_add_f32_e32 v14, v27, v5
	ds_read_b128 v[4:7], v3 offset:1504
	ds_read_b128 v[24:27], v3 offset:3296
	s_waitcnt lgkmcnt(2)
	v_mul_f32_e32 v9, v20, v9
	v_fmac_f32_e32 v9, v17, v8
	s_waitcnt lgkmcnt(1)
	v_mul_f32_e32 v5, v20, v5
	v_fmac_f32_e32 v5, v17, v4
	v_fmac_f32_e32 v9, v18, v10
	v_fmac_f32_e32 v5, v18, v6
	v_fmac_f32_e32 v9, v19, v11
	v_fmac_f32_e32 v5, v19, v7
	v_add_f32_e32 v13, v28, v9
	ds_read_b128 v[8:11], v3 offset:1760
	v_add_f32_e32 v12, v32, v5
	ds_read_b128 v[4:7], v3 offset:2016
	s_waitcnt lgkmcnt(1)
	v_mul_f32_e32 v9, v20, v9
	v_fmac_f32_e32 v9, v17, v8
	s_waitcnt lgkmcnt(0)
	v_mul_f32_e32 v5, v20, v5
	v_fmac_f32_e32 v5, v17, v4
	v_fmac_f32_e32 v9, v18, v10
	v_fmac_f32_e32 v5, v18, v6
	v_fmac_f32_e32 v9, v19, v11
	v_fmac_f32_e32 v5, v19, v7
	v_add_f32_e32 v112, v31, v9
	ds_read_b128 v[8:11], v3 offset:2272
	v_add_f32_e32 v95, v30, v5
	ds_read_b128 v[4:7], v3 offset:2528
	s_waitcnt lgkmcnt(1)
	v_mul_f32_e32 v9, v20, v9
	v_fmac_f32_e32 v9, v17, v8
	s_waitcnt lgkmcnt(0)
	v_mul_f32_e32 v5, v20, v5
	v_fmac_f32_e32 v5, v17, v4
	v_fmac_f32_e32 v9, v18, v10
	v_fmac_f32_e32 v5, v18, v6
	v_fmac_f32_e32 v9, v19, v11
	v_fmac_f32_e32 v5, v19, v7
	v_add_f32_e32 v94, v29, v9
	ds_read_b128 v[8:11], v3 offset:2784
	v_add_f32_e32 v93, v33, v5
	ds_read_b128 v[4:7], v3 offset:3040
	s_waitcnt lgkmcnt(1)
	v_mul_f32_e32 v9, v20, v9
	v_fmac_f32_e32 v9, v17, v8
	s_waitcnt lgkmcnt(0)
	v_mul_f32_e32 v5, v20, v5
	v_fmac_f32_e32 v5, v17, v4
	v_fmac_f32_e32 v5, v18, v6
	v_fmac_f32_e32 v5, v19, v7
	v_fmac_f32_e32 v9, v18, v10
	v_add_f32_e32 v10, v39, v5
	ds_read_b128 v[4:7], v3 offset:3552
	v_mul_f32_e32 v8, v20, v25
	v_fmac_f32_e32 v8, v17, v24
	v_fmac_f32_e32 v8, v18, v26
	v_fmac_f32_e32 v9, v19, v11
	s_waitcnt lgkmcnt(0)
	v_mul_f32_e32 v5, v20, v5
	v_fmac_f32_e32 v5, v17, v4
	v_fmac_f32_e32 v5, v18, v6
	v_fmac_f32_e32 v8, v19, v27
	v_fmac_f32_e32 v5, v19, v7
	v_add_f32_e32 v11, v38, v9
	v_add_f32_e32 v9, v40, v8
	ds_read_b128 v[24:27], v3 offset:3808
	v_add_f32_e32 v8, v41, v5
	ds_read_b128 v[4:7], v3 offset:4064
	s_waitcnt lgkmcnt(1)
	v_mul_f32_e32 v25, v20, v25
	v_fmac_f32_e32 v25, v17, v24
	s_waitcnt lgkmcnt(0)
	v_mul_f32_e32 v5, v20, v5
	v_fmac_f32_e32 v5, v17, v4
	v_fmac_f32_e32 v25, v18, v26
	v_fmac_f32_e32 v5, v18, v6
	v_fmac_f32_e32 v25, v19, v27
	v_fmac_f32_e32 v5, v19, v7
	v_add_f32_e32 v50, v34, v25
	ds_read_b128 v[24:27], v3 offset:240
	v_add_f32_e32 v51, v23, v5
	ds_read_b128 v[4:7], v3 offset:496
	s_waitcnt vmcnt(2) lgkmcnt(1)
	v_mul_f32_e32 v17, v46, v25
	v_fmac_f32_e32 v17, v44, v24
	s_waitcnt lgkmcnt(0)
	v_mul_f32_e32 v5, v46, v5
	v_fmac_f32_e32 v5, v44, v4
	s_waitcnt vmcnt(1)
	v_fmac_f32_e32 v17, v45, v26
	v_fmac_f32_e32 v5, v45, v6
	s_waitcnt vmcnt(0)
	v_fmac_f32_e32 v17, v47, v27
	v_fmac_f32_e32 v5, v47, v7
	v_add_f32_e32 v52, v22, v17
	ds_read_b128 v[22:25], v3 offset:752
	v_add_f32_e32 v53, v21, v5
	ds_read_b128 v[4:7], v3 offset:1008
	ds_read_b128 v[18:21], v3 offset:1264
	s_waitcnt lgkmcnt(2)
	v_mul_f32_e32 v17, v46, v23
	v_fmac_f32_e32 v17, v44, v22
	s_waitcnt lgkmcnt(1)
	v_mul_f32_e32 v5, v46, v5
	v_fmac_f32_e32 v5, v44, v4
	v_fmac_f32_e32 v5, v45, v6
	v_fmac_f32_e32 v5, v47, v7
	v_add_f32_e32 v55, v14, v5
	ds_read_b128 v[4:7], v3 offset:1520
	s_waitcnt lgkmcnt(1)
	v_mul_f32_e32 v14, v46, v19
	v_fmac_f32_e32 v14, v44, v18
	v_fmac_f32_e32 v14, v45, v20
	v_fmac_f32_e32 v14, v47, v21
	s_waitcnt lgkmcnt(0)
; __device__ __forceinline__ float bf2f(unsigned short b) { return __uint_as_float(((unsigned)b) << 16); }
; __device__ __forceinline__ void rwkv_fin_item(const Params& p, int l, int item, char* ldsraw) {
;     ...
;         gacc[t] += x[0] * g2c[i4 * 4] + x[1] * g2c[i4 * 4 + 1] + x[2] * g2c[i4 * 4 + 2] + x[3] * g2c[i4 * 4 + 3];
;       }
;     }
; #pragma unroll
;     for (int t = 0; t < 16; t++) lds[1024 + t * 256 + tid] = gacc[t];
;   }
;   const float lw = p.ln_w[l * 256 + tid], lb = p.ln_b[l * 256 + tid];
;   float yv[16], vv[16], c3v[16];
;   const size_t base0 = (size_t)(b * 4 + h) * S + s0;
; #pragma unroll
;   for (int t = 0; t < 16; t++) { yv[t] = bf2f(Y[(size_t)(tok0 + t) * 1024 + 512 + tid]); vv[t] = bf2f(RB[(base0 + t) * 320 + 256 + jl]); c3v[t] = RC[(base0 + t) * 4 + 2]; }
	v_mul_f32_e32 v5, v46, v5
	v_fmac_f32_e32 v5, v44, v4
	v_fmac_f32_e32 v5, v45, v6
	v_fmac_f32_e32 v5, v47, v7
	v_add_f32_e32 v92, v12, v5
	v_add_u32_e32 v12, s30, v0
	v_fmac_f32_e32 v17, v45, v24
	v_add_f32_e32 v91, v13, v14
	v_ashrrev_i32_e32 v13, 31, v12
	v_fmac_f32_e32 v17, v47, v25
	v_lshlrev_b64 v[12:13], 2, v[12:13]
	v_add_f32_e32 v54, v15, v17
	v_lshl_add_u64 v[14:15], s[8:9], 0, v[12:13]
	global_load_dword v58, v[14:15], off
	v_lshl_add_u64 v[14:15], s[28:29], 0, v[2:3]
	s_add_u32 s28, s27, 0xbfa8008
	s_addc_u32 s29, s39, 0
	s_ashr_i32 s27, s26, 31
	v_lshl_add_u64 v[12:13], s[10:11], 0, v[12:13]
	v_lshl_add_u64 v[14:15], v[14:15], 0, s[2:3]
	s_lshl_b64 s[2:3], s[26:27], 11
	global_load_dword v59, v[12:13], off
	v_lshlrev_b64 v[12:13], 12, v[48:49]
	s_add_u32 s2, s37, s2
	v_or_b32_e32 v12, s36, v12
	s_addc_u32 s3, s38, s3
	v_lshl_add_u64 v[42:43], s[2:3], 0, v[114:115]
	v_mad_u64_u32 v[14:15], s[2:3], v12, s4, v[14:15]
	s_or_b32 s2, s26, 1
	s_ashr_i32 s3, s2, 31
	s_lshl_b64 s[2:3], s[2:3], 11
	s_add_u32 s2, s37, s2
	ds_read_b128 v[18:21], v3 offset:1776
	ds_read_b128 v[4:7], v3 offset:2032
	v_lshlrev_b64 v[116:117], 4, v[12:13]
	s_addc_u32 s3, s38, s3
	v_mad_i32_i24 v15, v13, s4, v15
	v_lshl_add_u64 v[12:13], s[28:29], 0, v[116:117]
	v_lshl_add_u64 v[40:41], s[2:3], 0, v[114:115]
	s_mov_b64 s[2:3], 0x280
	global_load_ushort v75, v[14:15], off
	global_load_dword v74, v[12:13], off
	v_lshl_add_u64 v[12:13], v[14:15], 0, s[2:3]
	s_or_b32 s2, s26, 2
	s_ashr_i32 s3, s2, 31
	s_lshl_b64 s[2:3], s[2:3], 11
	s_waitcnt lgkmcnt(1)
	v_mul_f32_e32 v113, v46, v19
	s_add_u32 s2, s37, s2
	v_fmac_f32_e32 v113, v44, v18
	v_or_b32_e32 v16, 16, v116
	v_mov_b32_e32 v17, v117
	s_addc_u32 s3, s38, s3
	v_or_b32_e32 v18, 32, v116
	v_mov_b32_e32 v19, v117
	v_lshl_add_u64 v[16:17], s[28:29], 0, v[16:17]
	v_lshl_add_u64 v[38:39], s[2:3], 0, v[114:115]
	s_mov_b64 s[2:3], 0x500
	v_lshl_add_u64 v[18:19], s[28:29], 0, v[18:19]
	global_load_ushort v96, v[42:43], off offset:1024
	global_load_ushort v97, v[40:41], off offset:1024
	global_load_ushort v76, v[14:15], off offset:640
	global_load_dword v73, v[16:17], off
	global_load_dword v72, v[18:19], off
	global_load_ushort v77, v[14:15], off offset:1280
	v_lshl_add_u64 v[16:17], v[14:15], 0, s[2:3]
	s_or_b32 s2, s26, 3
	s_ashr_i32 s3, s2, 31
	s_lshl_b64 s[2:3], s[2:3], 11
	s_add_u32 s2, s37, s2
	s_addc_u32 s3, s38, s3
	v_lshl_add_u64 v[36:37], s[2:3], 0, v[114:115]
	s_mov_b64 s[2:3], 0x780
	v_lshl_add_u64 v[18:19], v[14:15], 0, s[2:3]
	s_or_b32 s2, s26, 4
	s_ashr_i32 s3, s2, 31
	s_lshl_b64 s[2:3], s[2:3], 11
	v_fmac_f32_e32 v113, v45, v20
	s_add_u32 s2, s37, s2
	v_fmac_f32_e32 v113, v47, v21
	v_or_b32_e32 v20, 48, v116
	v_mov_b32_e32 v21, v117
	s_addc_u32 s3, s38, s3
	v_or_b32_e32 v22, 64, v116
	v_mov_b32_e32 v23, v117
	v_lshl_add_u64 v[20:21], s[28:29], 0, v[20:21]
	v_lshl_add_u64 v[34:35], s[2:3], 0, v[114:115]
	s_mov_b64 s[2:3], 0xa00
	v_lshl_add_u64 v[22:23], s[28:29], 0, v[22:23]
	global_load_ushort v98, v[38:39], off offset:1024
	global_load_ushort v99, v[36:37], off offset:1024
	global_load_ushort v78, v[14:15], off offset:1920
	global_load_dword v71, v[20:21], off
	global_load_dword v70, v[22:23], off
	global_load_ushort v79, v[14:15], off offset:2560
	v_lshl_add_u64 v[20:21], v[14:15], 0, s[2:3]
	s_or_b32 s2, s26, 5
	s_ashr_i32 s3, s2, 31
	s_lshl_b64 s[2:3], s[2:3], 11
	s_add_u32 s2, s37, s2
	s_addc_u32 s3, s38, s3
	v_lshl_add_u64 v[32:33], s[2:3], 0, v[114:115]
	s_mov_b64 s[2:3], 0xc80
	v_lshl_add_u64 v[60:61], v[14:15], 0, s[2:3]
	s_or_b32 s2, s26, 6
	s_ashr_i32 s3, s2, 31
	s_lshl_b64 s[2:3], s[2:3], 11
	s_add_u32 s2, s37, s2
	s_addc_u32 s3, s38, s3
	v_lshl_add_u64 v[30:31], s[2:3], 0, v[114:115]
	s_or_b32 s2, s26, 7
	s_ashr_i32 s3, s2, 31
	s_lshl_b64 s[2:3], s[2:3], 11
	s_add_u32 s2, s37, s2
	s_addc_u32 s3, s38, s3
	v_lshl_add_u64 v[28:29], s[2:3], 0, v[114:115]
	s_or_b32 s2, s26, 8
	s_ashr_i32 s3, s2, 31
	s_lshl_b64 s[2:3], s[2:3], 11
	s_add_u32 s2, s37, s2
	s_addc_u32 s3, s38, s3
	v_lshl_add_u64 v[26:27], s[2:3], 0, v[114:115]
	s_or_b32 s2, s26, 9
	s_ashr_i32 s3, s2, 31
	s_lshl_b64 s[2:3], s[2:3], 11
	s_add_u32 s2, s37, s2
	s_addc_u32 s3, s38, s3
	v_lshl_add_u64 v[24:25], s[2:3], 0, v[114:115]
	s_or_b32 s2, s26, 10
	s_ashr_i32 s3, s2, 31
	s_mov_b64 s[4:5], 0xf00
	s_lshl_b64 s[2:3], s[2:3], 11
	global_load_ushort v100, v[34:35], off offset:1024
	global_load_ushort v101, v[32:33], off offset:1024
	global_load_ushort v80, v[14:15], off offset:3200
	global_load_ushort v81, v[14:15], off offset:3840
	v_or_b32_e32 v22, 0x50, v116
	v_mov_b32_e32 v23, v117
	v_lshl_add_u64 v[88:89], v[14:15], 0, s[4:5]
	v_or_b32_e32 v14, 0x60, v116
	v_mov_b32_e32 v15, v117
	s_add_u32 s2, s37, s2
	v_lshl_add_u64 v[22:23], s[28:29], 0, v[22:23]
	v_lshl_add_u64 v[14:15], s[28:29], 0, v[14:15]
	s_addc_u32 s3, s38, s3
	global_load_dword v69, v[22:23], off
	global_load_dword v68, v[14:15], off
	v_lshl_add_u64 v[22:23], s[2:3], 0, v[114:115]
	s_or_b32 s2, s26, 11
	global_load_ushort v102, v[30:31], off offset:1024
	global_load_ushort v103, v[28:29], off offset:1024
	v_lshl_add_u64 v[14:15], v[12:13], 0, s[4:5]
	global_load_ushort v82, v[12:13], off offset:3840
	v_or_b32_e32 v12, 0x70, v116
	v_mov_b32_e32 v13, v117
	s_ashr_i32 s3, s2, 31
	v_lshl_add_u64 v[12:13], s[28:29], 0, v[12:13]
	s_lshl_b64 s[2:3], s[2:3], 11
	global_load_dword v67, v[12:13], off
	v_lshl_add_u64 v[12:13], v[16:17], 0, s[4:5]
	global_load_ushort v83, v[16:17], off offset:3840
	v_or_b32_e32 v16, 0x80, v116
	v_mov_b32_e32 v17, v117
	s_add_u32 s2, s37, s2
	v_lshl_add_u64 v[16:17], s[28:29], 0, v[16:17]
	s_addc_u32 s3, s38, s3
	global_load_dword v66, v[16:17], off
; __device__ __forceinline__ float bf2f(unsigned short b) { return __uint_as_float(((unsigned)b) << 16); }
; __device__ __forceinline__ void rwkv_fin_item(const Params& p, int l, int item, char* ldsraw) {
;     ...
;     for (int t = 0; t < 16; t++) lds[1024 + t * 256 + tid] = gacc[t];
;   }
;   const float lw = p.ln_w[l * 256 + tid], lb = p.ln_b[l * 256 + tid];
;   float yv[16], vv[16], c3v[16];
;   const size_t base0 = (size_t)(b * 4 + h) * S + s0;
; #pragma unroll
;   for (int t = 0; t < 16; t++) { yv[t] = bf2f(Y[(size_t)(tok0 + t) * 1024 + 512 + tid]); vv[t] = bf2f(RB[(base0 + t) * 320 + 256 + jl]); c3v[t] = RC[(base0 + t) * 4 + 2]; }
;   if (s0 >= 2048) {
	global_load_ushort v105, v[26:27], off offset:1024
	global_load_ushort v106, v[24:25], off offset:1024
	global_load_ushort v85, v[20:21], off offset:3840
	v_lshl_add_u64 v[20:21], s[2:3], 0, v[114:115]
	s_or_b32 s2, s26, 12
	s_ashr_i32 s3, s2, 31
	v_or_b32_e32 v16, 0x90, v116
	v_mov_b32_e32 v17, v117
	s_lshl_b64 s[2:3], s[2:3], 11
	v_lshl_add_u64 v[16:17], s[28:29], 0, v[16:17]
	s_add_u32 s2, s37, s2
	global_load_dword v65, v[16:17], off
	v_or_b32_e32 v16, 0xa0, v116
	v_mov_b32_e32 v17, v117
	s_addc_u32 s3, s38, s3
	v_lshl_add_u64 v[118:119], v[18:19], 0, s[4:5]
	global_load_ushort v84, v[18:19], off offset:3840
	v_lshl_add_u64 v[16:17], s[28:29], 0, v[16:17]
	v_lshl_add_u64 v[18:19], s[2:3], 0, v[114:115]
	s_or_b32 s2, s26, 13
	global_load_dword v64, v[16:17], off
	v_or_b32_e32 v16, 0xb0, v116
	v_mov_b32_e32 v17, v117
	s_ashr_i32 s3, s2, 31
	v_lshl_add_u64 v[16:17], s[28:29], 0, v[16:17]
	s_lshl_b64 s[2:3], s[2:3], 11
	global_load_ushort v107, v[22:23], off offset:1024
	global_load_ushort v108, v[20:21], off offset:1024
	global_load_ushort v86, v[60:61], off offset:3840
	global_load_dword v63, v[16:17], off
	v_or_b32_e32 v16, 0xc0, v116
	v_mov_b32_e32 v17, v117
	s_add_u32 s2, s37, s2
	v_lshl_add_u64 v[16:17], s[28:29], 0, v[16:17]
	s_addc_u32 s3, s38, s3
	global_load_dword v62, v[16:17], off
	v_lshl_add_u64 v[16:17], s[2:3], 0, v[114:115]
	s_or_b32 s2, s26, 14
	s_ashr_i32 s3, s2, 31
	s_lshl_b64 s[2:3], s[2:3], 11
	global_load_ushort v87, v[88:89], off offset:3840
	global_load_ushort v109, v[18:19], off offset:1024
	global_load_ushort v110, v[16:17], off offset:1024
	s_nop 0
	global_load_ushort v88, v[14:15], off offset:3840
	v_or_b32_e32 v14, 0xd0, v116
	v_mov_b32_e32 v15, v117
	s_add_u32 s2, s37, s2
	global_load_ushort v89, v[12:13], off offset:3840
	v_or_b32_e32 v12, 0xe0, v116
	v_mov_b32_e32 v13, v117
	v_lshl_add_u64 v[14:15], s[28:29], 0, v[14:15]
	s_addc_u32 s3, s38, s3
	v_lshl_add_u64 v[12:13], s[28:29], 0, v[12:13]
	global_load_dword v61, v[14:15], off
	global_load_dword v60, v[12:13], off
	v_lshl_add_u64 v[14:15], s[2:3], 0, v[114:115]
	s_or_b32 s2, s26, 15
	s_ashr_i32 s3, s2, 31
	s_lshl_b64 s[2:3], s[2:3], 11
	s_add_u32 s2, s37, s2
	s_addc_u32 s3, s38, s3
	v_or_b32_e32 v116, 0xf0, v116
	v_lshl_add_u64 v[12:13], s[2:3], 0, v[114:115]
	v_lshl_add_u64 v[114:115], s[28:29], 0, v[116:117]
	global_load_ushort v104, v[14:15], off offset:1024
	global_load_ushort v111, v[12:13], off offset:1024
	global_load_ushort v90, v[118:119], off offset:3840
	global_load_dword v1, v[114:115], off
	s_waitcnt lgkmcnt(0)
	v_mul_f32_e32 v5, v46, v5
	ds_read_b128 v[114:117], v3 offset:2288
	v_fmac_f32_e32 v5, v44, v4
	v_fmac_f32_e32 v5, v45, v6
	v_fmac_f32_e32 v5, v47, v7
	v_add_f32_e32 v95, v95, v5
	ds_read_b128 v[4:7], v3 offset:2544
	v_add_f32_e32 v112, v112, v113
	s_waitcnt lgkmcnt(1)
	v_mul_f32_e32 v113, v46, v115
	v_fmac_f32_e32 v113, v44, v114
	v_fmac_f32_e32 v113, v45, v116
	v_fmac_f32_e32 v113, v47, v117
	ds_read_b128 v[114:117], v3 offset:2800
	s_waitcnt lgkmcnt(1)
	v_mul_f32_e32 v5, v46, v5
	v_fmac_f32_e32 v5, v44, v4
	v_fmac_f32_e32 v5, v45, v6
	v_fmac_f32_e32 v5, v47, v7
	v_add_f32_e32 v94, v94, v113
	v_add_f32_e32 v93, v93, v5
	ds_read_b128 v[4:7], v3 offset:3056
	s_waitcnt lgkmcnt(1)
	v_mul_f32_e32 v113, v46, v115
	v_fmac_f32_e32 v113, v44, v114
	v_fmac_f32_e32 v113, v45, v116
	v_fmac_f32_e32 v113, v47, v117
	ds_read_b128 v[116:119], v3 offset:3312
	ds_read_b128 v[120:123], v3 offset:3568
	s_waitcnt lgkmcnt(2)
	v_mul_f32_e32 v5, v46, v5
	v_fmac_f32_e32 v5, v44, v4
	v_fmac_f32_e32 v5, v45, v6
	s_waitcnt lgkmcnt(1)
	v_mul_f32_e32 v4, v46, v117
	v_fmac_f32_e32 v4, v44, v116
	v_fmac_f32_e32 v4, v45, v118
	v_fmac_f32_e32 v5, v47, v7
	v_fmac_f32_e32 v4, v47, v119
	v_add_f32_e32 v114, v10, v5
	v_add_f32_e32 v115, v9, v4
	s_waitcnt lgkmcnt(0)
	v_mul_f32_e32 v9, v46, v121
	ds_read_b128 v[4:7], v3 offset:3824
	v_fmac_f32_e32 v9, v44, v120
	v_fmac_f32_e32 v9, v45, v122
	v_fmac_f32_e32 v9, v47, v123
	v_add_f32_e32 v113, v11, v113
	v_add_f32_e32 v116, v8, v9
	ds_read_b128 v[8:11], v3 offset:4080
	s_waitcnt lgkmcnt(1)
	v_mul_f32_e32 v5, v46, v5
	v_fmac_f32_e32 v5, v44, v4
	v_fmac_f32_e32 v5, v45, v6
	v_fmac_f32_e32 v5, v47, v7
	v_add_f32_e32 v4, v50, v5
	s_waitcnt lgkmcnt(0)
	v_mul_f32_e32 v5, v46, v9
	v_fmac_f32_e32 v5, v44, v8
	v_fmac_f32_e32 v5, v45, v10
	v_fmac_f32_e32 v5, v47, v11
	v_add_f32_e32 v5, v51, v5
	ds_write2st64_b32 v56, v52, v53 offset0:16 offset1:20
	ds_write2st64_b32 v56, v54, v55 offset0:24 offset1:28
	ds_write2st64_b32 v56, v91, v92 offset0:32 offset1:36
	ds_write2st64_b32 v56, v112, v95 offset0:40 offset1:44
	ds_write2st64_b32 v56, v94, v93 offset0:48 offset1:52
	ds_write2st64_b32 v56, v113, v114 offset0:56 offset1:60
	ds_write2st64_b32 v56, v115, v116 offset0:64 offset1:68
	ds_write2st64_b32 v56, v4, v5 offset0:72 offset1:76
	s_waitcnt vmcnt(44)
	v_lshlrev_b32_e32 v53, 16, v97
	v_lshlrev_b32_e32 v52, 16, v96
	s_waitcnt vmcnt(38)
	v_lshlrev_b32_e32 v51, 16, v99
	v_lshlrev_b32_e32 v50, 16, v98
	s_waitcnt vmcnt(32)
	v_lshlrev_b32_e32 v47, 16, v101
	v_lshlrev_b32_e32 v46, 16, v100
	s_waitcnt vmcnt(26)
	v_lshlrev_b32_e32 v45, 16, v103
	v_lshlrev_b32_e32 v44, 16, v102
	s_waitcnt vmcnt(20)
	v_lshlrev_b32_e32 v11, 16, v106
	v_lshlrev_b32_e32 v10, 16, v105
	s_waitcnt vmcnt(14)
	v_lshlrev_b32_e32 v9, 16, v108
	v_lshlrev_b32_e32 v8, 16, v107
	s_waitcnt vmcnt(8)
	v_lshlrev_b32_e32 v7, 16, v110
	v_lshlrev_b32_e32 v6, 16, v109
	s_cmpk_lt_u32 s36, 0x800
	s_waitcnt vmcnt(3)
	v_lshlrev_b32_e32 v4, 16, v104
	s_waitcnt vmcnt(2)
	v_lshlrev_b32_e32 v5, 16, v111
	s_cbranch_scc1 .LBB0_139
; __device__ __forceinline__ unsigned char* WS(const Params& p) { unsigned z = 0; asm volatile("" : "+s"(z)); return p.ws + z; }
; __device__ __forceinline__ float bf2f(unsigned short b) { return __uint_as_float(((unsigned)b) << 16); }
; __device__ __forceinline__ void rwkv_fin_item(const Params& p, int l, int item, char* ldsraw) {
;     ...
;   if (s0 >= 2048) {
;     float* zl = lds + 5120;
;     const bf16_t* Z = (const bf16_t*)(WS(p) + OFF_Z);
; #pragma unroll
;     for (int t = 0; t < 16; t++) zl[t * 256 + tid] = bf2f(Z[((size_t)(b * 4 + h) * 2048 + (s0 - 2048 + t)) * 64 + jl]);
;     const float* sf = (const float*)(WS(p) + OFF_SF) + ((size_t)(b * 4 + h) * 64 + jl) * 64;
;     __syncthreads();
; #pragma unroll 1
;     for (int mq = 0; mq < 16; mq++) {
;       const f32x4 sv = *(const f32x4*)(sf + mq * 4);
	s_mov_b32 s3, 0
	s_add_u32 s26, s46, s3
	s_addc_u32 s27, s47, 0
	v_lshlrev_b64 v[54:55], 18, v[48:49]
	v_lshl_add_u64 v[54:55], s[26:27], 0, v[54:55]
	s_add_i32 s88, s36, 0xfffff800
	v_lshl_add_u64 v[54:55], v[54:55], 0, v[2:3]
	s_mov_b64 s[4:5], 0xfb4c000
	v_lshl_add_u64 v[54:55], v[54:55], 0, s[4:5]
	s_lshl_b64 s[26:27], s[88:89], 7
	s_add_i32 s88, s36, 0xfffff801
	v_lshl_add_u64 v[92:93], v[54:55], 0, s[26:27]
	s_lshl_b64 s[26:27], s[88:89], 7
	global_load_ushort v2, v[92:93], off
	v_lshl_add_u64 v[92:93], v[54:55], 0, s[26:27]
	global_load_ushort v91, v[92:93], off
	s_add_i32 s88, s36, 0xfffff802
	s_lshl_b64 s[26:27], s[88:89], 7
	s_add_i32 s88, s36, 0xfffff803
	v_lshl_add_u64 v[92:93], v[54:55], 0, s[26:27]
	s_lshl_b64 s[26:27], s[88:89], 7
	s_add_i32 s88, s36, 0xfffff804
	s_mov_b32 s3, 0
	v_lshlrev_b64 v[48:49], 14, v[48:49]
	v_lshlrev_b32_e32 v0, 2, v0
	s_mov_b64 s[4:5], 0xff4c000
	v_and_b32_e32 v0, 0xffffff00, v0
	s_mov_b32 s2, 0
	s_waitcnt vmcnt(1)
	v_lshlrev_b32_e32 v2, 16, v2
	s_waitcnt vmcnt(0)
	v_lshlrev_b32_e32 v91, 16, v91
	ds_write2st64_b32 v56, v2, v91 offset0:80 offset1:84
	global_load_ushort v2, v[92:93], off
	v_lshl_add_u64 v[92:93], v[54:55], 0, s[26:27]
	global_load_ushort v91, v[92:93], off
	s_lshl_b64 s[26:27], s[88:89], 7
	s_add_i32 s88, s36, 0xfffff805
	v_lshl_add_u64 v[92:93], v[54:55], 0, s[26:27]
	s_lshl_b64 s[26:27], s[88:89], 7
	s_add_i32 s88, s36, 0xfffff806
	s_waitcnt vmcnt(1)
	v_lshlrev_b32_e32 v2, 16, v2
	s_waitcnt vmcnt(0)
	v_lshlrev_b32_e32 v91, 16, v91
	ds_write2st64_b32 v56, v2, v91 offset0:88 offset1:92
	global_load_ushort v2, v[92:93], off
	v_lshl_add_u64 v[92:93], v[54:55], 0, s[26:27]
	global_load_ushort v91, v[92:93], off
	s_lshl_b64 s[26:27], s[88:89], 7
	s_add_i32 s88, s36, 0xfffff807
	v_lshl_add_u64 v[92:93], v[54:55], 0, s[26:27]
	s_lshl_b64 s[26:27], s[88:89], 7
	s_add_i32 s88, s36, 0xfffff808
	s_waitcnt vmcnt(1)
	v_lshlrev_b32_e32 v2, 16, v2
	s_waitcnt vmcnt(0)
	v_lshlrev_b32_e32 v91, 16, v91
	ds_write2st64_b32 v56, v2, v91 offset0:96 offset1:100
	global_load_ushort v2, v[92:93], off
	v_lshl_add_u64 v[92:93], v[54:55], 0, s[26:27]
	global_load_ushort v91, v[92:93], off
	s_lshl_b64 s[26:27], s[88:89], 7
	s_add_i32 s88, s36, 0xfffff809
	v_lshl_add_u64 v[92:93], v[54:55], 0, s[26:27]
	s_lshl_b64 s[26:27], s[88:89], 7
	s_add_i32 s88, s36, 0xfffff80a
	s_waitcnt vmcnt(1)
	v_lshlrev_b32_e32 v2, 16, v2
	s_waitcnt vmcnt(0)
	v_lshlrev_b32_e32 v91, 16, v91
	ds_write2st64_b32 v56, v2, v91 offset0:104 offset1:108
	global_load_ushort v2, v[92:93], off
	v_lshl_add_u64 v[92:93], v[54:55], 0, s[26:27]
	global_load_ushort v91, v[92:93], off
	s_lshl_b64 s[26:27], s[88:89], 7
	s_add_i32 s88, s36, 0xfffff80b
	v_lshl_add_u64 v[92:93], v[54:55], 0, s[26:27]
	s_lshl_b64 s[26:27], s[88:89], 7
	s_add_i32 s88, s36, 0xfffff80c
	s_waitcnt vmcnt(1)
	v_lshlrev_b32_e32 v2, 16, v2
	s_waitcnt vmcnt(0)
	v_lshlrev_b32_e32 v91, 16, v91
	ds_write2st64_b32 v56, v2, v91 offset0:112 offset1:116
	global_load_ushort v2, v[92:93], off
	v_lshl_add_u64 v[92:93], v[54:55], 0, s[26:27]
	global_load_ushort v91, v[92:93], off
	s_lshl_b64 s[26:27], s[88:89], 7
	s_add_i32 s88, s36, 0xfffff80d
	v_lshl_add_u64 v[92:93], v[54:55], 0, s[26:27]
	s_lshl_b64 s[26:27], s[88:89], 7
	s_add_i32 s88, s36, 0xfffff80e
	s_waitcnt vmcnt(1)
	v_lshlrev_b32_e32 v2, 16, v2
	s_waitcnt vmcnt(0)
	v_lshlrev_b32_e32 v91, 16, v91
	ds_write2st64_b32 v56, v2, v91 offset0:120 offset1:124
	global_load_ushort v2, v[92:93], off
	v_lshl_add_u64 v[92:93], v[54:55], 0, s[26:27]
	global_load_ushort v91, v[92:93], off
	s_lshl_b64 s[26:27], s[88:89], 7
	s_add_i32 s88, s36, 0xfffff80f
	v_lshl_add_u64 v[92:93], v[54:55], 0, s[26:27]
	s_lshl_b64 s[26:27], s[88:89], 7
	v_lshl_add_u64 v[54:55], v[54:55], 0, s[26:27]
	global_load_ushort v54, v[54:55], off
	s_waitcnt vmcnt(2)
	v_lshlrev_b32_e32 v2, 16, v2
	s_waitcnt vmcnt(1)
	v_lshlrev_b32_e32 v91, 16, v91
	ds_write2st64_b32 v56, v2, v91 offset0:128 offset1:132
	global_load_ushort v2, v[92:93], off
	s_waitcnt vmcnt(1)
	v_lshlrev_b32_e32 v54, 16, v54
	s_waitcnt vmcnt(0)
	v_lshlrev_b32_e32 v2, 16, v2
	ds_write2st64_b32 v56, v2, v54 offset0:136 offset1:140
	s_add_u32 s26, s46, s3
	s_addc_u32 s27, s47, 0
	v_lshl_add_u64 v[48:49], s[26:27], 0, v[48:49]
	v_lshlrev_b32_e32 v2, 8, v57
	v_lshl_add_u64 v[48:49], v[48:49], 0, v[2:3]
	s_add_i32 s3, 0, 0x5000
	v_lshl_add_u64 v[48:49], v[48:49], 0, s[4:5]
	global_load_dwordx4 v[124:127], v[48:49], off
	global_load_dwordx4 v[128:131], v[48:49], off offset:16
	global_load_dwordx4 v[132:135], v[48:49], off offset:32
	global_load_dwordx4 v[136:139], v[48:49], off offset:48
	global_load_dwordx4 v[140:143], v[48:49], off offset:64
	global_load_dwordx4 v[144:147], v[48:49], off offset:80
	global_load_dwordx4 v[148:151], v[48:49], off offset:96
	global_load_dwordx4 v[152:155], v[48:49], off offset:112
	global_load_dwordx4 v[156:159], v[48:49], off offset:128
	global_load_dwordx4 v[160:163], v[48:49], off offset:144
	global_load_dwordx4 v[164:167], v[48:49], off offset:160
	global_load_dwordx4 v[168:171], v[48:49], off offset:176
	global_load_dwordx4 v[172:175], v[48:49], off offset:192
	global_load_dwordx4 v[176:179], v[48:49], off offset:208
	global_load_dwordx4 v[180:183], v[48:49], off offset:224
	global_load_dwordx4 v[184:187], v[48:49], off offset:240
	v_add_u32_e32 v0, s3, v0
	s_waitcnt lgkmcnt(0)
	s_barrier
; __device__ __forceinline__ void rwkv_fin_item(const Params& p, int l, int item, char* ldsraw) {
;     ...
;     for (int mq = 0; mq < 16; mq++) {
;       const f32x4 sv = *(const f32x4*)(sf + mq * 4);
; #pragma unroll
;       for (int t = 0; t < 16; t++) {
;         const f32x4 zv = *(const f32x4*)(zl + t * 256 + h * 64 + mq * 4);
;         yv[t] += sv[0] * zv[0] + sv[1] * zv[1] + sv[2] * zv[2] + sv[3] * zv[3];
;       }
.LBB0_150:
	v_add_u32_e32 v57, s2, v0
	s_waitcnt vmcnt(15)
	ds_read_b128 v[96:99], v57
	ds_read_b128 v[100:103], v57 offset:1024
	s_waitcnt lgkmcnt(0)
	v_pk_mov_b32 v[54:55], v[96:97], v[100:101] op_sel:[1,0]
	v_mov_b32_e32 v97, v101
	v_pk_mul_f32 v[96:97], v[124:125], v[96:97]
	s_nop 0
	v_pk_fma_f32 v[54:55], v[124:125], v[54:55], v[96:97] op_sel:[1,0,0] op_sel_hi:[0,1,1]
	v_mov_b32_e32 v96, v98
	v_mov_b32_e32 v97, v102
	v_pk_fma_f32 v[54:55], v[126:127], v[96:97], v[54:55] op_sel_hi:[0,1,1]
	v_mov_b32_e32 v2, v127
	v_mov_b32_e32 v102, v99
	v_pk_fma_f32 v[54:55], v[2:3], v[102:103], v[54:55] op_sel_hi:[0,1,1]
	ds_read_b128 v[96:99], v57 offset:2048
	ds_read_b128 v[100:103], v57 offset:3072
	v_pk_add_f32 v[52:53], v[52:53], v[54:55]
	s_waitcnt lgkmcnt(0)
	v_pk_mov_b32 v[54:55], v[96:97], v[100:101] op_sel:[1,0]
	v_mov_b32_e32 v97, v101
	v_pk_mul_f32 v[96:97], v[124:125], v[96:97]
	s_nop 0
	v_pk_fma_f32 v[54:55], v[124:125], v[54:55], v[96:97] op_sel:[1,0,0] op_sel_hi:[0,1,1]
	v_mov_b32_e32 v96, v98
	v_mov_b32_e32 v97, v102
	v_pk_fma_f32 v[54:55], v[126:127], v[96:97], v[54:55] op_sel_hi:[0,1,1]
	v_mov_b32_e32 v102, v99
	v_pk_fma_f32 v[54:55], v[2:3], v[102:103], v[54:55] op_sel_hi:[0,1,1]
	ds_read_b128 v[96:99], v57 offset:4096
	ds_read_b128 v[100:103], v57 offset:5120
	v_pk_add_f32 v[50:51], v[50:51], v[54:55]
	s_waitcnt lgkmcnt(0)
	v_pk_mov_b32 v[54:55], v[96:97], v[100:101] op_sel:[1,0]
	v_mov_b32_e32 v97, v101
	v_pk_mul_f32 v[96:97], v[124:125], v[96:97]
	s_nop 0
	v_pk_fma_f32 v[54:55], v[124:125], v[54:55], v[96:97] op_sel:[1,0,0] op_sel_hi:[0,1,1]
	v_mov_b32_e32 v96, v98
	v_mov_b32_e32 v97, v102
	v_pk_fma_f32 v[54:55], v[126:127], v[96:97], v[54:55] op_sel_hi:[0,1,1]
	v_mov_b32_e32 v102, v99
	v_pk_fma_f32 v[54:55], v[2:3], v[102:103], v[54:55] op_sel_hi:[0,1,1]
	ds_read_b128 v[96:99], v57 offset:6144
	ds_read_b128 v[100:103], v57 offset:7168
	v_pk_add_f32 v[46:47], v[46:47], v[54:55]
	s_waitcnt lgkmcnt(0)
	v_pk_mov_b32 v[54:55], v[96:97], v[100:101] op_sel:[1,0]
	v_mov_b32_e32 v97, v101
	v_pk_mul_f32 v[96:97], v[124:125], v[96:97]
	s_nop 0
	v_pk_fma_f32 v[54:55], v[124:125], v[54:55], v[96:97] op_sel:[1,0,0] op_sel_hi:[0,1,1]
	v_mov_b32_e32 v96, v98
	v_mov_b32_e32 v97, v102
	v_pk_fma_f32 v[54:55], v[126:127], v[96:97], v[54:55] op_sel_hi:[0,1,1]
	v_mov_b32_e32 v102, v99
	v_pk_fma_f32 v[54:55], v[2:3], v[102:103], v[54:55] op_sel_hi:[0,1,1]
	ds_read_b128 v[96:99], v57 offset:8192
	ds_read_b128 v[100:103], v57 offset:9216
	v_pk_add_f32 v[44:45], v[44:45], v[54:55]
	s_waitcnt lgkmcnt(0)
	v_pk_mov_b32 v[54:55], v[96:97], v[100:101] op_sel:[1,0]
	v_mov_b32_e32 v97, v101
	v_pk_mul_f32 v[96:97], v[124:125], v[96:97]
	s_nop 0
	v_pk_fma_f32 v[54:55], v[124:125], v[54:55], v[96:97] op_sel:[1,0,0] op_sel_hi:[0,1,1]
	v_mov_b32_e32 v96, v98
	v_mov_b32_e32 v97, v102
	v_pk_fma_f32 v[54:55], v[126:127], v[96:97], v[54:55] op_sel_hi:[0,1,1]
	v_mov_b32_e32 v102, v99
	v_pk_fma_f32 v[54:55], v[2:3], v[102:103], v[54:55] op_sel_hi:[0,1,1]
	ds_read_b128 v[96:99], v57 offset:10240
	ds_read_b128 v[100:103], v57 offset:11264
	v_pk_add_f32 v[10:11], v[10:11], v[54:55]
	s_waitcnt lgkmcnt(0)
	v_pk_mov_b32 v[54:55], v[96:97], v[100:101] op_sel:[1,0]
	v_mov_b32_e32 v97, v101
	v_pk_mul_f32 v[96:97], v[124:125], v[96:97]
	s_nop 0
	v_pk_fma_f32 v[54:55], v[124:125], v[54:55], v[96:97] op_sel:[1,0,0] op_sel_hi:[0,1,1]
	v_mov_b32_e32 v96, v98
	v_mov_b32_e32 v97, v102
	v_pk_fma_f32 v[54:55], v[126:127], v[96:97], v[54:55] op_sel_hi:[0,1,1]
	v_mov_b32_e32 v102, v99
	v_pk_fma_f32 v[54:55], v[2:3], v[102:103], v[54:55] op_sel_hi:[0,1,1]
	ds_read_b128 v[96:99], v57 offset:12288
	ds_read_b128 v[100:103], v57 offset:13312
	v_pk_add_f32 v[8:9], v[8:9], v[54:55]
	s_waitcnt lgkmcnt(0)
	v_pk_mov_b32 v[54:55], v[96:97], v[100:101] op_sel:[1,0]
	v_mov_b32_e32 v97, v101
	v_pk_mul_f32 v[96:97], v[124:125], v[96:97]
	s_nop 0
	v_pk_fma_f32 v[54:55], v[124:125], v[54:55], v[96:97] op_sel:[1,0,0] op_sel_hi:[0,1,1]
	v_mov_b32_e32 v96, v98
	v_mov_b32_e32 v97, v102
	v_pk_fma_f32 v[54:55], v[126:127], v[96:97], v[54:55] op_sel_hi:[0,1,1]
	v_mov_b32_e32 v102, v99
	v_pk_fma_f32 v[54:55], v[2:3], v[102:103], v[54:55] op_sel_hi:[0,1,1]
	ds_read_b128 v[96:99], v57 offset:14336
	ds_read_b128 v[100:103], v57 offset:15360
	v_pk_add_f32 v[6:7], v[6:7], v[54:55]
	s_waitcnt lgkmcnt(0)
	v_pk_mov_b32 v[54:55], v[96:97], v[100:101] op_sel:[1,0]
	v_mov_b32_e32 v97, v101
	v_pk_mul_f32 v[96:97], v[124:125], v[96:97]
	s_nop 0
	v_pk_fma_f32 v[54:55], v[124:125], v[54:55], v[96:97] op_sel:[1,0,0] op_sel_hi:[0,1,1]
	v_mov_b32_e32 v96, v98
	v_mov_b32_e32 v97, v102
	v_pk_fma_f32 v[54:55], v[126:127], v[96:97], v[54:55] op_sel_hi:[0,1,1]
	v_mov_b32_e32 v102, v99
	v_pk_fma_f32 v[54:55], v[2:3], v[102:103], v[54:55] op_sel_hi:[0,1,1]
	v_pk_add_f32 v[4:5], v[4:5], v[54:55]
	s_waitcnt vmcnt(14)
	ds_read_b128 v[96:99], v57 offset:16
	ds_read_b128 v[100:103], v57 offset:1040
	s_waitcnt lgkmcnt(0)
	v_pk_mov_b32 v[54:55], v[96:97], v[100:101] op_sel:[1,0]
	v_mov_b32_e32 v97, v101
	v_pk_mul_f32 v[96:97], v[128:129], v[96:97]
	s_nop 0
	v_pk_fma_f32 v[54:55], v[128:129], v[54:55], v[96:97] op_sel:[1,0,0] op_sel_hi:[0,1,1]
	v_mov_b32_e32 v96, v98
	v_mov_b32_e32 v97, v102
	v_pk_fma_f32 v[54:55], v[130:131], v[96:97], v[54:55] op_sel_hi:[0,1,1]
	v_mov_b32_e32 v2, v131
	v_mov_b32_e32 v102, v99
	v_pk_fma_f32 v[54:55], v[2:3], v[102:103], v[54:55] op_sel_hi:[0,1,1]
	ds_read_b128 v[96:99], v57 offset:2064
	ds_read_b128 v[100:103], v57 offset:3088
	v_pk_add_f32 v[52:53], v[52:53], v[54:55]
	s_waitcnt lgkmcnt(0)
; __device__ __forceinline__ void rwkv_fin_item(const Params& p, int l, int item, char* ldsraw) {
;     ...
;     for (int mq = 0; mq < 16; mq++) {
;       const f32x4 sv = *(const f32x4*)(sf + mq * 4);
; #pragma unroll
;       for (int t = 0; t < 16; t++) {
;         const f32x4 zv = *(const f32x4*)(zl + t * 256 + h * 64 + mq * 4);
;         yv[t] += sv[0] * zv[0] + sv[1] * zv[1] + sv[2] * zv[2] + sv[3] * zv[3];
;       }
	v_pk_mov_b32 v[54:55], v[96:97], v[100:101] op_sel:[1,0]
	v_mov_b32_e32 v97, v101
	v_pk_mul_f32 v[96:97], v[128:129], v[96:97]
	s_nop 0
	v_pk_fma_f32 v[54:55], v[128:129], v[54:55], v[96:97] op_sel:[1,0,0] op_sel_hi:[0,1,1]
	v_mov_b32_e32 v96, v98
	v_mov_b32_e32 v97, v102
	v_pk_fma_f32 v[54:55], v[130:131], v[96:97], v[54:55] op_sel_hi:[0,1,1]
	v_mov_b32_e32 v102, v99
	v_pk_fma_f32 v[54:55], v[2:3], v[102:103], v[54:55] op_sel_hi:[0,1,1]
	ds_read_b128 v[96:99], v57 offset:4112
	ds_read_b128 v[100:103], v57 offset:5136
	v_pk_add_f32 v[50:51], v[50:51], v[54:55]
	s_waitcnt lgkmcnt(0)
	v_pk_mov_b32 v[54:55], v[96:97], v[100:101] op_sel:[1,0]
	v_mov_b32_e32 v97, v101
	v_pk_mul_f32 v[96:97], v[128:129], v[96:97]
	s_nop 0
	v_pk_fma_f32 v[54:55], v[128:129], v[54:55], v[96:97] op_sel:[1,0,0] op_sel_hi:[0,1,1]
	v_mov_b32_e32 v96, v98
	v_mov_b32_e32 v97, v102
	v_pk_fma_f32 v[54:55], v[130:131], v[96:97], v[54:55] op_sel_hi:[0,1,1]
	v_mov_b32_e32 v102, v99
	v_pk_fma_f32 v[54:55], v[2:3], v[102:103], v[54:55] op_sel_hi:[0,1,1]
	ds_read_b128 v[96:99], v57 offset:6160
	ds_read_b128 v[100:103], v57 offset:7184
	v_pk_add_f32 v[46:47], v[46:47], v[54:55]
	s_waitcnt lgkmcnt(0)
	v_pk_mov_b32 v[54:55], v[96:97], v[100:101] op_sel:[1,0]
	v_mov_b32_e32 v97, v101
	v_pk_mul_f32 v[96:97], v[128:129], v[96:97]
	s_nop 0
	v_pk_fma_f32 v[54:55], v[128:129], v[54:55], v[96:97] op_sel:[1,0,0] op_sel_hi:[0,1,1]
	v_mov_b32_e32 v96, v98
	v_mov_b32_e32 v97, v102
	v_pk_fma_f32 v[54:55], v[130:131], v[96:97], v[54:55] op_sel_hi:[0,1,1]
	v_mov_b32_e32 v102, v99
	v_pk_fma_f32 v[54:55], v[2:3], v[102:103], v[54:55] op_sel_hi:[0,1,1]
	ds_read_b128 v[96:99], v57 offset:8208
	ds_read_b128 v[100:103], v57 offset:9232
	v_pk_add_f32 v[44:45], v[44:45], v[54:55]
	s_waitcnt lgkmcnt(0)
	v_pk_mov_b32 v[54:55], v[96:97], v[100:101] op_sel:[1,0]
	v_mov_b32_e32 v97, v101
	v_pk_mul_f32 v[96:97], v[128:129], v[96:97]
	s_nop 0
	v_pk_fma_f32 v[54:55], v[128:129], v[54:55], v[96:97] op_sel:[1,0,0] op_sel_hi:[0,1,1]
	v_mov_b32_e32 v96, v98
	v_mov_b32_e32 v97, v102
	v_pk_fma_f32 v[54:55], v[130:131], v[96:97], v[54:55] op_sel_hi:[0,1,1]
	v_mov_b32_e32 v102, v99
	v_pk_fma_f32 v[54:55], v[2:3], v[102:103], v[54:55] op_sel_hi:[0,1,1]
	ds_read_b128 v[96:99], v57 offset:10256
	ds_read_b128 v[100:103], v57 offset:11280
	v_pk_add_f32 v[10:11], v[10:11], v[54:55]
	s_waitcnt lgkmcnt(0)
	v_pk_mov_b32 v[54:55], v[96:97], v[100:101] op_sel:[1,0]
	v_mov_b32_e32 v97, v101
	v_pk_mul_f32 v[96:97], v[128:129], v[96:97]
	s_nop 0
	v_pk_fma_f32 v[54:55], v[128:129], v[54:55], v[96:97] op_sel:[1,0,0] op_sel_hi:[0,1,1]
	v_mov_b32_e32 v96, v98
	v_mov_b32_e32 v97, v102
	v_pk_fma_f32 v[54:55], v[130:131], v[96:97], v[54:55] op_sel_hi:[0,1,1]
	v_mov_b32_e32 v102, v99
	v_pk_fma_f32 v[54:55], v[2:3], v[102:103], v[54:55] op_sel_hi:[0,1,1]
	ds_read_b128 v[96:99], v57 offset:12304
	ds_read_b128 v[100:103], v57 offset:13328
	v_pk_add_f32 v[8:9], v[8:9], v[54:55]
	s_waitcnt lgkmcnt(0)
	v_pk_mov_b32 v[54:55], v[96:97], v[100:101] op_sel:[1,0]
	v_mov_b32_e32 v97, v101
	v_pk_mul_f32 v[96:97], v[128:129], v[96:97]
	s_nop 0
	v_pk_fma_f32 v[54:55], v[128:129], v[54:55], v[96:97] op_sel:[1,0,0] op_sel_hi:[0,1,1]
	v_mov_b32_e32 v96, v98
	v_mov_b32_e32 v97, v102
	v_pk_fma_f32 v[54:55], v[130:131], v[96:97], v[54:55] op_sel_hi:[0,1,1]
	v_mov_b32_e32 v102, v99
	v_pk_fma_f32 v[54:55], v[2:3], v[102:103], v[54:55] op_sel_hi:[0,1,1]
	ds_read_b128 v[96:99], v57 offset:14352
	ds_read_b128 v[100:103], v57 offset:15376
	v_pk_add_f32 v[6:7], v[6:7], v[54:55]
	s_waitcnt lgkmcnt(0)
	v_pk_mov_b32 v[54:55], v[96:97], v[100:101] op_sel:[1,0]
	v_mov_b32_e32 v97, v101
	v_pk_mul_f32 v[96:97], v[128:129], v[96:97]
	s_nop 0
	v_pk_fma_f32 v[54:55], v[128:129], v[54:55], v[96:97] op_sel:[1,0,0] op_sel_hi:[0,1,1]
	v_mov_b32_e32 v96, v98
	v_mov_b32_e32 v97, v102
	v_pk_fma_f32 v[54:55], v[130:131], v[96:97], v[54:55] op_sel_hi:[0,1,1]
	v_mov_b32_e32 v102, v99
	v_pk_fma_f32 v[54:55], v[2:3], v[102:103], v[54:55] op_sel_hi:[0,1,1]
	v_pk_add_f32 v[4:5], v[4:5], v[54:55]
	s_waitcnt vmcnt(13)
	ds_read_b128 v[96:99], v57 offset:32
	ds_read_b128 v[100:103], v57 offset:1056
	s_waitcnt lgkmcnt(0)
	v_pk_mov_b32 v[54:55], v[96:97], v[100:101] op_sel:[1,0]
	v_mov_b32_e32 v97, v101
	v_pk_mul_f32 v[96:97], v[132:133], v[96:97]
	s_nop 0
	v_pk_fma_f32 v[54:55], v[132:133], v[54:55], v[96:97] op_sel:[1,0,0] op_sel_hi:[0,1,1]
	v_mov_b32_e32 v96, v98
	v_mov_b32_e32 v97, v102
	v_pk_fma_f32 v[54:55], v[134:135], v[96:97], v[54:55] op_sel_hi:[0,1,1]
	v_mov_b32_e32 v2, v135
	v_mov_b32_e32 v102, v99
	v_pk_fma_f32 v[54:55], v[2:3], v[102:103], v[54:55] op_sel_hi:[0,1,1]
	ds_read_b128 v[96:99], v57 offset:2080
	ds_read_b128 v[100:103], v57 offset:3104
	v_pk_add_f32 v[52:53], v[52:53], v[54:55]
	s_waitcnt lgkmcnt(0)
	v_pk_mov_b32 v[54:55], v[96:97], v[100:101] op_sel:[1,0]
	v_mov_b32_e32 v97, v101
	v_pk_mul_f32 v[96:97], v[132:133], v[96:97]
	s_nop 0
	v_pk_fma_f32 v[54:55], v[132:133], v[54:55], v[96:97] op_sel:[1,0,0] op_sel_hi:[0,1,1]
	v_mov_b32_e32 v96, v98
	v_mov_b32_e32 v97, v102
	v_pk_fma_f32 v[54:55], v[134:135], v[96:97], v[54:55] op_sel_hi:[0,1,1]
	v_mov_b32_e32 v102, v99
	v_pk_fma_f32 v[54:55], v[2:3], v[102:103], v[54:55] op_sel_hi:[0,1,1]
	ds_read_b128 v[96:99], v57 offset:4128
	ds_read_b128 v[100:103], v57 offset:5152
	v_pk_add_f32 v[50:51], v[50:51], v[54:55]
	s_waitcnt lgkmcnt(0)
; __device__ __forceinline__ void rwkv_fin_item(const Params& p, int l, int item, char* ldsraw) {
;     ...
;     for (int mq = 0; mq < 16; mq++) {
;       const f32x4 sv = *(const f32x4*)(sf + mq * 4);
; #pragma unroll
;       for (int t = 0; t < 16; t++) {
;         const f32x4 zv = *(const f32x4*)(zl + t * 256 + h * 64 + mq * 4);
;         yv[t] += sv[0] * zv[0] + sv[1] * zv[1] + sv[2] * zv[2] + sv[3] * zv[3];
;       }
	v_pk_mov_b32 v[54:55], v[96:97], v[100:101] op_sel:[1,0]
	v_mov_b32_e32 v97, v101
	v_pk_mul_f32 v[96:97], v[132:133], v[96:97]
	s_nop 0
	v_pk_fma_f32 v[54:55], v[132:133], v[54:55], v[96:97] op_sel:[1,0,0] op_sel_hi:[0,1,1]
	v_mov_b32_e32 v96, v98
	v_mov_b32_e32 v97, v102
	v_pk_fma_f32 v[54:55], v[134:135], v[96:97], v[54:55] op_sel_hi:[0,1,1]
	v_mov_b32_e32 v102, v99
	v_pk_fma_f32 v[54:55], v[2:3], v[102:103], v[54:55] op_sel_hi:[0,1,1]
	ds_read_b128 v[96:99], v57 offset:6176
	ds_read_b128 v[100:103], v57 offset:7200
	v_pk_add_f32 v[46:47], v[46:47], v[54:55]
	s_waitcnt lgkmcnt(0)
	v_pk_mov_b32 v[54:55], v[96:97], v[100:101] op_sel:[1,0]
	v_mov_b32_e32 v97, v101
	v_pk_mul_f32 v[96:97], v[132:133], v[96:97]
	s_nop 0
	v_pk_fma_f32 v[54:55], v[132:133], v[54:55], v[96:97] op_sel:[1,0,0] op_sel_hi:[0,1,1]
	v_mov_b32_e32 v96, v98
	v_mov_b32_e32 v97, v102
	v_pk_fma_f32 v[54:55], v[134:135], v[96:97], v[54:55] op_sel_hi:[0,1,1]
	v_mov_b32_e32 v102, v99
	v_pk_fma_f32 v[54:55], v[2:3], v[102:103], v[54:55] op_sel_hi:[0,1,1]
	ds_read_b128 v[96:99], v57 offset:8224
	ds_read_b128 v[100:103], v57 offset:9248
	v_pk_add_f32 v[44:45], v[44:45], v[54:55]
	s_waitcnt lgkmcnt(0)
	v_pk_mov_b32 v[54:55], v[96:97], v[100:101] op_sel:[1,0]
	v_mov_b32_e32 v97, v101
	v_pk_mul_f32 v[96:97], v[132:133], v[96:97]
	s_nop 0
	v_pk_fma_f32 v[54:55], v[132:133], v[54:55], v[96:97] op_sel:[1,0,0] op_sel_hi:[0,1,1]
	v_mov_b32_e32 v96, v98
	v_mov_b32_e32 v97, v102
	v_pk_fma_f32 v[54:55], v[134:135], v[96:97], v[54:55] op_sel_hi:[0,1,1]
	v_mov_b32_e32 v102, v99
	v_pk_fma_f32 v[54:55], v[2:3], v[102:103], v[54:55] op_sel_hi:[0,1,1]
	ds_read_b128 v[96:99], v57 offset:10272
	ds_read_b128 v[100:103], v57 offset:11296
	v_pk_add_f32 v[10:11], v[10:11], v[54:55]
	s_waitcnt lgkmcnt(0)
	v_pk_mov_b32 v[54:55], v[96:97], v[100:101] op_sel:[1,0]
	v_mov_b32_e32 v97, v101
	v_pk_mul_f32 v[96:97], v[132:133], v[96:97]
	s_nop 0
	v_pk_fma_f32 v[54:55], v[132:133], v[54:55], v[96:97] op_sel:[1,0,0] op_sel_hi:[0,1,1]
	v_mov_b32_e32 v96, v98
	v_mov_b32_e32 v97, v102
	v_pk_fma_f32 v[54:55], v[134:135], v[96:97], v[54:55] op_sel_hi:[0,1,1]
	v_mov_b32_e32 v102, v99
	v_pk_fma_f32 v[54:55], v[2:3], v[102:103], v[54:55] op_sel_hi:[0,1,1]
	ds_read_b128 v[96:99], v57 offset:12320
	ds_read_b128 v[100:103], v57 offset:13344
	v_pk_add_f32 v[8:9], v[8:9], v[54:55]
	s_waitcnt lgkmcnt(0)
	v_pk_mov_b32 v[54:55], v[96:97], v[100:101] op_sel:[1,0]
	v_mov_b32_e32 v97, v101
	v_pk_mul_f32 v[96:97], v[132:133], v[96:97]
	s_nop 0
	v_pk_fma_f32 v[54:55], v[132:133], v[54:55], v[96:97] op_sel:[1,0,0] op_sel_hi:[0,1,1]
	v_mov_b32_e32 v96, v98
	v_mov_b32_e32 v97, v102
	v_pk_fma_f32 v[54:55], v[134:135], v[96:97], v[54:55] op_sel_hi:[0,1,1]
	v_mov_b32_e32 v102, v99
	v_pk_fma_f32 v[54:55], v[2:3], v[102:103], v[54:55] op_sel_hi:[0,1,1]
	ds_read_b128 v[96:99], v57 offset:14368
	ds_read_b128 v[100:103], v57 offset:15392
	v_pk_add_f32 v[6:7], v[6:7], v[54:55]
	s_waitcnt lgkmcnt(0)
	v_pk_mov_b32 v[54:55], v[96:97], v[100:101] op_sel:[1,0]
	v_mov_b32_e32 v97, v101
	v_pk_mul_f32 v[96:97], v[132:133], v[96:97]
	s_nop 0
	v_pk_fma_f32 v[54:55], v[132:133], v[54:55], v[96:97] op_sel:[1,0,0] op_sel_hi:[0,1,1]
	v_mov_b32_e32 v96, v98
	v_mov_b32_e32 v97, v102
	v_pk_fma_f32 v[54:55], v[134:135], v[96:97], v[54:55] op_sel_hi:[0,1,1]
	v_mov_b32_e32 v102, v99
	v_pk_fma_f32 v[54:55], v[2:3], v[102:103], v[54:55] op_sel_hi:[0,1,1]
	v_pk_add_f32 v[4:5], v[4:5], v[54:55]
	s_waitcnt vmcnt(12)
	ds_read_b128 v[96:99], v57 offset:48
	ds_read_b128 v[100:103], v57 offset:1072
	s_waitcnt lgkmcnt(0)
	v_pk_mov_b32 v[54:55], v[96:97], v[100:101] op_sel:[1,0]
	v_mov_b32_e32 v97, v101
	v_pk_mul_f32 v[96:97], v[136:137], v[96:97]
	s_nop 0
	v_pk_fma_f32 v[54:55], v[136:137], v[54:55], v[96:97] op_sel:[1,0,0] op_sel_hi:[0,1,1]
	v_mov_b32_e32 v96, v98
	v_mov_b32_e32 v97, v102
	v_pk_fma_f32 v[54:55], v[138:139], v[96:97], v[54:55] op_sel_hi:[0,1,1]
	v_mov_b32_e32 v2, v139
	v_mov_b32_e32 v102, v99
	v_pk_fma_f32 v[54:55], v[2:3], v[102:103], v[54:55] op_sel_hi:[0,1,1]
	ds_read_b128 v[96:99], v57 offset:2096
	ds_read_b128 v[100:103], v57 offset:3120
	v_pk_add_f32 v[52:53], v[52:53], v[54:55]
	s_waitcnt lgkmcnt(0)
	v_pk_mov_b32 v[54:55], v[96:97], v[100:101] op_sel:[1,0]
	v_mov_b32_e32 v97, v101
	v_pk_mul_f32 v[96:97], v[136:137], v[96:97]
	s_nop 0
	v_pk_fma_f32 v[54:55], v[136:137], v[54:55], v[96:97] op_sel:[1,0,0] op_sel_hi:[0,1,1]
	v_mov_b32_e32 v96, v98
	v_mov_b32_e32 v97, v102
	v_pk_fma_f32 v[54:55], v[138:139], v[96:97], v[54:55] op_sel_hi:[0,1,1]
	v_mov_b32_e32 v102, v99
	v_pk_fma_f32 v[54:55], v[2:3], v[102:103], v[54:55] op_sel_hi:[0,1,1]
	ds_read_b128 v[96:99], v57 offset:4144
	ds_read_b128 v[100:103], v57 offset:5168
	v_pk_add_f32 v[50:51], v[50:51], v[54:55]
	s_waitcnt lgkmcnt(0)
	v_pk_mov_b32 v[54:55], v[96:97], v[100:101] op_sel:[1,0]
	v_mov_b32_e32 v97, v101
	v_pk_mul_f32 v[96:97], v[136:137], v[96:97]
	s_nop 0
	v_pk_fma_f32 v[54:55], v[136:137], v[54:55], v[96:97] op_sel:[1,0,0] op_sel_hi:[0,1,1]
	v_mov_b32_e32 v96, v98
	v_mov_b32_e32 v97, v102
	v_pk_fma_f32 v[54:55], v[138:139], v[96:97], v[54:55] op_sel_hi:[0,1,1]
	v_mov_b32_e32 v102, v99
	v_pk_fma_f32 v[54:55], v[2:3], v[102:103], v[54:55] op_sel_hi:[0,1,1]
	ds_read_b128 v[96:99], v57 offset:6192
	ds_read_b128 v[100:103], v57 offset:7216
	v_pk_add_f32 v[46:47], v[46:47], v[54:55]
	s_waitcnt lgkmcnt(0)
; __device__ __forceinline__ void rwkv_fin_item(const Params& p, int l, int item, char* ldsraw) {
;     ...
;     for (int mq = 0; mq < 16; mq++) {
;       const f32x4 sv = *(const f32x4*)(sf + mq * 4);
; #pragma unroll
;       for (int t = 0; t < 16; t++) {
;         const f32x4 zv = *(const f32x4*)(zl + t * 256 + h * 64 + mq * 4);
;         yv[t] += sv[0] * zv[0] + sv[1] * zv[1] + sv[2] * zv[2] + sv[3] * zv[3];
;       }
	v_pk_mov_b32 v[54:55], v[96:97], v[100:101] op_sel:[1,0]
	v_mov_b32_e32 v97, v101
	v_pk_mul_f32 v[96:97], v[136:137], v[96:97]
	s_nop 0
	v_pk_fma_f32 v[54:55], v[136:137], v[54:55], v[96:97] op_sel:[1,0,0] op_sel_hi:[0,1,1]
	v_mov_b32_e32 v96, v98
	v_mov_b32_e32 v97, v102
	v_pk_fma_f32 v[54:55], v[138:139], v[96:97], v[54:55] op_sel_hi:[0,1,1]
	v_mov_b32_e32 v102, v99
	v_pk_fma_f32 v[54:55], v[2:3], v[102:103], v[54:55] op_sel_hi:[0,1,1]
	ds_read_b128 v[96:99], v57 offset:8240
	ds_read_b128 v[100:103], v57 offset:9264
	v_pk_add_f32 v[44:45], v[44:45], v[54:55]
	s_waitcnt lgkmcnt(0)
	v_pk_mov_b32 v[54:55], v[96:97], v[100:101] op_sel:[1,0]
	v_mov_b32_e32 v97, v101
	v_pk_mul_f32 v[96:97], v[136:137], v[96:97]
	s_nop 0
	v_pk_fma_f32 v[54:55], v[136:137], v[54:55], v[96:97] op_sel:[1,0,0] op_sel_hi:[0,1,1]
	v_mov_b32_e32 v96, v98
	v_mov_b32_e32 v97, v102
	v_pk_fma_f32 v[54:55], v[138:139], v[96:97], v[54:55] op_sel_hi:[0,1,1]
	v_mov_b32_e32 v102, v99
	v_pk_fma_f32 v[54:55], v[2:3], v[102:103], v[54:55] op_sel_hi:[0,1,1]
	ds_read_b128 v[96:99], v57 offset:10288
	ds_read_b128 v[100:103], v57 offset:11312
	v_pk_add_f32 v[10:11], v[10:11], v[54:55]
	s_waitcnt lgkmcnt(0)
	v_pk_mov_b32 v[54:55], v[96:97], v[100:101] op_sel:[1,0]
	v_mov_b32_e32 v97, v101
	v_pk_mul_f32 v[96:97], v[136:137], v[96:97]
	s_nop 0
	v_pk_fma_f32 v[54:55], v[136:137], v[54:55], v[96:97] op_sel:[1,0,0] op_sel_hi:[0,1,1]
	v_mov_b32_e32 v96, v98
	v_mov_b32_e32 v97, v102
	v_pk_fma_f32 v[54:55], v[138:139], v[96:97], v[54:55] op_sel_hi:[0,1,1]
	v_mov_b32_e32 v102, v99
	v_pk_fma_f32 v[54:55], v[2:3], v[102:103], v[54:55] op_sel_hi:[0,1,1]
	ds_read_b128 v[96:99], v57 offset:12336
	ds_read_b128 v[100:103], v57 offset:13360
	v_pk_add_f32 v[8:9], v[8:9], v[54:55]
	s_waitcnt lgkmcnt(0)
	v_pk_mov_b32 v[54:55], v[96:97], v[100:101] op_sel:[1,0]
	v_mov_b32_e32 v97, v101
	v_pk_mul_f32 v[96:97], v[136:137], v[96:97]
	s_nop 0
	v_pk_fma_f32 v[54:55], v[136:137], v[54:55], v[96:97] op_sel:[1,0,0] op_sel_hi:[0,1,1]
	v_mov_b32_e32 v96, v98
	v_mov_b32_e32 v97, v102
	v_pk_fma_f32 v[54:55], v[138:139], v[96:97], v[54:55] op_sel_hi:[0,1,1]
	v_mov_b32_e32 v102, v99
	v_pk_fma_f32 v[54:55], v[2:3], v[102:103], v[54:55] op_sel_hi:[0,1,1]
	ds_read_b128 v[96:99], v57 offset:14384
	ds_read_b128 v[100:103], v57 offset:15408
	v_pk_add_f32 v[6:7], v[6:7], v[54:55]
	s_waitcnt lgkmcnt(0)
	v_pk_mov_b32 v[54:55], v[96:97], v[100:101] op_sel:[1,0]
	v_mov_b32_e32 v97, v101
	v_pk_mul_f32 v[96:97], v[136:137], v[96:97]
	s_nop 0
	v_pk_fma_f32 v[54:55], v[136:137], v[54:55], v[96:97] op_sel:[1,0,0] op_sel_hi:[0,1,1]
	v_mov_b32_e32 v96, v98
	v_mov_b32_e32 v97, v102
	v_pk_fma_f32 v[54:55], v[138:139], v[96:97], v[54:55] op_sel_hi:[0,1,1]
	v_mov_b32_e32 v102, v99
	v_pk_fma_f32 v[54:55], v[2:3], v[102:103], v[54:55] op_sel_hi:[0,1,1]
	v_pk_add_f32 v[4:5], v[4:5], v[54:55]
	s_waitcnt vmcnt(11)
	ds_read_b128 v[96:99], v57 offset:64
	ds_read_b128 v[100:103], v57 offset:1088
	s_waitcnt lgkmcnt(0)
	v_pk_mov_b32 v[54:55], v[96:97], v[100:101] op_sel:[1,0]
	v_mov_b32_e32 v97, v101
	v_pk_mul_f32 v[96:97], v[140:141], v[96:97]
	s_nop 0
	v_pk_fma_f32 v[54:55], v[140:141], v[54:55], v[96:97] op_sel:[1,0,0] op_sel_hi:[0,1,1]
	v_mov_b32_e32 v96, v98
	v_mov_b32_e32 v97, v102
	v_pk_fma_f32 v[54:55], v[142:143], v[96:97], v[54:55] op_sel_hi:[0,1,1]
	v_mov_b32_e32 v2, v143
	v_mov_b32_e32 v102, v99
	v_pk_fma_f32 v[54:55], v[2:3], v[102:103], v[54:55] op_sel_hi:[0,1,1]
	ds_read_b128 v[96:99], v57 offset:2112
	ds_read_b128 v[100:103], v57 offset:3136
	v_pk_add_f32 v[52:53], v[52:53], v[54:55]
	s_waitcnt lgkmcnt(0)
	v_pk_mov_b32 v[54:55], v[96:97], v[100:101] op_sel:[1,0]
	v_mov_b32_e32 v97, v101
	v_pk_mul_f32 v[96:97], v[140:141], v[96:97]
	s_nop 0
	v_pk_fma_f32 v[54:55], v[140:141], v[54:55], v[96:97] op_sel:[1,0,0] op_sel_hi:[0,1,1]
	v_mov_b32_e32 v96, v98
	v_mov_b32_e32 v97, v102
	v_pk_fma_f32 v[54:55], v[142:143], v[96:97], v[54:55] op_sel_hi:[0,1,1]
	v_mov_b32_e32 v102, v99
	v_pk_fma_f32 v[54:55], v[2:3], v[102:103], v[54:55] op_sel_hi:[0,1,1]
	ds_read_b128 v[96:99], v57 offset:4160
	ds_read_b128 v[100:103], v57 offset:5184
	v_pk_add_f32 v[50:51], v[50:51], v[54:55]
	s_waitcnt lgkmcnt(0)
	v_pk_mov_b32 v[54:55], v[96:97], v[100:101] op_sel:[1,0]
	v_mov_b32_e32 v97, v101
	v_pk_mul_f32 v[96:97], v[140:141], v[96:97]
	s_nop 0
	v_pk_fma_f32 v[54:55], v[140:141], v[54:55], v[96:97] op_sel:[1,0,0] op_sel_hi:[0,1,1]
	v_mov_b32_e32 v96, v98
	v_mov_b32_e32 v97, v102
	v_pk_fma_f32 v[54:55], v[142:143], v[96:97], v[54:55] op_sel_hi:[0,1,1]
	v_mov_b32_e32 v102, v99
	v_pk_fma_f32 v[54:55], v[2:3], v[102:103], v[54:55] op_sel_hi:[0,1,1]
	ds_read_b128 v[96:99], v57 offset:6208
	ds_read_b128 v[100:103], v57 offset:7232
	v_pk_add_f32 v[46:47], v[46:47], v[54:55]
	s_waitcnt lgkmcnt(0)
	v_pk_mov_b32 v[54:55], v[96:97], v[100:101] op_sel:[1,0]
	v_mov_b32_e32 v97, v101
	v_pk_mul_f32 v[96:97], v[140:141], v[96:97]
	s_nop 0
	v_pk_fma_f32 v[54:55], v[140:141], v[54:55], v[96:97] op_sel:[1,0,0] op_sel_hi:[0,1,1]
	v_mov_b32_e32 v96, v98
	v_mov_b32_e32 v97, v102
	v_pk_fma_f32 v[54:55], v[142:143], v[96:97], v[54:55] op_sel_hi:[0,1,1]
	v_mov_b32_e32 v102, v99
	v_pk_fma_f32 v[54:55], v[2:3], v[102:103], v[54:55] op_sel_hi:[0,1,1]
	ds_read_b128 v[96:99], v57 offset:8256
	ds_read_b128 v[100:103], v57 offset:9280
	v_pk_add_f32 v[44:45], v[44:45], v[54:55]
	s_waitcnt lgkmcnt(0)
; __device__ __forceinline__ void rwkv_fin_item(const Params& p, int l, int item, char* ldsraw) {
;     ...
;     for (int mq = 0; mq < 16; mq++) {
;       const f32x4 sv = *(const f32x4*)(sf + mq * 4);
; #pragma unroll
;       for (int t = 0; t < 16; t++) {
;         const f32x4 zv = *(const f32x4*)(zl + t * 256 + h * 64 + mq * 4);
;         yv[t] += sv[0] * zv[0] + sv[1] * zv[1] + sv[2] * zv[2] + sv[3] * zv[3];
;       }
	v_pk_mov_b32 v[54:55], v[96:97], v[100:101] op_sel:[1,0]
	v_mov_b32_e32 v97, v101
	v_pk_mul_f32 v[96:97], v[140:141], v[96:97]
	s_nop 0
	v_pk_fma_f32 v[54:55], v[140:141], v[54:55], v[96:97] op_sel:[1,0,0] op_sel_hi:[0,1,1]
	v_mov_b32_e32 v96, v98
	v_mov_b32_e32 v97, v102
	v_pk_fma_f32 v[54:55], v[142:143], v[96:97], v[54:55] op_sel_hi:[0,1,1]
	v_mov_b32_e32 v102, v99
	v_pk_fma_f32 v[54:55], v[2:3], v[102:103], v[54:55] op_sel_hi:[0,1,1]
	ds_read_b128 v[96:99], v57 offset:10304
	ds_read_b128 v[100:103], v57 offset:11328
	v_pk_add_f32 v[10:11], v[10:11], v[54:55]
	s_waitcnt lgkmcnt(0)
	v_pk_mov_b32 v[54:55], v[96:97], v[100:101] op_sel:[1,0]
	v_mov_b32_e32 v97, v101
	v_pk_mul_f32 v[96:97], v[140:141], v[96:97]
	s_nop 0
	v_pk_fma_f32 v[54:55], v[140:141], v[54:55], v[96:97] op_sel:[1,0,0] op_sel_hi:[0,1,1]
	v_mov_b32_e32 v96, v98
	v_mov_b32_e32 v97, v102
	v_pk_fma_f32 v[54:55], v[142:143], v[96:97], v[54:55] op_sel_hi:[0,1,1]
	v_mov_b32_e32 v102, v99
	v_pk_fma_f32 v[54:55], v[2:3], v[102:103], v[54:55] op_sel_hi:[0,1,1]
	ds_read_b128 v[96:99], v57 offset:12352
	ds_read_b128 v[100:103], v57 offset:13376
	v_pk_add_f32 v[8:9], v[8:9], v[54:55]
	s_waitcnt lgkmcnt(0)
	v_pk_mov_b32 v[54:55], v[96:97], v[100:101] op_sel:[1,0]
	v_mov_b32_e32 v97, v101
	v_pk_mul_f32 v[96:97], v[140:141], v[96:97]
	s_nop 0
	v_pk_fma_f32 v[54:55], v[140:141], v[54:55], v[96:97] op_sel:[1,0,0] op_sel_hi:[0,1,1]
	v_mov_b32_e32 v96, v98
	v_mov_b32_e32 v97, v102
	v_pk_fma_f32 v[54:55], v[142:143], v[96:97], v[54:55] op_sel_hi:[0,1,1]
	v_mov_b32_e32 v102, v99
	v_pk_fma_f32 v[54:55], v[2:3], v[102:103], v[54:55] op_sel_hi:[0,1,1]
	ds_read_b128 v[96:99], v57 offset:14400
	ds_read_b128 v[100:103], v57 offset:15424
	v_pk_add_f32 v[6:7], v[6:7], v[54:55]
	s_waitcnt lgkmcnt(0)
	v_pk_mov_b32 v[54:55], v[96:97], v[100:101] op_sel:[1,0]
	v_mov_b32_e32 v97, v101
	v_pk_mul_f32 v[96:97], v[140:141], v[96:97]
	s_nop 0
	v_pk_fma_f32 v[54:55], v[140:141], v[54:55], v[96:97] op_sel:[1,0,0] op_sel_hi:[0,1,1]
	v_mov_b32_e32 v96, v98
	v_mov_b32_e32 v97, v102
	v_pk_fma_f32 v[54:55], v[142:143], v[96:97], v[54:55] op_sel_hi:[0,1,1]
	v_mov_b32_e32 v102, v99
	v_pk_fma_f32 v[54:55], v[2:3], v[102:103], v[54:55] op_sel_hi:[0,1,1]
	v_pk_add_f32 v[4:5], v[4:5], v[54:55]
	s_waitcnt vmcnt(10)
	ds_read_b128 v[96:99], v57 offset:80
	ds_read_b128 v[100:103], v57 offset:1104
	s_waitcnt lgkmcnt(0)
	v_pk_mov_b32 v[54:55], v[96:97], v[100:101] op_sel:[1,0]
	v_mov_b32_e32 v97, v101
	v_pk_mul_f32 v[96:97], v[144:145], v[96:97]
	s_nop 0
	v_pk_fma_f32 v[54:55], v[144:145], v[54:55], v[96:97] op_sel:[1,0,0] op_sel_hi:[0,1,1]
	v_mov_b32_e32 v96, v98
	v_mov_b32_e32 v97, v102
	v_pk_fma_f32 v[54:55], v[146:147], v[96:97], v[54:55] op_sel_hi:[0,1,1]
	v_mov_b32_e32 v2, v147
	v_mov_b32_e32 v102, v99
	v_pk_fma_f32 v[54:55], v[2:3], v[102:103], v[54:55] op_sel_hi:[0,1,1]
	ds_read_b128 v[96:99], v57 offset:2128
	ds_read_b128 v[100:103], v57 offset:3152
	v_pk_add_f32 v[52:53], v[52:53], v[54:55]
	s_waitcnt lgkmcnt(0)
	v_pk_mov_b32 v[54:55], v[96:97], v[100:101] op_sel:[1,0]
	v_mov_b32_e32 v97, v101
	v_pk_mul_f32 v[96:97], v[144:145], v[96:97]
	s_nop 0
	v_pk_fma_f32 v[54:55], v[144:145], v[54:55], v[96:97] op_sel:[1,0,0] op_sel_hi:[0,1,1]
	v_mov_b32_e32 v96, v98
	v_mov_b32_e32 v97, v102
	v_pk_fma_f32 v[54:55], v[146:147], v[96:97], v[54:55] op_sel_hi:[0,1,1]
	v_mov_b32_e32 v102, v99
	v_pk_fma_f32 v[54:55], v[2:3], v[102:103], v[54:55] op_sel_hi:[0,1,1]
	ds_read_b128 v[96:99], v57 offset:4176
	ds_read_b128 v[100:103], v57 offset:5200
	v_pk_add_f32 v[50:51], v[50:51], v[54:55]
	s_waitcnt lgkmcnt(0)
	v_pk_mov_b32 v[54:55], v[96:97], v[100:101] op_sel:[1,0]
	v_mov_b32_e32 v97, v101
	v_pk_mul_f32 v[96:97], v[144:145], v[96:97]
	s_nop 0
	v_pk_fma_f32 v[54:55], v[144:145], v[54:55], v[96:97] op_sel:[1,0,0] op_sel_hi:[0,1,1]
	v_mov_b32_e32 v96, v98
	v_mov_b32_e32 v97, v102
	v_pk_fma_f32 v[54:55], v[146:147], v[96:97], v[54:55] op_sel_hi:[0,1,1]
	v_mov_b32_e32 v102, v99
	v_pk_fma_f32 v[54:55], v[2:3], v[102:103], v[54:55] op_sel_hi:[0,1,1]
	ds_read_b128 v[96:99], v57 offset:6224
	ds_read_b128 v[100:103], v57 offset:7248
	v_pk_add_f32 v[46:47], v[46:47], v[54:55]
	s_waitcnt lgkmcnt(0)
	v_pk_mov_b32 v[54:55], v[96:97], v[100:101] op_sel:[1,0]
	v_mov_b32_e32 v97, v101
	v_pk_mul_f32 v[96:97], v[144:145], v[96:97]
	s_nop 0
	v_pk_fma_f32 v[54:55], v[144:145], v[54:55], v[96:97] op_sel:[1,0,0] op_sel_hi:[0,1,1]
	v_mov_b32_e32 v96, v98
	v_mov_b32_e32 v97, v102
	v_pk_fma_f32 v[54:55], v[146:147], v[96:97], v[54:55] op_sel_hi:[0,1,1]
	v_mov_b32_e32 v102, v99
	v_pk_fma_f32 v[54:55], v[2:3], v[102:103], v[54:55] op_sel_hi:[0,1,1]
	ds_read_b128 v[96:99], v57 offset:8272
	ds_read_b128 v[100:103], v57 offset:9296
	v_pk_add_f32 v[44:45], v[44:45], v[54:55]
	s_waitcnt lgkmcnt(0)
	v_pk_mov_b32 v[54:55], v[96:97], v[100:101] op_sel:[1,0]
	v_mov_b32_e32 v97, v101
	v_pk_mul_f32 v[96:97], v[144:145], v[96:97]
	s_nop 0
	v_pk_fma_f32 v[54:55], v[144:145], v[54:55], v[96:97] op_sel:[1,0,0] op_sel_hi:[0,1,1]
	v_mov_b32_e32 v96, v98
	v_mov_b32_e32 v97, v102
	v_pk_fma_f32 v[54:55], v[146:147], v[96:97], v[54:55] op_sel_hi:[0,1,1]
	v_mov_b32_e32 v102, v99
	v_pk_fma_f32 v[54:55], v[2:3], v[102:103], v[54:55] op_sel_hi:[0,1,1]
	ds_read_b128 v[96:99], v57 offset:10320
	ds_read_b128 v[100:103], v57 offset:11344
	v_pk_add_f32 v[10:11], v[10:11], v[54:55]
	s_waitcnt lgkmcnt(0)
; __device__ __forceinline__ void rwkv_fin_item(const Params& p, int l, int item, char* ldsraw) {
;     ...
;     for (int mq = 0; mq < 16; mq++) {
;       const f32x4 sv = *(const f32x4*)(sf + mq * 4);
; #pragma unroll
;       for (int t = 0; t < 16; t++) {
;         const f32x4 zv = *(const f32x4*)(zl + t * 256 + h * 64 + mq * 4);
;         yv[t] += sv[0] * zv[0] + sv[1] * zv[1] + sv[2] * zv[2] + sv[3] * zv[3];
;       }
	v_pk_mov_b32 v[54:55], v[96:97], v[100:101] op_sel:[1,0]
	v_mov_b32_e32 v97, v101
	v_pk_mul_f32 v[96:97], v[144:145], v[96:97]
	s_nop 0
	v_pk_fma_f32 v[54:55], v[144:145], v[54:55], v[96:97] op_sel:[1,0,0] op_sel_hi:[0,1,1]
	v_mov_b32_e32 v96, v98
	v_mov_b32_e32 v97, v102
	v_pk_fma_f32 v[54:55], v[146:147], v[96:97], v[54:55] op_sel_hi:[0,1,1]
	v_mov_b32_e32 v102, v99
	v_pk_fma_f32 v[54:55], v[2:3], v[102:103], v[54:55] op_sel_hi:[0,1,1]
	ds_read_b128 v[96:99], v57 offset:12368
	ds_read_b128 v[100:103], v57 offset:13392
	v_pk_add_f32 v[8:9], v[8:9], v[54:55]
	s_waitcnt lgkmcnt(0)
	v_pk_mov_b32 v[54:55], v[96:97], v[100:101] op_sel:[1,0]
	v_mov_b32_e32 v97, v101
	v_pk_mul_f32 v[96:97], v[144:145], v[96:97]
	s_nop 0
	v_pk_fma_f32 v[54:55], v[144:145], v[54:55], v[96:97] op_sel:[1,0,0] op_sel_hi:[0,1,1]
	v_mov_b32_e32 v96, v98
	v_mov_b32_e32 v97, v102
	v_pk_fma_f32 v[54:55], v[146:147], v[96:97], v[54:55] op_sel_hi:[0,1,1]
	v_mov_b32_e32 v102, v99
	v_pk_fma_f32 v[54:55], v[2:3], v[102:103], v[54:55] op_sel_hi:[0,1,1]
	ds_read_b128 v[96:99], v57 offset:14416
	ds_read_b128 v[100:103], v57 offset:15440
	v_pk_add_f32 v[6:7], v[6:7], v[54:55]
	s_waitcnt lgkmcnt(0)
	v_pk_mov_b32 v[54:55], v[96:97], v[100:101] op_sel:[1,0]
	v_mov_b32_e32 v97, v101
	v_pk_mul_f32 v[96:97], v[144:145], v[96:97]
	s_nop 0
	v_pk_fma_f32 v[54:55], v[144:145], v[54:55], v[96:97] op_sel:[1,0,0] op_sel_hi:[0,1,1]
	v_mov_b32_e32 v96, v98
	v_mov_b32_e32 v97, v102
	v_pk_fma_f32 v[54:55], v[146:147], v[96:97], v[54:55] op_sel_hi:[0,1,1]
	v_mov_b32_e32 v102, v99
	v_pk_fma_f32 v[54:55], v[2:3], v[102:103], v[54:55] op_sel_hi:[0,1,1]
	v_pk_add_f32 v[4:5], v[4:5], v[54:55]
	s_waitcnt vmcnt(9)
	ds_read_b128 v[96:99], v57 offset:96
	ds_read_b128 v[100:103], v57 offset:1120
	s_waitcnt lgkmcnt(0)
	v_pk_mov_b32 v[54:55], v[96:97], v[100:101] op_sel:[1,0]
	v_mov_b32_e32 v97, v101
	v_pk_mul_f32 v[96:97], v[148:149], v[96:97]
	s_nop 0
	v_pk_fma_f32 v[54:55], v[148:149], v[54:55], v[96:97] op_sel:[1,0,0] op_sel_hi:[0,1,1]
	v_mov_b32_e32 v96, v98
	v_mov_b32_e32 v97, v102
	v_pk_fma_f32 v[54:55], v[150:151], v[96:97], v[54:55] op_sel_hi:[0,1,1]
	v_mov_b32_e32 v2, v151
	v_mov_b32_e32 v102, v99
	v_pk_fma_f32 v[54:55], v[2:3], v[102:103], v[54:55] op_sel_hi:[0,1,1]
	ds_read_b128 v[96:99], v57 offset:2144
	ds_read_b128 v[100:103], v57 offset:3168
	v_pk_add_f32 v[52:53], v[52:53], v[54:55]
	s_waitcnt lgkmcnt(0)
	v_pk_mov_b32 v[54:55], v[96:97], v[100:101] op_sel:[1,0]
	v_mov_b32_e32 v97, v101
	v_pk_mul_f32 v[96:97], v[148:149], v[96:97]
	s_nop 0
	v_pk_fma_f32 v[54:55], v[148:149], v[54:55], v[96:97] op_sel:[1,0,0] op_sel_hi:[0,1,1]
	v_mov_b32_e32 v96, v98
	v_mov_b32_e32 v97, v102
	v_pk_fma_f32 v[54:55], v[150:151], v[96:97], v[54:55] op_sel_hi:[0,1,1]
	v_mov_b32_e32 v102, v99
	v_pk_fma_f32 v[54:55], v[2:3], v[102:103], v[54:55] op_sel_hi:[0,1,1]
	ds_read_b128 v[96:99], v57 offset:4192
	ds_read_b128 v[100:103], v57 offset:5216
	v_pk_add_f32 v[50:51], v[50:51], v[54:55]
	s_waitcnt lgkmcnt(0)
	v_pk_mov_b32 v[54:55], v[96:97], v[100:101] op_sel:[1,0]
	v_mov_b32_e32 v97, v101
	v_pk_mul_f32 v[96:97], v[148:149], v[96:97]
	s_nop 0
	v_pk_fma_f32 v[54:55], v[148:149], v[54:55], v[96:97] op_sel:[1,0,0] op_sel_hi:[0,1,1]
	v_mov_b32_e32 v96, v98
	v_mov_b32_e32 v97, v102
	v_pk_fma_f32 v[54:55], v[150:151], v[96:97], v[54:55] op_sel_hi:[0,1,1]
	v_mov_b32_e32 v102, v99
	v_pk_fma_f32 v[54:55], v[2:3], v[102:103], v[54:55] op_sel_hi:[0,1,1]
	ds_read_b128 v[96:99], v57 offset:6240
	ds_read_b128 v[100:103], v57 offset:7264
	v_pk_add_f32 v[46:47], v[46:47], v[54:55]
	s_waitcnt lgkmcnt(0)
	v_pk_mov_b32 v[54:55], v[96:97], v[100:101] op_sel:[1,0]
	v_mov_b32_e32 v97, v101
	v_pk_mul_f32 v[96:97], v[148:149], v[96:97]
	s_nop 0
	v_pk_fma_f32 v[54:55], v[148:149], v[54:55], v[96:97] op_sel:[1,0,0] op_sel_hi:[0,1,1]
	v_mov_b32_e32 v96, v98
	v_mov_b32_e32 v97, v102
	v_pk_fma_f32 v[54:55], v[150:151], v[96:97], v[54:55] op_sel_hi:[0,1,1]
	v_mov_b32_e32 v102, v99
	v_pk_fma_f32 v[54:55], v[2:3], v[102:103], v[54:55] op_sel_hi:[0,1,1]
	ds_read_b128 v[96:99], v57 offset:8288
	ds_read_b128 v[100:103], v57 offset:9312
	v_pk_add_f32 v[44:45], v[44:45], v[54:55]
	s_waitcnt lgkmcnt(0)
	v_pk_mov_b32 v[54:55], v[96:97], v[100:101] op_sel:[1,0]
	v_mov_b32_e32 v97, v101
	v_pk_mul_f32 v[96:97], v[148:149], v[96:97]
	s_nop 0
	v_pk_fma_f32 v[54:55], v[148:149], v[54:55], v[96:97] op_sel:[1,0,0] op_sel_hi:[0,1,1]
	v_mov_b32_e32 v96, v98
	v_mov_b32_e32 v97, v102
	v_pk_fma_f32 v[54:55], v[150:151], v[96:97], v[54:55] op_sel_hi:[0,1,1]
	v_mov_b32_e32 v102, v99
	v_pk_fma_f32 v[54:55], v[2:3], v[102:103], v[54:55] op_sel_hi:[0,1,1]
	ds_read_b128 v[96:99], v57 offset:10336
	ds_read_b128 v[100:103], v57 offset:11360
	v_pk_add_f32 v[10:11], v[10:11], v[54:55]
	s_waitcnt lgkmcnt(0)
	v_pk_mov_b32 v[54:55], v[96:97], v[100:101] op_sel:[1,0]
	v_mov_b32_e32 v97, v101
	v_pk_mul_f32 v[96:97], v[148:149], v[96:97]
	s_nop 0
	v_pk_fma_f32 v[54:55], v[148:149], v[54:55], v[96:97] op_sel:[1,0,0] op_sel_hi:[0,1,1]
	v_mov_b32_e32 v96, v98
	v_mov_b32_e32 v97, v102
	v_pk_fma_f32 v[54:55], v[150:151], v[96:97], v[54:55] op_sel_hi:[0,1,1]
	v_mov_b32_e32 v102, v99
	v_pk_fma_f32 v[54:55], v[2:3], v[102:103], v[54:55] op_sel_hi:[0,1,1]
	ds_read_b128 v[96:99], v57 offset:12384
	ds_read_b128 v[100:103], v57 offset:13408
	v_pk_add_f32 v[8:9], v[8:9], v[54:55]
	s_waitcnt lgkmcnt(0)
	v_pk_mov_b32 v[54:55], v[96:97], v[100:101] op_sel:[1,0]
	v_mov_b32_e32 v97, v101
	v_pk_mul_f32 v[96:97], v[148:149], v[96:97]
	s_nop 0
	v_pk_fma_f32 v[54:55], v[148:149], v[54:55], v[96:97] op_sel:[1,0,0] op_sel_hi:[0,1,1]
	v_mov_b32_e32 v96, v98
	v_mov_b32_e32 v97, v102
	v_pk_fma_f32 v[54:55], v[150:151], v[96:97], v[54:55] op_sel_hi:[0,1,1]
	v_mov_b32_e32 v102, v99
	v_pk_fma_f32 v[54:55], v[2:3], v[102:103], v[54:55] op_sel_hi:[0,1,1]
	ds_read_b128 v[96:99], v57 offset:14432
	ds_read_b128 v[100:103], v57 offset:15456
	v_pk_add_f32 v[6:7], v[6:7], v[54:55]
	s_waitcnt lgkmcnt(0)
; __device__ __forceinline__ void rwkv_fin_item(const Params& p, int l, int item, char* ldsraw) {
;     ...
;     for (int mq = 0; mq < 16; mq++) {
;       const f32x4 sv = *(const f32x4*)(sf + mq * 4);
; #pragma unroll
;       for (int t = 0; t < 16; t++) {
;         const f32x4 zv = *(const f32x4*)(zl + t * 256 + h * 64 + mq * 4);
;         yv[t] += sv[0] * zv[0] + sv[1] * zv[1] + sv[2] * zv[2] + sv[3] * zv[3];
;       }
	v_pk_mov_b32 v[54:55], v[96:97], v[100:101] op_sel:[1,0]
	v_mov_b32_e32 v97, v101
	v_pk_mul_f32 v[96:97], v[148:149], v[96:97]
	s_nop 0
	v_pk_fma_f32 v[54:55], v[148:149], v[54:55], v[96:97] op_sel:[1,0,0] op_sel_hi:[0,1,1]
	v_mov_b32_e32 v96, v98
	v_mov_b32_e32 v97, v102
	v_pk_fma_f32 v[54:55], v[150:151], v[96:97], v[54:55] op_sel_hi:[0,1,1]
	v_mov_b32_e32 v102, v99
	v_pk_fma_f32 v[54:55], v[2:3], v[102:103], v[54:55] op_sel_hi:[0,1,1]
	v_pk_add_f32 v[4:5], v[4:5], v[54:55]
	s_waitcnt vmcnt(8)
	ds_read_b128 v[96:99], v57 offset:112
	ds_read_b128 v[100:103], v57 offset:1136
	s_waitcnt lgkmcnt(0)
	v_pk_mov_b32 v[54:55], v[96:97], v[100:101] op_sel:[1,0]
	v_mov_b32_e32 v97, v101
	v_pk_mul_f32 v[96:97], v[152:153], v[96:97]
	s_nop 0
	v_pk_fma_f32 v[54:55], v[152:153], v[54:55], v[96:97] op_sel:[1,0,0] op_sel_hi:[0,1,1]
	v_mov_b32_e32 v96, v98
	v_mov_b32_e32 v97, v102
	v_pk_fma_f32 v[54:55], v[154:155], v[96:97], v[54:55] op_sel_hi:[0,1,1]
	v_mov_b32_e32 v2, v155
	v_mov_b32_e32 v102, v99
	v_pk_fma_f32 v[54:55], v[2:3], v[102:103], v[54:55] op_sel_hi:[0,1,1]
	ds_read_b128 v[96:99], v57 offset:2160
	ds_read_b128 v[100:103], v57 offset:3184
	v_pk_add_f32 v[52:53], v[52:53], v[54:55]
	s_waitcnt lgkmcnt(0)
	v_pk_mov_b32 v[54:55], v[96:97], v[100:101] op_sel:[1,0]
	v_mov_b32_e32 v97, v101
	v_pk_mul_f32 v[96:97], v[152:153], v[96:97]
	s_nop 0
	v_pk_fma_f32 v[54:55], v[152:153], v[54:55], v[96:97] op_sel:[1,0,0] op_sel_hi:[0,1,1]
	v_mov_b32_e32 v96, v98
	v_mov_b32_e32 v97, v102
	v_pk_fma_f32 v[54:55], v[154:155], v[96:97], v[54:55] op_sel_hi:[0,1,1]
	v_mov_b32_e32 v102, v99
	v_pk_fma_f32 v[54:55], v[2:3], v[102:103], v[54:55] op_sel_hi:[0,1,1]
	ds_read_b128 v[96:99], v57 offset:4208
	ds_read_b128 v[100:103], v57 offset:5232
	v_pk_add_f32 v[50:51], v[50:51], v[54:55]
	s_waitcnt lgkmcnt(0)
	v_pk_mov_b32 v[54:55], v[96:97], v[100:101] op_sel:[1,0]
	v_mov_b32_e32 v97, v101
	v_pk_mul_f32 v[96:97], v[152:153], v[96:97]
	s_nop 0
	v_pk_fma_f32 v[54:55], v[152:153], v[54:55], v[96:97] op_sel:[1,0,0] op_sel_hi:[0,1,1]
	v_mov_b32_e32 v96, v98
	v_mov_b32_e32 v97, v102
	v_pk_fma_f32 v[54:55], v[154:155], v[96:97], v[54:55] op_sel_hi:[0,1,1]
	v_mov_b32_e32 v102, v99
	v_pk_fma_f32 v[54:55], v[2:3], v[102:103], v[54:55] op_sel_hi:[0,1,1]
	ds_read_b128 v[96:99], v57 offset:6256
	ds_read_b128 v[100:103], v57 offset:7280
	v_pk_add_f32 v[46:47], v[46:47], v[54:55]
	s_waitcnt lgkmcnt(0)
	v_pk_mov_b32 v[54:55], v[96:97], v[100:101] op_sel:[1,0]
	v_mov_b32_e32 v97, v101
	v_pk_mul_f32 v[96:97], v[152:153], v[96:97]
	s_nop 0
	v_pk_fma_f32 v[54:55], v[152:153], v[54:55], v[96:97] op_sel:[1,0,0] op_sel_hi:[0,1,1]
	v_mov_b32_e32 v96, v98
	v_mov_b32_e32 v97, v102
	v_pk_fma_f32 v[54:55], v[154:155], v[96:97], v[54:55] op_sel_hi:[0,1,1]
	v_mov_b32_e32 v102, v99
	v_pk_fma_f32 v[54:55], v[2:3], v[102:103], v[54:55] op_sel_hi:[0,1,1]
	ds_read_b128 v[96:99], v57 offset:8304
	ds_read_b128 v[100:103], v57 offset:9328
	v_pk_add_f32 v[44:45], v[44:45], v[54:55]
	s_waitcnt lgkmcnt(0)
	v_pk_mov_b32 v[54:55], v[96:97], v[100:101] op_sel:[1,0]
	v_mov_b32_e32 v97, v101
	v_pk_mul_f32 v[96:97], v[152:153], v[96:97]
	s_nop 0
	v_pk_fma_f32 v[54:55], v[152:153], v[54:55], v[96:97] op_sel:[1,0,0] op_sel_hi:[0,1,1]
	v_mov_b32_e32 v96, v98
	v_mov_b32_e32 v97, v102
	v_pk_fma_f32 v[54:55], v[154:155], v[96:97], v[54:55] op_sel_hi:[0,1,1]
	v_mov_b32_e32 v102, v99
	v_pk_fma_f32 v[54:55], v[2:3], v[102:103], v[54:55] op_sel_hi:[0,1,1]
	ds_read_b128 v[96:99], v57 offset:10352
	ds_read_b128 v[100:103], v57 offset:11376
	v_pk_add_f32 v[10:11], v[10:11], v[54:55]
	s_waitcnt lgkmcnt(0)
	v_pk_mov_b32 v[54:55], v[96:97], v[100:101] op_sel:[1,0]
	v_mov_b32_e32 v97, v101
	v_pk_mul_f32 v[96:97], v[152:153], v[96:97]
	s_nop 0
	v_pk_fma_f32 v[54:55], v[152:153], v[54:55], v[96:97] op_sel:[1,0,0] op_sel_hi:[0,1,1]
	v_mov_b32_e32 v96, v98
	v_mov_b32_e32 v97, v102
	v_pk_fma_f32 v[54:55], v[154:155], v[96:97], v[54:55] op_sel_hi:[0,1,1]
	v_mov_b32_e32 v102, v99
	v_pk_fma_f32 v[54:55], v[2:3], v[102:103], v[54:55] op_sel_hi:[0,1,1]
	ds_read_b128 v[96:99], v57 offset:12400
	ds_read_b128 v[100:103], v57 offset:13424
	v_pk_add_f32 v[8:9], v[8:9], v[54:55]
	s_waitcnt lgkmcnt(0)
	v_pk_mov_b32 v[54:55], v[96:97], v[100:101] op_sel:[1,0]
	v_mov_b32_e32 v97, v101
	v_pk_mul_f32 v[96:97], v[152:153], v[96:97]
	s_nop 0
	v_pk_fma_f32 v[54:55], v[152:153], v[54:55], v[96:97] op_sel:[1,0,0] op_sel_hi:[0,1,1]
	v_mov_b32_e32 v96, v98
	v_mov_b32_e32 v97, v102
	v_pk_fma_f32 v[54:55], v[154:155], v[96:97], v[54:55] op_sel_hi:[0,1,1]
	v_mov_b32_e32 v102, v99
	v_pk_fma_f32 v[54:55], v[2:3], v[102:103], v[54:55] op_sel_hi:[0,1,1]
	ds_read_b128 v[96:99], v57 offset:14448
	ds_read_b128 v[100:103], v57 offset:15472
	v_pk_add_f32 v[6:7], v[6:7], v[54:55]
	s_waitcnt lgkmcnt(0)
	v_pk_mov_b32 v[54:55], v[96:97], v[100:101] op_sel:[1,0]
	v_mov_b32_e32 v97, v101
	v_pk_mul_f32 v[96:97], v[152:153], v[96:97]
	s_nop 0
	v_pk_fma_f32 v[54:55], v[152:153], v[54:55], v[96:97] op_sel:[1,0,0] op_sel_hi:[0,1,1]
	v_mov_b32_e32 v96, v98
	v_mov_b32_e32 v97, v102
	v_pk_fma_f32 v[54:55], v[154:155], v[96:97], v[54:55] op_sel_hi:[0,1,1]
	v_mov_b32_e32 v102, v99
	v_pk_fma_f32 v[54:55], v[2:3], v[102:103], v[54:55] op_sel_hi:[0,1,1]
	v_pk_add_f32 v[4:5], v[4:5], v[54:55]
	s_waitcnt vmcnt(7)
	ds_read_b128 v[96:99], v57 offset:128
	ds_read_b128 v[100:103], v57 offset:1152
	s_waitcnt lgkmcnt(0)
; __device__ __forceinline__ void rwkv_fin_item(const Params& p, int l, int item, char* ldsraw) {
;     ...
;     for (int mq = 0; mq < 16; mq++) {
;       const f32x4 sv = *(const f32x4*)(sf + mq * 4);
; #pragma unroll
;       for (int t = 0; t < 16; t++) {
;         const f32x4 zv = *(const f32x4*)(zl + t * 256 + h * 64 + mq * 4);
;         yv[t] += sv[0] * zv[0] + sv[1] * zv[1] + sv[2] * zv[2] + sv[3] * zv[3];
;       }
	v_pk_mov_b32 v[54:55], v[96:97], v[100:101] op_sel:[1,0]
	v_mov_b32_e32 v97, v101
	v_pk_mul_f32 v[96:97], v[156:157], v[96:97]
	s_nop 0
	v_pk_fma_f32 v[54:55], v[156:157], v[54:55], v[96:97] op_sel:[1,0,0] op_sel_hi:[0,1,1]
	v_mov_b32_e32 v96, v98
	v_mov_b32_e32 v97, v102
	v_pk_fma_f32 v[54:55], v[158:159], v[96:97], v[54:55] op_sel_hi:[0,1,1]
	v_mov_b32_e32 v2, v159
	v_mov_b32_e32 v102, v99
	v_pk_fma_f32 v[54:55], v[2:3], v[102:103], v[54:55] op_sel_hi:[0,1,1]
	ds_read_b128 v[96:99], v57 offset:2176
	ds_read_b128 v[100:103], v57 offset:3200
	v_pk_add_f32 v[52:53], v[52:53], v[54:55]
	s_waitcnt lgkmcnt(0)
	v_pk_mov_b32 v[54:55], v[96:97], v[100:101] op_sel:[1,0]
	v_mov_b32_e32 v97, v101
	v_pk_mul_f32 v[96:97], v[156:157], v[96:97]
	s_nop 0
	v_pk_fma_f32 v[54:55], v[156:157], v[54:55], v[96:97] op_sel:[1,0,0] op_sel_hi:[0,1,1]
	v_mov_b32_e32 v96, v98
	v_mov_b32_e32 v97, v102
	v_pk_fma_f32 v[54:55], v[158:159], v[96:97], v[54:55] op_sel_hi:[0,1,1]
	v_mov_b32_e32 v102, v99
	v_pk_fma_f32 v[54:55], v[2:3], v[102:103], v[54:55] op_sel_hi:[0,1,1]
	ds_read_b128 v[96:99], v57 offset:4224
	ds_read_b128 v[100:103], v57 offset:5248
	v_pk_add_f32 v[50:51], v[50:51], v[54:55]
	s_waitcnt lgkmcnt(0)
	v_pk_mov_b32 v[54:55], v[96:97], v[100:101] op_sel:[1,0]
	v_mov_b32_e32 v97, v101
	v_pk_mul_f32 v[96:97], v[156:157], v[96:97]
	s_nop 0
	v_pk_fma_f32 v[54:55], v[156:157], v[54:55], v[96:97] op_sel:[1,0,0] op_sel_hi:[0,1,1]
	v_mov_b32_e32 v96, v98
	v_mov_b32_e32 v97, v102
	v_pk_fma_f32 v[54:55], v[158:159], v[96:97], v[54:55] op_sel_hi:[0,1,1]
	v_mov_b32_e32 v102, v99
	v_pk_fma_f32 v[54:55], v[2:3], v[102:103], v[54:55] op_sel_hi:[0,1,1]
	ds_read_b128 v[96:99], v57 offset:6272
	ds_read_b128 v[100:103], v57 offset:7296
	v_pk_add_f32 v[46:47], v[46:47], v[54:55]
	s_waitcnt lgkmcnt(0)
	v_pk_mov_b32 v[54:55], v[96:97], v[100:101] op_sel:[1,0]
	v_mov_b32_e32 v97, v101
	v_pk_mul_f32 v[96:97], v[156:157], v[96:97]
	s_nop 0
	v_pk_fma_f32 v[54:55], v[156:157], v[54:55], v[96:97] op_sel:[1,0,0] op_sel_hi:[0,1,1]
	v_mov_b32_e32 v96, v98
	v_mov_b32_e32 v97, v102
	v_pk_fma_f32 v[54:55], v[158:159], v[96:97], v[54:55] op_sel_hi:[0,1,1]
	v_mov_b32_e32 v102, v99
	v_pk_fma_f32 v[54:55], v[2:3], v[102:103], v[54:55] op_sel_hi:[0,1,1]
	ds_read_b128 v[96:99], v57 offset:8320
	ds_read_b128 v[100:103], v57 offset:9344
	v_pk_add_f32 v[44:45], v[44:45], v[54:55]
	s_waitcnt lgkmcnt(0)
	v_pk_mov_b32 v[54:55], v[96:97], v[100:101] op_sel:[1,0]
	v_mov_b32_e32 v97, v101
	v_pk_mul_f32 v[96:97], v[156:157], v[96:97]
	s_nop 0
	v_pk_fma_f32 v[54:55], v[156:157], v[54:55], v[96:97] op_sel:[1,0,0] op_sel_hi:[0,1,1]
	v_mov_b32_e32 v96, v98
	v_mov_b32_e32 v97, v102
	v_pk_fma_f32 v[54:55], v[158:159], v[96:97], v[54:55] op_sel_hi:[0,1,1]
	v_mov_b32_e32 v102, v99
	v_pk_fma_f32 v[54:55], v[2:3], v[102:103], v[54:55] op_sel_hi:[0,1,1]
	ds_read_b128 v[96:99], v57 offset:10368
	ds_read_b128 v[100:103], v57 offset:11392
	v_pk_add_f32 v[10:11], v[10:11], v[54:55]
	s_waitcnt lgkmcnt(0)
	v_pk_mov_b32 v[54:55], v[96:97], v[100:101] op_sel:[1,0]
	v_mov_b32_e32 v97, v101
	v_pk_mul_f32 v[96:97], v[156:157], v[96:97]
	s_nop 0
	v_pk_fma_f32 v[54:55], v[156:157], v[54:55], v[96:97] op_sel:[1,0,0] op_sel_hi:[0,1,1]
	v_mov_b32_e32 v96, v98
	v_mov_b32_e32 v97, v102
	v_pk_fma_f32 v[54:55], v[158:159], v[96:97], v[54:55] op_sel_hi:[0,1,1]
	v_mov_b32_e32 v102, v99
	v_pk_fma_f32 v[54:55], v[2:3], v[102:103], v[54:55] op_sel_hi:[0,1,1]
	ds_read_b128 v[96:99], v57 offset:12416
	ds_read_b128 v[100:103], v57 offset:13440
	v_pk_add_f32 v[8:9], v[8:9], v[54:55]
	s_waitcnt lgkmcnt(0)
	v_pk_mov_b32 v[54:55], v[96:97], v[100:101] op_sel:[1,0]
	v_mov_b32_e32 v97, v101
	v_pk_mul_f32 v[96:97], v[156:157], v[96:97]
	s_nop 0
	v_pk_fma_f32 v[54:55], v[156:157], v[54:55], v[96:97] op_sel:[1,0,0] op_sel_hi:[0,1,1]
	v_mov_b32_e32 v96, v98
	v_mov_b32_e32 v97, v102
	v_pk_fma_f32 v[54:55], v[158:159], v[96:97], v[54:55] op_sel_hi:[0,1,1]
	v_mov_b32_e32 v102, v99
	v_pk_fma_f32 v[54:55], v[2:3], v[102:103], v[54:55] op_sel_hi:[0,1,1]
	ds_read_b128 v[96:99], v57 offset:14464
	ds_read_b128 v[100:103], v57 offset:15488
	v_pk_add_f32 v[6:7], v[6:7], v[54:55]
	s_waitcnt lgkmcnt(0)
	v_pk_mov_b32 v[54:55], v[96:97], v[100:101] op_sel:[1,0]
	v_mov_b32_e32 v97, v101
	v_pk_mul_f32 v[96:97], v[156:157], v[96:97]
	s_nop 0
	v_pk_fma_f32 v[54:55], v[156:157], v[54:55], v[96:97] op_sel:[1,0,0] op_sel_hi:[0,1,1]
	v_mov_b32_e32 v96, v98
	v_mov_b32_e32 v97, v102
	v_pk_fma_f32 v[54:55], v[158:159], v[96:97], v[54:55] op_sel_hi:[0,1,1]
	v_mov_b32_e32 v102, v99
	v_pk_fma_f32 v[54:55], v[2:3], v[102:103], v[54:55] op_sel_hi:[0,1,1]
	v_pk_add_f32 v[4:5], v[4:5], v[54:55]
	s_waitcnt vmcnt(6)
	ds_read_b128 v[96:99], v57 offset:144
	ds_read_b128 v[100:103], v57 offset:1168
	s_waitcnt lgkmcnt(0)
	v_pk_mov_b32 v[54:55], v[96:97], v[100:101] op_sel:[1,0]
	v_mov_b32_e32 v97, v101
	v_pk_mul_f32 v[96:97], v[160:161], v[96:97]
	s_nop 0
	v_pk_fma_f32 v[54:55], v[160:161], v[54:55], v[96:97] op_sel:[1,0,0] op_sel_hi:[0,1,1]
	v_mov_b32_e32 v96, v98
	v_mov_b32_e32 v97, v102
	v_pk_fma_f32 v[54:55], v[162:163], v[96:97], v[54:55] op_sel_hi:[0,1,1]
	v_mov_b32_e32 v2, v163
	v_mov_b32_e32 v102, v99
	v_pk_fma_f32 v[54:55], v[2:3], v[102:103], v[54:55] op_sel_hi:[0,1,1]
	ds_read_b128 v[96:99], v57 offset:2192
	ds_read_b128 v[100:103], v57 offset:3216
	v_pk_add_f32 v[52:53], v[52:53], v[54:55]
	s_waitcnt lgkmcnt(0)
; __device__ __forceinline__ void rwkv_fin_item(const Params& p, int l, int item, char* ldsraw) {
;     ...
;     for (int mq = 0; mq < 16; mq++) {
;       const f32x4 sv = *(const f32x4*)(sf + mq * 4);
; #pragma unroll
;       for (int t = 0; t < 16; t++) {
;         const f32x4 zv = *(const f32x4*)(zl + t * 256 + h * 64 + mq * 4);
;         yv[t] += sv[0] * zv[0] + sv[1] * zv[1] + sv[2] * zv[2] + sv[3] * zv[3];
;       }
	v_pk_mov_b32 v[54:55], v[96:97], v[100:101] op_sel:[1,0]
	v_mov_b32_e32 v97, v101
	v_pk_mul_f32 v[96:97], v[160:161], v[96:97]
	s_nop 0
	v_pk_fma_f32 v[54:55], v[160:161], v[54:55], v[96:97] op_sel:[1,0,0] op_sel_hi:[0,1,1]
	v_mov_b32_e32 v96, v98
	v_mov_b32_e32 v97, v102
	v_pk_fma_f32 v[54:55], v[162:163], v[96:97], v[54:55] op_sel_hi:[0,1,1]
	v_mov_b32_e32 v102, v99
	v_pk_fma_f32 v[54:55], v[2:3], v[102:103], v[54:55] op_sel_hi:[0,1,1]
	ds_read_b128 v[96:99], v57 offset:4240
	ds_read_b128 v[100:103], v57 offset:5264
	v_pk_add_f32 v[50:51], v[50:51], v[54:55]
	s_waitcnt lgkmcnt(0)
	v_pk_mov_b32 v[54:55], v[96:97], v[100:101] op_sel:[1,0]
	v_mov_b32_e32 v97, v101
	v_pk_mul_f32 v[96:97], v[160:161], v[96:97]
	s_nop 0
	v_pk_fma_f32 v[54:55], v[160:161], v[54:55], v[96:97] op_sel:[1,0,0] op_sel_hi:[0,1,1]
	v_mov_b32_e32 v96, v98
	v_mov_b32_e32 v97, v102
	v_pk_fma_f32 v[54:55], v[162:163], v[96:97], v[54:55] op_sel_hi:[0,1,1]
	v_mov_b32_e32 v102, v99
	v_pk_fma_f32 v[54:55], v[2:3], v[102:103], v[54:55] op_sel_hi:[0,1,1]
	ds_read_b128 v[96:99], v57 offset:6288
	ds_read_b128 v[100:103], v57 offset:7312
	v_pk_add_f32 v[46:47], v[46:47], v[54:55]
	s_waitcnt lgkmcnt(0)
	v_pk_mov_b32 v[54:55], v[96:97], v[100:101] op_sel:[1,0]
	v_mov_b32_e32 v97, v101
	v_pk_mul_f32 v[96:97], v[160:161], v[96:97]
	s_nop 0
	v_pk_fma_f32 v[54:55], v[160:161], v[54:55], v[96:97] op_sel:[1,0,0] op_sel_hi:[0,1,1]
	v_mov_b32_e32 v96, v98
	v_mov_b32_e32 v97, v102
	v_pk_fma_f32 v[54:55], v[162:163], v[96:97], v[54:55] op_sel_hi:[0,1,1]
	v_mov_b32_e32 v102, v99
	v_pk_fma_f32 v[54:55], v[2:3], v[102:103], v[54:55] op_sel_hi:[0,1,1]
	ds_read_b128 v[96:99], v57 offset:8336
	ds_read_b128 v[100:103], v57 offset:9360
	v_pk_add_f32 v[44:45], v[44:45], v[54:55]
	s_waitcnt lgkmcnt(0)
	v_pk_mov_b32 v[54:55], v[96:97], v[100:101] op_sel:[1,0]
	v_mov_b32_e32 v97, v101
	v_pk_mul_f32 v[96:97], v[160:161], v[96:97]
	s_nop 0
	v_pk_fma_f32 v[54:55], v[160:161], v[54:55], v[96:97] op_sel:[1,0,0] op_sel_hi:[0,1,1]
	v_mov_b32_e32 v96, v98
	v_mov_b32_e32 v97, v102
	v_pk_fma_f32 v[54:55], v[162:163], v[96:97], v[54:55] op_sel_hi:[0,1,1]
	v_mov_b32_e32 v102, v99
	v_pk_fma_f32 v[54:55], v[2:3], v[102:103], v[54:55] op_sel_hi:[0,1,1]
	ds_read_b128 v[96:99], v57 offset:10384
	ds_read_b128 v[100:103], v57 offset:11408
	v_pk_add_f32 v[10:11], v[10:11], v[54:55]
	s_waitcnt lgkmcnt(0)
	v_pk_mov_b32 v[54:55], v[96:97], v[100:101] op_sel:[1,0]
	v_mov_b32_e32 v97, v101
	v_pk_mul_f32 v[96:97], v[160:161], v[96:97]
	s_nop 0
	v_pk_fma_f32 v[54:55], v[160:161], v[54:55], v[96:97] op_sel:[1,0,0] op_sel_hi:[0,1,1]
	v_mov_b32_e32 v96, v98
	v_mov_b32_e32 v97, v102
	v_pk_fma_f32 v[54:55], v[162:163], v[96:97], v[54:55] op_sel_hi:[0,1,1]
	v_mov_b32_e32 v102, v99
	v_pk_fma_f32 v[54:55], v[2:3], v[102:103], v[54:55] op_sel_hi:[0,1,1]
	ds_read_b128 v[96:99], v57 offset:12432
	ds_read_b128 v[100:103], v57 offset:13456
	v_pk_add_f32 v[8:9], v[8:9], v[54:55]
	s_waitcnt lgkmcnt(0)
	v_pk_mov_b32 v[54:55], v[96:97], v[100:101] op_sel:[1,0]
	v_mov_b32_e32 v97, v101
	v_pk_mul_f32 v[96:97], v[160:161], v[96:97]
	s_nop 0
	v_pk_fma_f32 v[54:55], v[160:161], v[54:55], v[96:97] op_sel:[1,0,0] op_sel_hi:[0,1,1]
	v_mov_b32_e32 v96, v98
	v_mov_b32_e32 v97, v102
	v_pk_fma_f32 v[54:55], v[162:163], v[96:97], v[54:55] op_sel_hi:[0,1,1]
	v_mov_b32_e32 v102, v99
	v_pk_fma_f32 v[54:55], v[2:3], v[102:103], v[54:55] op_sel_hi:[0,1,1]
	ds_read_b128 v[96:99], v57 offset:14480
	ds_read_b128 v[100:103], v57 offset:15504
	v_pk_add_f32 v[6:7], v[6:7], v[54:55]
	s_waitcnt lgkmcnt(0)
	v_pk_mov_b32 v[54:55], v[96:97], v[100:101] op_sel:[1,0]
	v_mov_b32_e32 v97, v101
	v_pk_mul_f32 v[96:97], v[160:161], v[96:97]
	s_nop 0
	v_pk_fma_f32 v[54:55], v[160:161], v[54:55], v[96:97] op_sel:[1,0,0] op_sel_hi:[0,1,1]
	v_mov_b32_e32 v96, v98
	v_mov_b32_e32 v97, v102
	v_pk_fma_f32 v[54:55], v[162:163], v[96:97], v[54:55] op_sel_hi:[0,1,1]
	v_mov_b32_e32 v102, v99
	v_pk_fma_f32 v[54:55], v[2:3], v[102:103], v[54:55] op_sel_hi:[0,1,1]
	v_pk_add_f32 v[4:5], v[4:5], v[54:55]
	s_waitcnt vmcnt(5)
	ds_read_b128 v[96:99], v57 offset:160
	ds_read_b128 v[100:103], v57 offset:1184
	s_waitcnt lgkmcnt(0)
	v_pk_mov_b32 v[54:55], v[96:97], v[100:101] op_sel:[1,0]
	v_mov_b32_e32 v97, v101
	v_pk_mul_f32 v[96:97], v[164:165], v[96:97]
	s_nop 0
	v_pk_fma_f32 v[54:55], v[164:165], v[54:55], v[96:97] op_sel:[1,0,0] op_sel_hi:[0,1,1]
	v_mov_b32_e32 v96, v98
	v_mov_b32_e32 v97, v102
	v_pk_fma_f32 v[54:55], v[166:167], v[96:97], v[54:55] op_sel_hi:[0,1,1]
	v_mov_b32_e32 v2, v167
	v_mov_b32_e32 v102, v99
	v_pk_fma_f32 v[54:55], v[2:3], v[102:103], v[54:55] op_sel_hi:[0,1,1]
	ds_read_b128 v[96:99], v57 offset:2208
	ds_read_b128 v[100:103], v57 offset:3232
	v_pk_add_f32 v[52:53], v[52:53], v[54:55]
	s_waitcnt lgkmcnt(0)
	v_pk_mov_b32 v[54:55], v[96:97], v[100:101] op_sel:[1,0]
	v_mov_b32_e32 v97, v101
	v_pk_mul_f32 v[96:97], v[164:165], v[96:97]
	s_nop 0
	v_pk_fma_f32 v[54:55], v[164:165], v[54:55], v[96:97] op_sel:[1,0,0] op_sel_hi:[0,1,1]
	v_mov_b32_e32 v96, v98
	v_mov_b32_e32 v97, v102
	v_pk_fma_f32 v[54:55], v[166:167], v[96:97], v[54:55] op_sel_hi:[0,1,1]
	v_mov_b32_e32 v102, v99
	v_pk_fma_f32 v[54:55], v[2:3], v[102:103], v[54:55] op_sel_hi:[0,1,1]
	ds_read_b128 v[96:99], v57 offset:4256
	ds_read_b128 v[100:103], v57 offset:5280
	v_pk_add_f32 v[50:51], v[50:51], v[54:55]
	s_waitcnt lgkmcnt(0)
; __device__ __forceinline__ void rwkv_fin_item(const Params& p, int l, int item, char* ldsraw) {
;     ...
;     for (int mq = 0; mq < 16; mq++) {
;       const f32x4 sv = *(const f32x4*)(sf + mq * 4);
; #pragma unroll
;       for (int t = 0; t < 16; t++) {
;         const f32x4 zv = *(const f32x4*)(zl + t * 256 + h * 64 + mq * 4);
;         yv[t] += sv[0] * zv[0] + sv[1] * zv[1] + sv[2] * zv[2] + sv[3] * zv[3];
;       }
	v_pk_mov_b32 v[54:55], v[96:97], v[100:101] op_sel:[1,0]
	v_mov_b32_e32 v97, v101
	v_pk_mul_f32 v[96:97], v[164:165], v[96:97]
	s_nop 0
	v_pk_fma_f32 v[54:55], v[164:165], v[54:55], v[96:97] op_sel:[1,0,0] op_sel_hi:[0,1,1]
	v_mov_b32_e32 v96, v98
	v_mov_b32_e32 v97, v102
	v_pk_fma_f32 v[54:55], v[166:167], v[96:97], v[54:55] op_sel_hi:[0,1,1]
	v_mov_b32_e32 v102, v99
	v_pk_fma_f32 v[54:55], v[2:3], v[102:103], v[54:55] op_sel_hi:[0,1,1]
	ds_read_b128 v[96:99], v57 offset:6304
	ds_read_b128 v[100:103], v57 offset:7328
	v_pk_add_f32 v[46:47], v[46:47], v[54:55]
	s_waitcnt lgkmcnt(0)
	v_pk_mov_b32 v[54:55], v[96:97], v[100:101] op_sel:[1,0]
	v_mov_b32_e32 v97, v101
	v_pk_mul_f32 v[96:97], v[164:165], v[96:97]
	s_nop 0
	v_pk_fma_f32 v[54:55], v[164:165], v[54:55], v[96:97] op_sel:[1,0,0] op_sel_hi:[0,1,1]
	v_mov_b32_e32 v96, v98
	v_mov_b32_e32 v97, v102
	v_pk_fma_f32 v[54:55], v[166:167], v[96:97], v[54:55] op_sel_hi:[0,1,1]
	v_mov_b32_e32 v102, v99
	v_pk_fma_f32 v[54:55], v[2:3], v[102:103], v[54:55] op_sel_hi:[0,1,1]
	ds_read_b128 v[96:99], v57 offset:8352
	ds_read_b128 v[100:103], v57 offset:9376
	v_pk_add_f32 v[44:45], v[44:45], v[54:55]
	s_waitcnt lgkmcnt(0)
	v_pk_mov_b32 v[54:55], v[96:97], v[100:101] op_sel:[1,0]
	v_mov_b32_e32 v97, v101
	v_pk_mul_f32 v[96:97], v[164:165], v[96:97]
	s_nop 0
	v_pk_fma_f32 v[54:55], v[164:165], v[54:55], v[96:97] op_sel:[1,0,0] op_sel_hi:[0,1,1]
	v_mov_b32_e32 v96, v98
	v_mov_b32_e32 v97, v102
	v_pk_fma_f32 v[54:55], v[166:167], v[96:97], v[54:55] op_sel_hi:[0,1,1]
	v_mov_b32_e32 v102, v99
	v_pk_fma_f32 v[54:55], v[2:3], v[102:103], v[54:55] op_sel_hi:[0,1,1]
	ds_read_b128 v[96:99], v57 offset:10400
	ds_read_b128 v[100:103], v57 offset:11424
	v_pk_add_f32 v[10:11], v[10:11], v[54:55]
	s_waitcnt lgkmcnt(0)
	v_pk_mov_b32 v[54:55], v[96:97], v[100:101] op_sel:[1,0]
	v_mov_b32_e32 v97, v101
	v_pk_mul_f32 v[96:97], v[164:165], v[96:97]
	s_nop 0
	v_pk_fma_f32 v[54:55], v[164:165], v[54:55], v[96:97] op_sel:[1,0,0] op_sel_hi:[0,1,1]
	v_mov_b32_e32 v96, v98
	v_mov_b32_e32 v97, v102
	v_pk_fma_f32 v[54:55], v[166:167], v[96:97], v[54:55] op_sel_hi:[0,1,1]
	v_mov_b32_e32 v102, v99
	v_pk_fma_f32 v[54:55], v[2:3], v[102:103], v[54:55] op_sel_hi:[0,1,1]
	ds_read_b128 v[96:99], v57 offset:12448
	ds_read_b128 v[100:103], v57 offset:13472
	v_pk_add_f32 v[8:9], v[8:9], v[54:55]
	s_waitcnt lgkmcnt(0)
	v_pk_mov_b32 v[54:55], v[96:97], v[100:101] op_sel:[1,0]
	v_mov_b32_e32 v97, v101
	v_pk_mul_f32 v[96:97], v[164:165], v[96:97]
	s_nop 0
	v_pk_fma_f32 v[54:55], v[164:165], v[54:55], v[96:97] op_sel:[1,0,0] op_sel_hi:[0,1,1]
	v_mov_b32_e32 v96, v98
	v_mov_b32_e32 v97, v102
	v_pk_fma_f32 v[54:55], v[166:167], v[96:97], v[54:55] op_sel_hi:[0,1,1]
	v_mov_b32_e32 v102, v99
	v_pk_fma_f32 v[54:55], v[2:3], v[102:103], v[54:55] op_sel_hi:[0,1,1]
	ds_read_b128 v[96:99], v57 offset:14496
	ds_read_b128 v[100:103], v57 offset:15520
	v_pk_add_f32 v[6:7], v[6:7], v[54:55]
	s_waitcnt lgkmcnt(0)
	v_pk_mov_b32 v[54:55], v[96:97], v[100:101] op_sel:[1,0]
	v_mov_b32_e32 v97, v101
	v_pk_mul_f32 v[96:97], v[164:165], v[96:97]
	s_nop 0
	v_pk_fma_f32 v[54:55], v[164:165], v[54:55], v[96:97] op_sel:[1,0,0] op_sel_hi:[0,1,1]
	v_mov_b32_e32 v96, v98
	v_mov_b32_e32 v97, v102
	v_pk_fma_f32 v[54:55], v[166:167], v[96:97], v[54:55] op_sel_hi:[0,1,1]
	v_mov_b32_e32 v102, v99
	v_pk_fma_f32 v[54:55], v[2:3], v[102:103], v[54:55] op_sel_hi:[0,1,1]
	v_pk_add_f32 v[4:5], v[4:5], v[54:55]
	s_waitcnt vmcnt(4)
	ds_read_b128 v[96:99], v57 offset:176
	ds_read_b128 v[100:103], v57 offset:1200
	s_waitcnt lgkmcnt(0)
	v_pk_mov_b32 v[54:55], v[96:97], v[100:101] op_sel:[1,0]
	v_mov_b32_e32 v97, v101
	v_pk_mul_f32 v[96:97], v[168:169], v[96:97]
	s_nop 0
	v_pk_fma_f32 v[54:55], v[168:169], v[54:55], v[96:97] op_sel:[1,0,0] op_sel_hi:[0,1,1]
	v_mov_b32_e32 v96, v98
	v_mov_b32_e32 v97, v102
	v_pk_fma_f32 v[54:55], v[170:171], v[96:97], v[54:55] op_sel_hi:[0,1,1]
	v_mov_b32_e32 v2, v171
	v_mov_b32_e32 v102, v99
	v_pk_fma_f32 v[54:55], v[2:3], v[102:103], v[54:55] op_sel_hi:[0,1,1]
	ds_read_b128 v[96:99], v57 offset:2224
	ds_read_b128 v[100:103], v57 offset:3248
	v_pk_add_f32 v[52:53], v[52:53], v[54:55]
	s_waitcnt lgkmcnt(0)
	v_pk_mov_b32 v[54:55], v[96:97], v[100:101] op_sel:[1,0]
	v_mov_b32_e32 v97, v101
	v_pk_mul_f32 v[96:97], v[168:169], v[96:97]
	s_nop 0
	v_pk_fma_f32 v[54:55], v[168:169], v[54:55], v[96:97] op_sel:[1,0,0] op_sel_hi:[0,1,1]
	v_mov_b32_e32 v96, v98
	v_mov_b32_e32 v97, v102
	v_pk_fma_f32 v[54:55], v[170:171], v[96:97], v[54:55] op_sel_hi:[0,1,1]
	v_mov_b32_e32 v102, v99
	v_pk_fma_f32 v[54:55], v[2:3], v[102:103], v[54:55] op_sel_hi:[0,1,1]
	ds_read_b128 v[96:99], v57 offset:4272
	ds_read_b128 v[100:103], v57 offset:5296
	v_pk_add_f32 v[50:51], v[50:51], v[54:55]
	s_waitcnt lgkmcnt(0)
	v_pk_mov_b32 v[54:55], v[96:97], v[100:101] op_sel:[1,0]
	v_mov_b32_e32 v97, v101
	v_pk_mul_f32 v[96:97], v[168:169], v[96:97]
	s_nop 0
	v_pk_fma_f32 v[54:55], v[168:169], v[54:55], v[96:97] op_sel:[1,0,0] op_sel_hi:[0,1,1]
	v_mov_b32_e32 v96, v98
	v_mov_b32_e32 v97, v102
	v_pk_fma_f32 v[54:55], v[170:171], v[96:97], v[54:55] op_sel_hi:[0,1,1]
	v_mov_b32_e32 v102, v99
	v_pk_fma_f32 v[54:55], v[2:3], v[102:103], v[54:55] op_sel_hi:[0,1,1]
	ds_read_b128 v[96:99], v57 offset:6320
	ds_read_b128 v[100:103], v57 offset:7344
	v_pk_add_f32 v[46:47], v[46:47], v[54:55]
	s_waitcnt lgkmcnt(0)
; __device__ __forceinline__ void rwkv_fin_item(const Params& p, int l, int item, char* ldsraw) {
;     ...
;     for (int mq = 0; mq < 16; mq++) {
;       const f32x4 sv = *(const f32x4*)(sf + mq * 4);
; #pragma unroll
;       for (int t = 0; t < 16; t++) {
;         const f32x4 zv = *(const f32x4*)(zl + t * 256 + h * 64 + mq * 4);
;         yv[t] += sv[0] * zv[0] + sv[1] * zv[1] + sv[2] * zv[2] + sv[3] * zv[3];
;       }
	v_pk_mov_b32 v[54:55], v[96:97], v[100:101] op_sel:[1,0]
	v_mov_b32_e32 v97, v101
	v_pk_mul_f32 v[96:97], v[168:169], v[96:97]
	s_nop 0
	v_pk_fma_f32 v[54:55], v[168:169], v[54:55], v[96:97] op_sel:[1,0,0] op_sel_hi:[0,1,1]
	v_mov_b32_e32 v96, v98
	v_mov_b32_e32 v97, v102
	v_pk_fma_f32 v[54:55], v[170:171], v[96:97], v[54:55] op_sel_hi:[0,1,1]
	v_mov_b32_e32 v102, v99
	v_pk_fma_f32 v[54:55], v[2:3], v[102:103], v[54:55] op_sel_hi:[0,1,1]
	ds_read_b128 v[96:99], v57 offset:8368
	ds_read_b128 v[100:103], v57 offset:9392
	v_pk_add_f32 v[44:45], v[44:45], v[54:55]
	s_waitcnt lgkmcnt(0)
	v_pk_mov_b32 v[54:55], v[96:97], v[100:101] op_sel:[1,0]
	v_mov_b32_e32 v97, v101
	v_pk_mul_f32 v[96:97], v[168:169], v[96:97]
	s_nop 0
	v_pk_fma_f32 v[54:55], v[168:169], v[54:55], v[96:97] op_sel:[1,0,0] op_sel_hi:[0,1,1]
	v_mov_b32_e32 v96, v98
	v_mov_b32_e32 v97, v102
	v_pk_fma_f32 v[54:55], v[170:171], v[96:97], v[54:55] op_sel_hi:[0,1,1]
	v_mov_b32_e32 v102, v99
	v_pk_fma_f32 v[54:55], v[2:3], v[102:103], v[54:55] op_sel_hi:[0,1,1]
	ds_read_b128 v[96:99], v57 offset:10416
	ds_read_b128 v[100:103], v57 offset:11440
	v_pk_add_f32 v[10:11], v[10:11], v[54:55]
	s_waitcnt lgkmcnt(0)
	v_pk_mov_b32 v[54:55], v[96:97], v[100:101] op_sel:[1,0]
	v_mov_b32_e32 v97, v101
	v_pk_mul_f32 v[96:97], v[168:169], v[96:97]
	s_nop 0
	v_pk_fma_f32 v[54:55], v[168:169], v[54:55], v[96:97] op_sel:[1,0,0] op_sel_hi:[0,1,1]
	v_mov_b32_e32 v96, v98
	v_mov_b32_e32 v97, v102
	v_pk_fma_f32 v[54:55], v[170:171], v[96:97], v[54:55] op_sel_hi:[0,1,1]
	v_mov_b32_e32 v102, v99
	v_pk_fma_f32 v[54:55], v[2:3], v[102:103], v[54:55] op_sel_hi:[0,1,1]
	ds_read_b128 v[96:99], v57 offset:12464
	ds_read_b128 v[100:103], v57 offset:13488
	v_pk_add_f32 v[8:9], v[8:9], v[54:55]
	s_waitcnt lgkmcnt(0)
	v_pk_mov_b32 v[54:55], v[96:97], v[100:101] op_sel:[1,0]
	v_mov_b32_e32 v97, v101
	v_pk_mul_f32 v[96:97], v[168:169], v[96:97]
	s_nop 0
	v_pk_fma_f32 v[54:55], v[168:169], v[54:55], v[96:97] op_sel:[1,0,0] op_sel_hi:[0,1,1]
	v_mov_b32_e32 v96, v98
	v_mov_b32_e32 v97, v102
	v_pk_fma_f32 v[54:55], v[170:171], v[96:97], v[54:55] op_sel_hi:[0,1,1]
	v_mov_b32_e32 v102, v99
	v_pk_fma_f32 v[54:55], v[2:3], v[102:103], v[54:55] op_sel_hi:[0,1,1]
	ds_read_b128 v[96:99], v57 offset:14512
	ds_read_b128 v[100:103], v57 offset:15536
	v_pk_add_f32 v[6:7], v[6:7], v[54:55]
	s_waitcnt lgkmcnt(0)
	v_pk_mov_b32 v[54:55], v[96:97], v[100:101] op_sel:[1,0]
	v_mov_b32_e32 v97, v101
	v_pk_mul_f32 v[96:97], v[168:169], v[96:97]
	s_nop 0
	v_pk_fma_f32 v[54:55], v[168:169], v[54:55], v[96:97] op_sel:[1,0,0] op_sel_hi:[0,1,1]
	v_mov_b32_e32 v96, v98
	v_mov_b32_e32 v97, v102
	v_pk_fma_f32 v[54:55], v[170:171], v[96:97], v[54:55] op_sel_hi:[0,1,1]
	v_mov_b32_e32 v102, v99
	v_pk_fma_f32 v[54:55], v[2:3], v[102:103], v[54:55] op_sel_hi:[0,1,1]
	v_pk_add_f32 v[4:5], v[4:5], v[54:55]
	s_waitcnt vmcnt(3)
	ds_read_b128 v[96:99], v57 offset:192
	ds_read_b128 v[100:103], v57 offset:1216
	s_waitcnt lgkmcnt(0)
	v_pk_mov_b32 v[54:55], v[96:97], v[100:101] op_sel:[1,0]
	v_mov_b32_e32 v97, v101
	v_pk_mul_f32 v[96:97], v[172:173], v[96:97]
	s_nop 0
	v_pk_fma_f32 v[54:55], v[172:173], v[54:55], v[96:97] op_sel:[1,0,0] op_sel_hi:[0,1,1]
	v_mov_b32_e32 v96, v98
	v_mov_b32_e32 v97, v102
	v_pk_fma_f32 v[54:55], v[174:175], v[96:97], v[54:55] op_sel_hi:[0,1,1]
	v_mov_b32_e32 v2, v175
	v_mov_b32_e32 v102, v99
	v_pk_fma_f32 v[54:55], v[2:3], v[102:103], v[54:55] op_sel_hi:[0,1,1]
	ds_read_b128 v[96:99], v57 offset:2240
	ds_read_b128 v[100:103], v57 offset:3264
	v_pk_add_f32 v[52:53], v[52:53], v[54:55]
	s_waitcnt lgkmcnt(0)
	v_pk_mov_b32 v[54:55], v[96:97], v[100:101] op_sel:[1,0]
	v_mov_b32_e32 v97, v101
	v_pk_mul_f32 v[96:97], v[172:173], v[96:97]
	s_nop 0
	v_pk_fma_f32 v[54:55], v[172:173], v[54:55], v[96:97] op_sel:[1,0,0] op_sel_hi:[0,1,1]
	v_mov_b32_e32 v96, v98
	v_mov_b32_e32 v97, v102
	v_pk_fma_f32 v[54:55], v[174:175], v[96:97], v[54:55] op_sel_hi:[0,1,1]
	v_mov_b32_e32 v102, v99
	v_pk_fma_f32 v[54:55], v[2:3], v[102:103], v[54:55] op_sel_hi:[0,1,1]
	ds_read_b128 v[96:99], v57 offset:4288
	ds_read_b128 v[100:103], v57 offset:5312
	v_pk_add_f32 v[50:51], v[50:51], v[54:55]
	s_waitcnt lgkmcnt(0)
	v_pk_mov_b32 v[54:55], v[96:97], v[100:101] op_sel:[1,0]
	v_mov_b32_e32 v97, v101
	v_pk_mul_f32 v[96:97], v[172:173], v[96:97]
	s_nop 0
	v_pk_fma_f32 v[54:55], v[172:173], v[54:55], v[96:97] op_sel:[1,0,0] op_sel_hi:[0,1,1]
	v_mov_b32_e32 v96, v98
	v_mov_b32_e32 v97, v102
	v_pk_fma_f32 v[54:55], v[174:175], v[96:97], v[54:55] op_sel_hi:[0,1,1]
	v_mov_b32_e32 v102, v99
	v_pk_fma_f32 v[54:55], v[2:3], v[102:103], v[54:55] op_sel_hi:[0,1,1]
	ds_read_b128 v[96:99], v57 offset:6336
	ds_read_b128 v[100:103], v57 offset:7360
	v_pk_add_f32 v[46:47], v[46:47], v[54:55]
	s_waitcnt lgkmcnt(0)
	v_pk_mov_b32 v[54:55], v[96:97], v[100:101] op_sel:[1,0]
	v_mov_b32_e32 v97, v101
	v_pk_mul_f32 v[96:97], v[172:173], v[96:97]
	s_nop 0
	v_pk_fma_f32 v[54:55], v[172:173], v[54:55], v[96:97] op_sel:[1,0,0] op_sel_hi:[0,1,1]
	v_mov_b32_e32 v96, v98
	v_mov_b32_e32 v97, v102
	v_pk_fma_f32 v[54:55], v[174:175], v[96:97], v[54:55] op_sel_hi:[0,1,1]
	v_mov_b32_e32 v102, v99
	v_pk_fma_f32 v[54:55], v[2:3], v[102:103], v[54:55] op_sel_hi:[0,1,1]
	ds_read_b128 v[96:99], v57 offset:8384
	ds_read_b128 v[100:103], v57 offset:9408
	v_pk_add_f32 v[44:45], v[44:45], v[54:55]
	s_waitcnt lgkmcnt(0)
; __device__ __forceinline__ void rwkv_fin_item(const Params& p, int l, int item, char* ldsraw) {
;     ...
;     for (int mq = 0; mq < 16; mq++) {
;       const f32x4 sv = *(const f32x4*)(sf + mq * 4);
; #pragma unroll
;       for (int t = 0; t < 16; t++) {
;         const f32x4 zv = *(const f32x4*)(zl + t * 256 + h * 64 + mq * 4);
;         yv[t] += sv[0] * zv[0] + sv[1] * zv[1] + sv[2] * zv[2] + sv[3] * zv[3];
;       }
	v_pk_mov_b32 v[54:55], v[96:97], v[100:101] op_sel:[1,0]
	v_mov_b32_e32 v97, v101
	v_pk_mul_f32 v[96:97], v[172:173], v[96:97]
	s_nop 0
	v_pk_fma_f32 v[54:55], v[172:173], v[54:55], v[96:97] op_sel:[1,0,0] op_sel_hi:[0,1,1]
	v_mov_b32_e32 v96, v98
	v_mov_b32_e32 v97, v102
	v_pk_fma_f32 v[54:55], v[174:175], v[96:97], v[54:55] op_sel_hi:[0,1,1]
	v_mov_b32_e32 v102, v99
	v_pk_fma_f32 v[54:55], v[2:3], v[102:103], v[54:55] op_sel_hi:[0,1,1]
	ds_read_b128 v[96:99], v57 offset:10432
	ds_read_b128 v[100:103], v57 offset:11456
	v_pk_add_f32 v[10:11], v[10:11], v[54:55]
	s_waitcnt lgkmcnt(0)
	v_pk_mov_b32 v[54:55], v[96:97], v[100:101] op_sel:[1,0]
	v_mov_b32_e32 v97, v101
	v_pk_mul_f32 v[96:97], v[172:173], v[96:97]
	s_nop 0
	v_pk_fma_f32 v[54:55], v[172:173], v[54:55], v[96:97] op_sel:[1,0,0] op_sel_hi:[0,1,1]
	v_mov_b32_e32 v96, v98
	v_mov_b32_e32 v97, v102
	v_pk_fma_f32 v[54:55], v[174:175], v[96:97], v[54:55] op_sel_hi:[0,1,1]
	v_mov_b32_e32 v102, v99
	v_pk_fma_f32 v[54:55], v[2:3], v[102:103], v[54:55] op_sel_hi:[0,1,1]
	ds_read_b128 v[96:99], v57 offset:12480
	ds_read_b128 v[100:103], v57 offset:13504
	v_pk_add_f32 v[8:9], v[8:9], v[54:55]
	s_waitcnt lgkmcnt(0)
	v_pk_mov_b32 v[54:55], v[96:97], v[100:101] op_sel:[1,0]
	v_mov_b32_e32 v97, v101
	v_pk_mul_f32 v[96:97], v[172:173], v[96:97]
	s_nop 0
	v_pk_fma_f32 v[54:55], v[172:173], v[54:55], v[96:97] op_sel:[1,0,0] op_sel_hi:[0,1,1]
	v_mov_b32_e32 v96, v98
	v_mov_b32_e32 v97, v102
	v_pk_fma_f32 v[54:55], v[174:175], v[96:97], v[54:55] op_sel_hi:[0,1,1]
	v_mov_b32_e32 v102, v99
	v_pk_fma_f32 v[54:55], v[2:3], v[102:103], v[54:55] op_sel_hi:[0,1,1]
	ds_read_b128 v[96:99], v57 offset:14528
	ds_read_b128 v[100:103], v57 offset:15552
	v_pk_add_f32 v[6:7], v[6:7], v[54:55]
	s_waitcnt lgkmcnt(0)
	v_pk_mov_b32 v[54:55], v[96:97], v[100:101] op_sel:[1,0]
	v_mov_b32_e32 v97, v101
	v_pk_mul_f32 v[96:97], v[172:173], v[96:97]
	s_nop 0
	v_pk_fma_f32 v[54:55], v[172:173], v[54:55], v[96:97] op_sel:[1,0,0] op_sel_hi:[0,1,1]
	v_mov_b32_e32 v96, v98
	v_mov_b32_e32 v97, v102
	v_pk_fma_f32 v[54:55], v[174:175], v[96:97], v[54:55] op_sel_hi:[0,1,1]
	v_mov_b32_e32 v102, v99
	v_pk_fma_f32 v[54:55], v[2:3], v[102:103], v[54:55] op_sel_hi:[0,1,1]
	v_pk_add_f32 v[4:5], v[4:5], v[54:55]
	s_waitcnt vmcnt(2)
	ds_read_b128 v[96:99], v57 offset:208
	ds_read_b128 v[100:103], v57 offset:1232
	s_waitcnt lgkmcnt(0)
	v_pk_mov_b32 v[54:55], v[96:97], v[100:101] op_sel:[1,0]
	v_mov_b32_e32 v97, v101
	v_pk_mul_f32 v[96:97], v[176:177], v[96:97]
	s_nop 0
	v_pk_fma_f32 v[54:55], v[176:177], v[54:55], v[96:97] op_sel:[1,0,0] op_sel_hi:[0,1,1]
	v_mov_b32_e32 v96, v98
	v_mov_b32_e32 v97, v102
	v_pk_fma_f32 v[54:55], v[178:179], v[96:97], v[54:55] op_sel_hi:[0,1,1]
	v_mov_b32_e32 v2, v179
	v_mov_b32_e32 v102, v99
	v_pk_fma_f32 v[54:55], v[2:3], v[102:103], v[54:55] op_sel_hi:[0,1,1]
	ds_read_b128 v[96:99], v57 offset:2256
	ds_read_b128 v[100:103], v57 offset:3280
	v_pk_add_f32 v[52:53], v[52:53], v[54:55]
	s_waitcnt lgkmcnt(0)
	v_pk_mov_b32 v[54:55], v[96:97], v[100:101] op_sel:[1,0]
	v_mov_b32_e32 v97, v101
	v_pk_mul_f32 v[96:97], v[176:177], v[96:97]
	s_nop 0
	v_pk_fma_f32 v[54:55], v[176:177], v[54:55], v[96:97] op_sel:[1,0,0] op_sel_hi:[0,1,1]
	v_mov_b32_e32 v96, v98
	v_mov_b32_e32 v97, v102
	v_pk_fma_f32 v[54:55], v[178:179], v[96:97], v[54:55] op_sel_hi:[0,1,1]
	v_mov_b32_e32 v102, v99
	v_pk_fma_f32 v[54:55], v[2:3], v[102:103], v[54:55] op_sel_hi:[0,1,1]
	ds_read_b128 v[96:99], v57 offset:4304
	ds_read_b128 v[100:103], v57 offset:5328
	v_pk_add_f32 v[50:51], v[50:51], v[54:55]
	s_waitcnt lgkmcnt(0)
	v_pk_mov_b32 v[54:55], v[96:97], v[100:101] op_sel:[1,0]
	v_mov_b32_e32 v97, v101
	v_pk_mul_f32 v[96:97], v[176:177], v[96:97]
	s_nop 0
	v_pk_fma_f32 v[54:55], v[176:177], v[54:55], v[96:97] op_sel:[1,0,0] op_sel_hi:[0,1,1]
	v_mov_b32_e32 v96, v98
	v_mov_b32_e32 v97, v102
	v_pk_fma_f32 v[54:55], v[178:179], v[96:97], v[54:55] op_sel_hi:[0,1,1]
	v_mov_b32_e32 v102, v99
	v_pk_fma_f32 v[54:55], v[2:3], v[102:103], v[54:55] op_sel_hi:[0,1,1]
	ds_read_b128 v[96:99], v57 offset:6352
	ds_read_b128 v[100:103], v57 offset:7376
	v_pk_add_f32 v[46:47], v[46:47], v[54:55]
	s_waitcnt lgkmcnt(0)
	v_pk_mov_b32 v[54:55], v[96:97], v[100:101] op_sel:[1,0]
	v_mov_b32_e32 v97, v101
	v_pk_mul_f32 v[96:97], v[176:177], v[96:97]
	s_nop 0
	v_pk_fma_f32 v[54:55], v[176:177], v[54:55], v[96:97] op_sel:[1,0,0] op_sel_hi:[0,1,1]
	v_mov_b32_e32 v96, v98
	v_mov_b32_e32 v97, v102
	v_pk_fma_f32 v[54:55], v[178:179], v[96:97], v[54:55] op_sel_hi:[0,1,1]
	v_mov_b32_e32 v102, v99
	v_pk_fma_f32 v[54:55], v[2:3], v[102:103], v[54:55] op_sel_hi:[0,1,1]
	ds_read_b128 v[96:99], v57 offset:8400
	ds_read_b128 v[100:103], v57 offset:9424
	v_pk_add_f32 v[44:45], v[44:45], v[54:55]
	s_waitcnt lgkmcnt(0)
	v_pk_mov_b32 v[54:55], v[96:97], v[100:101] op_sel:[1,0]
	v_mov_b32_e32 v97, v101
	v_pk_mul_f32 v[96:97], v[176:177], v[96:97]
	s_nop 0
	v_pk_fma_f32 v[54:55], v[176:177], v[54:55], v[96:97] op_sel:[1,0,0] op_sel_hi:[0,1,1]
	v_mov_b32_e32 v96, v98
	v_mov_b32_e32 v97, v102
	v_pk_fma_f32 v[54:55], v[178:179], v[96:97], v[54:55] op_sel_hi:[0,1,1]
	v_mov_b32_e32 v102, v99
	v_pk_fma_f32 v[54:55], v[2:3], v[102:103], v[54:55] op_sel_hi:[0,1,1]
	ds_read_b128 v[96:99], v57 offset:10448
	ds_read_b128 v[100:103], v57 offset:11472
	v_pk_add_f32 v[10:11], v[10:11], v[54:55]
	s_waitcnt lgkmcnt(0)
; __device__ __forceinline__ void rwkv_fin_item(const Params& p, int l, int item, char* ldsraw) {
;     ...
;     for (int mq = 0; mq < 16; mq++) {
;       const f32x4 sv = *(const f32x4*)(sf + mq * 4);
; #pragma unroll
;       for (int t = 0; t < 16; t++) {
;         const f32x4 zv = *(const f32x4*)(zl + t * 256 + h * 64 + mq * 4);
;         yv[t] += sv[0] * zv[0] + sv[1] * zv[1] + sv[2] * zv[2] + sv[3] * zv[3];
;       }
	v_pk_mov_b32 v[54:55], v[96:97], v[100:101] op_sel:[1,0]
	v_mov_b32_e32 v97, v101
	v_pk_mul_f32 v[96:97], v[176:177], v[96:97]
	s_nop 0
	v_pk_fma_f32 v[54:55], v[176:177], v[54:55], v[96:97] op_sel:[1,0,0] op_sel_hi:[0,1,1]
	v_mov_b32_e32 v96, v98
	v_mov_b32_e32 v97, v102
	v_pk_fma_f32 v[54:55], v[178:179], v[96:97], v[54:55] op_sel_hi:[0,1,1]
	v_mov_b32_e32 v102, v99
	v_pk_fma_f32 v[54:55], v[2:3], v[102:103], v[54:55] op_sel_hi:[0,1,1]
	ds_read_b128 v[96:99], v57 offset:12496
	ds_read_b128 v[100:103], v57 offset:13520
	v_pk_add_f32 v[8:9], v[8:9], v[54:55]
	s_waitcnt lgkmcnt(0)
	v_pk_mov_b32 v[54:55], v[96:97], v[100:101] op_sel:[1,0]
	v_mov_b32_e32 v97, v101
	v_pk_mul_f32 v[96:97], v[176:177], v[96:97]
	s_nop 0
	v_pk_fma_f32 v[54:55], v[176:177], v[54:55], v[96:97] op_sel:[1,0,0] op_sel_hi:[0,1,1]
	v_mov_b32_e32 v96, v98
	v_mov_b32_e32 v97, v102
	v_pk_fma_f32 v[54:55], v[178:179], v[96:97], v[54:55] op_sel_hi:[0,1,1]
	v_mov_b32_e32 v102, v99
	v_pk_fma_f32 v[54:55], v[2:3], v[102:103], v[54:55] op_sel_hi:[0,1,1]
	ds_read_b128 v[96:99], v57 offset:14544
	ds_read_b128 v[100:103], v57 offset:15568
	v_pk_add_f32 v[6:7], v[6:7], v[54:55]
	s_waitcnt lgkmcnt(0)
	v_pk_mov_b32 v[54:55], v[96:97], v[100:101] op_sel:[1,0]
	v_mov_b32_e32 v97, v101
	v_pk_mul_f32 v[96:97], v[176:177], v[96:97]
	s_nop 0
	v_pk_fma_f32 v[54:55], v[176:177], v[54:55], v[96:97] op_sel:[1,0,0] op_sel_hi:[0,1,1]
	v_mov_b32_e32 v96, v98
	v_mov_b32_e32 v97, v102
	v_pk_fma_f32 v[54:55], v[178:179], v[96:97], v[54:55] op_sel_hi:[0,1,1]
	v_mov_b32_e32 v102, v99
	v_pk_fma_f32 v[54:55], v[2:3], v[102:103], v[54:55] op_sel_hi:[0,1,1]
	v_pk_add_f32 v[4:5], v[4:5], v[54:55]
	s_waitcnt vmcnt(1)
	ds_read_b128 v[96:99], v57 offset:224
	ds_read_b128 v[100:103], v57 offset:1248
	s_waitcnt lgkmcnt(0)
	v_pk_mov_b32 v[54:55], v[96:97], v[100:101] op_sel:[1,0]
	v_mov_b32_e32 v97, v101
	v_pk_mul_f32 v[96:97], v[180:181], v[96:97]
	s_nop 0
	v_pk_fma_f32 v[54:55], v[180:181], v[54:55], v[96:97] op_sel:[1,0,0] op_sel_hi:[0,1,1]
	v_mov_b32_e32 v96, v98
	v_mov_b32_e32 v97, v102
	v_pk_fma_f32 v[54:55], v[182:183], v[96:97], v[54:55] op_sel_hi:[0,1,1]
	v_mov_b32_e32 v2, v183
	v_mov_b32_e32 v102, v99
	v_pk_fma_f32 v[54:55], v[2:3], v[102:103], v[54:55] op_sel_hi:[0,1,1]
	ds_read_b128 v[96:99], v57 offset:2272
	ds_read_b128 v[100:103], v57 offset:3296
	v_pk_add_f32 v[52:53], v[52:53], v[54:55]
	s_waitcnt lgkmcnt(0)
	v_pk_mov_b32 v[54:55], v[96:97], v[100:101] op_sel:[1,0]
	v_mov_b32_e32 v97, v101
	v_pk_mul_f32 v[96:97], v[180:181], v[96:97]
	s_nop 0
	v_pk_fma_f32 v[54:55], v[180:181], v[54:55], v[96:97] op_sel:[1,0,0] op_sel_hi:[0,1,1]
	v_mov_b32_e32 v96, v98
	v_mov_b32_e32 v97, v102
	v_pk_fma_f32 v[54:55], v[182:183], v[96:97], v[54:55] op_sel_hi:[0,1,1]
	v_mov_b32_e32 v102, v99
	v_pk_fma_f32 v[54:55], v[2:3], v[102:103], v[54:55] op_sel_hi:[0,1,1]
	ds_read_b128 v[96:99], v57 offset:4320
	ds_read_b128 v[100:103], v57 offset:5344
	v_pk_add_f32 v[50:51], v[50:51], v[54:55]
	s_waitcnt lgkmcnt(0)
	v_pk_mov_b32 v[54:55], v[96:97], v[100:101] op_sel:[1,0]
	v_mov_b32_e32 v97, v101
	v_pk_mul_f32 v[96:97], v[180:181], v[96:97]
	s_nop 0
	v_pk_fma_f32 v[54:55], v[180:181], v[54:55], v[96:97] op_sel:[1,0,0] op_sel_hi:[0,1,1]
	v_mov_b32_e32 v96, v98
	v_mov_b32_e32 v97, v102
	v_pk_fma_f32 v[54:55], v[182:183], v[96:97], v[54:55] op_sel_hi:[0,1,1]
	v_mov_b32_e32 v102, v99
	v_pk_fma_f32 v[54:55], v[2:3], v[102:103], v[54:55] op_sel_hi:[0,1,1]
	ds_read_b128 v[96:99], v57 offset:6368
	ds_read_b128 v[100:103], v57 offset:7392
	v_pk_add_f32 v[46:47], v[46:47], v[54:55]
	s_waitcnt lgkmcnt(0)
	v_pk_mov_b32 v[54:55], v[96:97], v[100:101] op_sel:[1,0]
	v_mov_b32_e32 v97, v101
	v_pk_mul_f32 v[96:97], v[180:181], v[96:97]
	s_nop 0
	v_pk_fma_f32 v[54:55], v[180:181], v[54:55], v[96:97] op_sel:[1,0,0] op_sel_hi:[0,1,1]
	v_mov_b32_e32 v96, v98
	v_mov_b32_e32 v97, v102
	v_pk_fma_f32 v[54:55], v[182:183], v[96:97], v[54:55] op_sel_hi:[0,1,1]
	v_mov_b32_e32 v102, v99
	v_pk_fma_f32 v[54:55], v[2:3], v[102:103], v[54:55] op_sel_hi:[0,1,1]
	ds_read_b128 v[96:99], v57 offset:8416
	ds_read_b128 v[100:103], v57 offset:9440
	v_pk_add_f32 v[44:45], v[44:45], v[54:55]
	s_waitcnt lgkmcnt(0)
	v_pk_mov_b32 v[54:55], v[96:97], v[100:101] op_sel:[1,0]
	v_mov_b32_e32 v97, v101
	v_pk_mul_f32 v[96:97], v[180:181], v[96:97]
	s_nop 0
	v_pk_fma_f32 v[54:55], v[180:181], v[54:55], v[96:97] op_sel:[1,0,0] op_sel_hi:[0,1,1]
	v_mov_b32_e32 v96, v98
	v_mov_b32_e32 v97, v102
	v_pk_fma_f32 v[54:55], v[182:183], v[96:97], v[54:55] op_sel_hi:[0,1,1]
	v_mov_b32_e32 v102, v99
	v_pk_fma_f32 v[54:55], v[2:3], v[102:103], v[54:55] op_sel_hi:[0,1,1]
	ds_read_b128 v[96:99], v57 offset:10464
	ds_read_b128 v[100:103], v57 offset:11488
	v_pk_add_f32 v[10:11], v[10:11], v[54:55]
	s_waitcnt lgkmcnt(0)
	v_pk_mov_b32 v[54:55], v[96:97], v[100:101] op_sel:[1,0]
	v_mov_b32_e32 v97, v101
	v_pk_mul_f32 v[96:97], v[180:181], v[96:97]
	s_nop 0
	v_pk_fma_f32 v[54:55], v[180:181], v[54:55], v[96:97] op_sel:[1,0,0] op_sel_hi:[0,1,1]
	v_mov_b32_e32 v96, v98
	v_mov_b32_e32 v97, v102
	v_pk_fma_f32 v[54:55], v[182:183], v[96:97], v[54:55] op_sel_hi:[0,1,1]
	v_mov_b32_e32 v102, v99
	v_pk_fma_f32 v[54:55], v[2:3], v[102:103], v[54:55] op_sel_hi:[0,1,1]
	ds_read_b128 v[96:99], v57 offset:12512
	ds_read_b128 v[100:103], v57 offset:13536
	v_pk_add_f32 v[8:9], v[8:9], v[54:55]
	s_waitcnt lgkmcnt(0)
; __device__ __forceinline__ void rwkv_fin_item(const Params& p, int l, int item, char* ldsraw) {
;     ...
;     for (int mq = 0; mq < 16; mq++) {
;       const f32x4 sv = *(const f32x4*)(sf + mq * 4);
; #pragma unroll
;       for (int t = 0; t < 16; t++) {
;         const f32x4 zv = *(const f32x4*)(zl + t * 256 + h * 64 + mq * 4);
;         yv[t] += sv[0] * zv[0] + sv[1] * zv[1] + sv[2] * zv[2] + sv[3] * zv[3];
;       }
	v_pk_mov_b32 v[54:55], v[96:97], v[100:101] op_sel:[1,0]
	v_mov_b32_e32 v97, v101
	v_pk_mul_f32 v[96:97], v[180:181], v[96:97]
	s_nop 0
	v_pk_fma_f32 v[54:55], v[180:181], v[54:55], v[96:97] op_sel:[1,0,0] op_sel_hi:[0,1,1]
	v_mov_b32_e32 v96, v98
	v_mov_b32_e32 v97, v102
	v_pk_fma_f32 v[54:55], v[182:183], v[96:97], v[54:55] op_sel_hi:[0,1,1]
	v_mov_b32_e32 v102, v99
	v_pk_fma_f32 v[54:55], v[2:3], v[102:103], v[54:55] op_sel_hi:[0,1,1]
	ds_read_b128 v[96:99], v57 offset:14560
	ds_read_b128 v[100:103], v57 offset:15584
	v_pk_add_f32 v[6:7], v[6:7], v[54:55]
	s_waitcnt lgkmcnt(0)
	v_pk_mov_b32 v[54:55], v[96:97], v[100:101] op_sel:[1,0]
	v_mov_b32_e32 v97, v101
	v_pk_mul_f32 v[96:97], v[180:181], v[96:97]
	s_nop 0
	v_pk_fma_f32 v[54:55], v[180:181], v[54:55], v[96:97] op_sel:[1,0,0] op_sel_hi:[0,1,1]
	v_mov_b32_e32 v96, v98
	v_mov_b32_e32 v97, v102
	v_pk_fma_f32 v[54:55], v[182:183], v[96:97], v[54:55] op_sel_hi:[0,1,1]
	v_mov_b32_e32 v102, v99
	v_pk_fma_f32 v[54:55], v[2:3], v[102:103], v[54:55] op_sel_hi:[0,1,1]
	v_pk_add_f32 v[4:5], v[4:5], v[54:55]
	s_waitcnt vmcnt(0)
	ds_read_b128 v[96:99], v57 offset:240
	ds_read_b128 v[100:103], v57 offset:1264
	s_waitcnt lgkmcnt(0)
	v_pk_mov_b32 v[54:55], v[96:97], v[100:101] op_sel:[1,0]
	v_mov_b32_e32 v97, v101
	v_pk_mul_f32 v[96:97], v[184:185], v[96:97]
	s_nop 0
	v_pk_fma_f32 v[54:55], v[184:185], v[54:55], v[96:97] op_sel:[1,0,0] op_sel_hi:[0,1,1]
	v_mov_b32_e32 v96, v98
	v_mov_b32_e32 v97, v102
	v_pk_fma_f32 v[54:55], v[186:187], v[96:97], v[54:55] op_sel_hi:[0,1,1]
	v_mov_b32_e32 v2, v187
	v_mov_b32_e32 v102, v99
	v_pk_fma_f32 v[54:55], v[2:3], v[102:103], v[54:55] op_sel_hi:[0,1,1]
	ds_read_b128 v[96:99], v57 offset:2288
	ds_read_b128 v[100:103], v57 offset:3312
	v_pk_add_f32 v[52:53], v[52:53], v[54:55]
	s_waitcnt lgkmcnt(0)
	v_pk_mov_b32 v[54:55], v[96:97], v[100:101] op_sel:[1,0]
	v_mov_b32_e32 v97, v101
	v_pk_mul_f32 v[96:97], v[184:185], v[96:97]
	s_nop 0
	v_pk_fma_f32 v[54:55], v[184:185], v[54:55], v[96:97] op_sel:[1,0,0] op_sel_hi:[0,1,1]
	v_mov_b32_e32 v96, v98
	v_mov_b32_e32 v97, v102
	v_pk_fma_f32 v[54:55], v[186:187], v[96:97], v[54:55] op_sel_hi:[0,1,1]
	v_mov_b32_e32 v102, v99
	v_pk_fma_f32 v[54:55], v[2:3], v[102:103], v[54:55] op_sel_hi:[0,1,1]
	ds_read_b128 v[96:99], v57 offset:4336
	ds_read_b128 v[100:103], v57 offset:5360
	v_pk_add_f32 v[50:51], v[50:51], v[54:55]
	s_waitcnt lgkmcnt(0)
	v_pk_mov_b32 v[54:55], v[96:97], v[100:101] op_sel:[1,0]
	v_mov_b32_e32 v97, v101
	v_pk_mul_f32 v[96:97], v[184:185], v[96:97]
	s_nop 0
	v_pk_fma_f32 v[54:55], v[184:185], v[54:55], v[96:97] op_sel:[1,0,0] op_sel_hi:[0,1,1]
	v_mov_b32_e32 v96, v98
	v_mov_b32_e32 v97, v102
	v_pk_fma_f32 v[54:55], v[186:187], v[96:97], v[54:55] op_sel_hi:[0,1,1]
	v_mov_b32_e32 v102, v99
	v_pk_fma_f32 v[54:55], v[2:3], v[102:103], v[54:55] op_sel_hi:[0,1,1]
	ds_read_b128 v[96:99], v57 offset:6384
	ds_read_b128 v[100:103], v57 offset:7408
	v_pk_add_f32 v[46:47], v[46:47], v[54:55]
	s_waitcnt lgkmcnt(0)
	v_pk_mov_b32 v[54:55], v[96:97], v[100:101] op_sel:[1,0]
	v_mov_b32_e32 v97, v101
	v_pk_mul_f32 v[96:97], v[184:185], v[96:97]
	s_nop 0
	v_pk_fma_f32 v[54:55], v[184:185], v[54:55], v[96:97] op_sel:[1,0,0] op_sel_hi:[0,1,1]
	v_mov_b32_e32 v96, v98
	v_mov_b32_e32 v97, v102
	v_pk_fma_f32 v[54:55], v[186:187], v[96:97], v[54:55] op_sel_hi:[0,1,1]
	v_mov_b32_e32 v102, v99
	v_pk_fma_f32 v[54:55], v[2:3], v[102:103], v[54:55] op_sel_hi:[0,1,1]
	ds_read_b128 v[96:99], v57 offset:8432
	ds_read_b128 v[100:103], v57 offset:9456
	v_pk_add_f32 v[44:45], v[44:45], v[54:55]
	s_waitcnt lgkmcnt(0)
	v_pk_mov_b32 v[54:55], v[96:97], v[100:101] op_sel:[1,0]
	v_mov_b32_e32 v97, v101
	v_pk_mul_f32 v[96:97], v[184:185], v[96:97]
	s_nop 0
	v_pk_fma_f32 v[54:55], v[184:185], v[54:55], v[96:97] op_sel:[1,0,0] op_sel_hi:[0,1,1]
	v_mov_b32_e32 v96, v98
	v_mov_b32_e32 v97, v102
	v_pk_fma_f32 v[54:55], v[186:187], v[96:97], v[54:55] op_sel_hi:[0,1,1]
	v_mov_b32_e32 v102, v99
	v_pk_fma_f32 v[54:55], v[2:3], v[102:103], v[54:55] op_sel_hi:[0,1,1]
	ds_read_b128 v[96:99], v57 offset:10480
	ds_read_b128 v[100:103], v57 offset:11504
	v_pk_add_f32 v[10:11], v[10:11], v[54:55]
	s_waitcnt lgkmcnt(0)
	v_pk_mov_b32 v[54:55], v[96:97], v[100:101] op_sel:[1,0]
	v_mov_b32_e32 v97, v101
	v_pk_mul_f32 v[96:97], v[184:185], v[96:97]
	s_nop 0
	v_pk_fma_f32 v[54:55], v[184:185], v[54:55], v[96:97] op_sel:[1,0,0] op_sel_hi:[0,1,1]
	v_mov_b32_e32 v96, v98
	v_mov_b32_e32 v97, v102
	v_pk_fma_f32 v[54:55], v[186:187], v[96:97], v[54:55] op_sel_hi:[0,1,1]
	v_mov_b32_e32 v102, v99
	v_pk_fma_f32 v[54:55], v[2:3], v[102:103], v[54:55] op_sel_hi:[0,1,1]
	ds_read_b128 v[96:99], v57 offset:12528
	ds_read_b128 v[100:103], v57 offset:13552
	v_pk_add_f32 v[8:9], v[8:9], v[54:55]
	s_waitcnt lgkmcnt(0)
	v_pk_mov_b32 v[54:55], v[96:97], v[100:101] op_sel:[1,0]
	v_mov_b32_e32 v97, v101
	v_pk_mul_f32 v[96:97], v[184:185], v[96:97]
	s_nop 0
	v_pk_fma_f32 v[54:55], v[184:185], v[54:55], v[96:97] op_sel:[1,0,0] op_sel_hi:[0,1,1]
	v_mov_b32_e32 v96, v98
	v_mov_b32_e32 v97, v102
	v_pk_fma_f32 v[54:55], v[186:187], v[96:97], v[54:55] op_sel_hi:[0,1,1]
	v_mov_b32_e32 v102, v99
	v_pk_fma_f32 v[54:55], v[2:3], v[102:103], v[54:55] op_sel_hi:[0,1,1]
	ds_read_b128 v[96:99], v57 offset:14576
	ds_read_b128 v[100:103], v57 offset:15600
	v_pk_add_f32 v[6:7], v[6:7], v[54:55]
	s_waitcnt lgkmcnt(0)
	v_pk_mov_b32 v[54:55], v[96:97], v[100:101] op_sel:[1,0]
	v_mov_b32_e32 v97, v101
	v_pk_mul_f32 v[96:97], v[184:185], v[96:97]
	s_nop 0
	v_pk_fma_f32 v[54:55], v[184:185], v[54:55], v[96:97] op_sel:[1,0,0] op_sel_hi:[0,1,1]
	v_mov_b32_e32 v96, v98
	v_mov_b32_e32 v97, v102
	v_pk_fma_f32 v[54:55], v[186:187], v[96:97], v[54:55] op_sel_hi:[0,1,1]
	v_mov_b32_e32 v102, v99
	v_pk_fma_f32 v[54:55], v[2:3], v[102:103], v[54:55] op_sel_hi:[0,1,1]
	v_pk_add_f32 v[4:5], v[4:5], v[54:55]
	s_movk_i32 s2, 0x100
	s_branch .LBB0_139
